# combined: fine-grained first-step waits in GEMM loops, out-proj remainder ring GEMM, ffnup rowss load hoist, g1 V^T LDS-transposed stores
# speedup vs baseline: 1.0073x; 1.0073x over previous
; DI f32x4 mfma16(bf16x8 a, bf16x8 b, f32x4 c) { return __builtin_amdgcn_mfma_f32_16x16x32_bf16(a, b, c, 0, 0, 0); }
; template <int MI, int NI>
; DI void gemm_kloop(const u16* Au, int lda, const u16* Bu, int ldb, int K, f32x4 (&acc)[NI][MI], unsigned char* smem) {
;     ...
;   for (int kt = 0; kt < nk; ++kt) {
;     __syncthreads();
;     if (kt + 1 < nk) {
;       SWRITE((kt + 1) & 1);
;       if (kt + 2 < nk) GLOAD((kt + 2) << 6);
;     }
;     {
;       const unsigned char* sa = smem + (kt & 1) * 65536;
;       const unsigned char* sb = sa + 32768;
; #pragma unroll
;       for (int ks = 0; ks < 2; ++ks) {
;         const int fo = ks ? fro1 : fro0;
;         bf16x8 af[MI];
; #pragma unroll
;         for (int i = 0; i < MI; ++i) af[i] = *(const bf16x8*)(sa + (wm * 16 * MI + i * 16) * 128 + fo);
; #pragma unroll
;         for (int nh = 0; nh < NI; nh += 4) {
;           bf16x8 wf[4];
; #pragma unroll
;           for (int i = 0; i < 4; ++i) wf[i] = *(const bf16x8*)(sb + (wn * 16 * NI + (nh + i) * 16) * 128 + fo);
; #pragma unroll
;           for (int ni = 0; ni < 4; ++ni)
; #pragma unroll
;             for (int mi = 0; mi < MI; ++mi) acc[nh + ni][mi] = mfma16(wf[ni], af[mi], acc[nh + ni][mi]);
;         }
.Lk_ffnup:
	s_waitcnt vmcnt(0) lgkmcnt(0)
	s_barrier
	ds_read_b128 v[110:113], v232 offset:32768
	ds_read_b128 v[118:121], v230
	ds_read_b128 v[122:125], v230 offset:2048
	ds_read_b128 v[130:133], v230 offset:4096
	ds_read_b128 v[134:137], v230 offset:6144
	ds_read_b128 v[126:129], v232 offset:34816
	ds_read_b128 v[162:165], v232 offset:36864
	s_and_b32 s92, s95, 1
	s_xor_b32 s92, s92, 1
	s_lshl_b32 s92, s92, 16
	s_waitcnt lgkmcnt(5)
	v_mfma_f32_16x16x32_bf16 v[114:117], v[110:113], v[118:121], v[114:117]
	ds_read_b128 v[226:229], v232 offset:38912
	s_waitcnt lgkmcnt(5)
	v_mfma_f32_16x16x32_bf16 v[106:109], v[110:113], v[122:125], v[106:109]
	s_waitcnt lgkmcnt(4)
	v_mfma_f32_16x16x32_bf16 v[102:105], v[110:113], v[130:133], v[102:105]
	s_add_u32 m0, s92, s94
	s_nop 0
	global_load_lds_dwordx4 v186, s[88:89]
	s_waitcnt lgkmcnt(3)
	v_mfma_f32_16x16x32_bf16 v[98:101], v[110:113], v[134:137], v[98:101]
	s_waitcnt lgkmcnt(2)
	v_mfma_f32_16x16x32_bf16 v[94:97], v[126:129], v[118:121], v[94:97]
	ds_read_b128 v[110:113], v232 offset:40960
	v_mfma_f32_16x16x32_bf16 v[90:93], v[126:129], v[122:125], v[90:93]
	ds_read_b128 v[138:141], v231
	v_mfma_f32_16x16x32_bf16 v[86:89], v[126:129], v[130:133], v[86:89]
	s_add_u32 m0, m0, 0x2000
	s_add_u32 s92, s88, 0x20000
	s_addc_u32 s93, s89, 0
	global_load_lds_dwordx4 v186, s[92:93]
	v_mfma_f32_16x16x32_bf16 v[82:85], v[126:129], v[134:137], v[82:85]
	s_waitcnt lgkmcnt(3)
	v_mfma_f32_16x16x32_bf16 v[78:81], v[162:165], v[118:121], v[78:81]
	ds_read_b128 v[126:129], v232 offset:43008
	v_mfma_f32_16x16x32_bf16 v[74:77], v[162:165], v[122:125], v[74:77]
	ds_read_b128 v[142:145], v231 offset:2048
	v_mfma_f32_16x16x32_bf16 v[70:73], v[162:165], v[130:133], v[70:73]
	s_add_u32 m0, m0, 0x2000
	s_add_u32 s92, s88, 0x40000
	s_addc_u32 s93, s89, 0
	global_load_lds_dwordx4 v186, s[92:93]
	v_mfma_f32_16x16x32_bf16 v[66:69], v[162:165], v[134:137], v[66:69]
	s_waitcnt lgkmcnt(4)
	v_mfma_f32_16x16x32_bf16 v[62:65], v[226:229], v[118:121], v[62:65]
	ds_read_b128 v[162:165], v232 offset:45056
	v_mfma_f32_16x16x32_bf16 v[58:61], v[226:229], v[122:125], v[58:61]
	ds_read_b128 v[178:181], v231 offset:4096
	v_mfma_f32_16x16x32_bf16 v[50:53], v[226:229], v[130:133], v[50:53]
	s_add_u32 m0, m0, 0x2000
	s_add_u32 s92, s88, 0x60000
	s_addc_u32 s93, s89, 0
	global_load_lds_dwordx4 v186, s[92:93]
	v_mfma_f32_16x16x32_bf16 v[46:49], v[226:229], v[134:137], v[46:49]
	s_waitcnt lgkmcnt(5)
	v_mfma_f32_16x16x32_bf16 v[42:45], v[110:113], v[118:121], v[42:45]
	ds_read_b128 v[226:229], v232 offset:47104
	v_mfma_f32_16x16x32_bf16 v[34:37], v[110:113], v[122:125], v[34:37]
	ds_read_b128 v[182:185], v231 offset:6144
	v_mfma_f32_16x16x32_bf16 v[22:25], v[110:113], v[130:133], v[22:25]
	s_add_u32 m0, m0, 0x2000
	s_nop 0
	global_load_lds_dwordx4 v186, s[90:91]
	v_mfma_f32_16x16x32_bf16 v[18:21], v[110:113], v[134:137], v[18:21]
	s_waitcnt lgkmcnt(5)
	v_mfma_f32_16x16x32_bf16 v[14:17], v[126:129], v[118:121], v[14:17]
	ds_read_b128 v[110:113], v233 offset:32768
	v_mfma_f32_16x16x32_bf16 v[6:9], v[126:129], v[122:125], v[6:9]
	v_mfma_f32_16x16x32_bf16 v[2:5], v[126:129], v[130:133], v[2:5]
	s_add_u32 m0, m0, 0x2000
	s_add_u32 s92, s90, 0x20000
	s_addc_u32 s93, s91, 0
	global_load_lds_dwordx4 v186, s[92:93]
	v_mfma_f32_16x16x32_bf16 v[30:33], v[126:129], v[134:137], v[30:33]
	s_waitcnt lgkmcnt(4)
	v_mfma_f32_16x16x32_bf16 v[10:13], v[162:165], v[118:121], v[10:13]
	ds_read_b128 v[126:129], v233 offset:34816
	v_mfma_f32_16x16x32_bf16 v[26:29], v[162:165], v[122:125], v[26:29]
	v_mfma_f32_16x16x32_bf16 v[38:41], v[162:165], v[130:133], v[38:41]
	s_add_u32 m0, m0, 0x2000
	s_add_u32 s92, s90, 0x40000
	s_addc_u32 s93, s91, 0
	global_load_lds_dwordx4 v186, s[92:93]
	v_mfma_f32_16x16x32_bf16 v[54:57], v[162:165], v[134:137], v[54:57]
	s_waitcnt lgkmcnt(3)
	v_mfma_f32_16x16x32_bf16 v[146:149], v[226:229], v[118:121], v[146:149]
	ds_read_b128 v[162:165], v233 offset:36864
	v_mfma_f32_16x16x32_bf16 v[154:157], v[226:229], v[122:125], v[154:157]
	v_mfma_f32_16x16x32_bf16 v[150:153], v[226:229], v[130:133], v[150:153]
	s_add_u32 m0, m0, 0x2000
	s_add_u32 s92, s90, 0x60000
	s_addc_u32 s93, s91, 0
	global_load_lds_dwordx4 v186, s[92:93]
	v_mfma_f32_16x16x32_bf16 v[158:161], v[226:229], v[134:137], v[158:161]
	s_waitcnt lgkmcnt(2)
	v_mfma_f32_16x16x32_bf16 v[114:117], v[110:113], v[138:141], v[114:117]
	ds_read_b128 v[226:229], v233 offset:38912
	v_mfma_f32_16x16x32_bf16 v[106:109], v[110:113], v[142:145], v[106:109]
	v_mfma_f32_16x16x32_bf16 v[102:105], v[110:113], v[178:181], v[102:105]
	v_mfma_f32_16x16x32_bf16 v[98:101], v[110:113], v[182:185], v[98:101]
	s_waitcnt lgkmcnt(2)
	v_mfma_f32_16x16x32_bf16 v[94:97], v[126:129], v[138:141], v[94:97]
	ds_read_b128 v[110:113], v233 offset:40960
	v_mfma_f32_16x16x32_bf16 v[90:93], v[126:129], v[142:145], v[90:93]
	v_mfma_f32_16x16x32_bf16 v[86:89], v[126:129], v[178:181], v[86:89]
	v_mfma_f32_16x16x32_bf16 v[82:85], v[126:129], v[182:185], v[82:85]
	s_waitcnt lgkmcnt(2)
	v_mfma_f32_16x16x32_bf16 v[78:81], v[162:165], v[138:141], v[78:81]
	ds_read_b128 v[126:129], v233 offset:43008
	v_mfma_f32_16x16x32_bf16 v[74:77], v[162:165], v[142:145], v[74:77]
	v_mfma_f32_16x16x32_bf16 v[70:73], v[162:165], v[178:181], v[70:73]
	v_mfma_f32_16x16x32_bf16 v[66:69], v[162:165], v[182:185], v[66:69]
	s_waitcnt lgkmcnt(2)
	v_mfma_f32_16x16x32_bf16 v[62:65], v[226:229], v[138:141], v[62:65]
	ds_read_b128 v[162:165], v233 offset:45056
	v_mfma_f32_16x16x32_bf16 v[58:61], v[226:229], v[142:145], v[58:61]
	v_mfma_f32_16x16x32_bf16 v[50:53], v[226:229], v[178:181], v[50:53]
	v_mfma_f32_16x16x32_bf16 v[46:49], v[226:229], v[182:185], v[46:49]
	s_waitcnt lgkmcnt(2)
; DI f32x4 mfma16(bf16x8 a, bf16x8 b, f32x4 c) { return __builtin_amdgcn_mfma_f32_16x16x32_bf16(a, b, c, 0, 0, 0); }
; template <int MI, int NI>
; DI void gemm_kloop(const u16* Au, int lda, const u16* Bu, int ldb, int K, f32x4 (&acc)[NI][MI], unsigned char* smem) {
;     ...
;   for (int kt = 0; kt < nk; ++kt) {
;     __syncthreads();
;     if (kt + 1 < nk) {
;       SWRITE((kt + 1) & 1);
;       if (kt + 2 < nk) GLOAD((kt + 2) << 6);
;     }
;     {
;       const unsigned char* sa = smem + (kt & 1) * 65536;
;       const unsigned char* sb = sa + 32768;
; #pragma unroll
;       for (int ks = 0; ks < 2; ++ks) {
;         const int fo = ks ? fro1 : fro0;
;         bf16x8 af[MI];
; #pragma unroll
;         for (int i = 0; i < MI; ++i) af[i] = *(const bf16x8*)(sa + (wm * 16 * MI + i * 16) * 128 + fo);
; #pragma unroll
;         for (int nh = 0; nh < NI; nh += 4) {
;           bf16x8 wf[4];
; #pragma unroll
;           for (int i = 0; i < 4; ++i) wf[i] = *(const bf16x8*)(sb + (wn * 16 * NI + (nh + i) * 16) * 128 + fo);
; #pragma unroll
;           for (int ni = 0; ni < 4; ++ni)
; #pragma unroll
;             for (int mi = 0; mi < MI; ++mi) acc[nh + ni][mi] = mfma16(wf[ni], af[mi], acc[nh + ni][mi]);
;         }
; DI void phase_ffnup(const Params& p, int layer, unsigned char* smem) {
;     ...
;       const int r = r0 + mi * 16;
;       tt[mi] = tbase + r;
;       float rs = (tt[mi] >= 0 && tt[mi] < TP) ? rsqrtf(rowss[b * TP + tt[mi]] * (1.f / DM) + EPS) : 0.f;
	v_mfma_f32_16x16x32_bf16 v[42:45], v[110:113], v[138:141], v[42:45]
	ds_read_b128 v[226:229], v233 offset:47104
	v_mfma_f32_16x16x32_bf16 v[34:37], v[110:113], v[142:145], v[34:37]
	v_mfma_f32_16x16x32_bf16 v[22:25], v[110:113], v[178:181], v[22:25]
	v_mfma_f32_16x16x32_bf16 v[18:21], v[110:113], v[182:185], v[18:21]
	s_waitcnt lgkmcnt(2)
	v_mfma_f32_16x16x32_bf16 v[14:17], v[126:129], v[138:141], v[14:17]
	v_mfma_f32_16x16x32_bf16 v[6:9], v[126:129], v[142:145], v[6:9]
	v_mfma_f32_16x16x32_bf16 v[2:5], v[126:129], v[178:181], v[2:5]
	v_mfma_f32_16x16x32_bf16 v[30:33], v[126:129], v[182:185], v[30:33]
	s_waitcnt lgkmcnt(1)
	v_mfma_f32_16x16x32_bf16 v[10:13], v[162:165], v[138:141], v[10:13]
	v_mfma_f32_16x16x32_bf16 v[26:29], v[162:165], v[142:145], v[26:29]
	v_mfma_f32_16x16x32_bf16 v[38:41], v[162:165], v[178:181], v[38:41]
	v_mfma_f32_16x16x32_bf16 v[54:57], v[162:165], v[182:185], v[54:57]
	s_waitcnt lgkmcnt(0)
	v_mfma_f32_16x16x32_bf16 v[146:149], v[226:229], v[138:141], v[146:149]
	v_mfma_f32_16x16x32_bf16 v[154:157], v[226:229], v[142:145], v[154:157]
	v_mfma_f32_16x16x32_bf16 v[150:153], v[226:229], v[178:181], v[150:153]
	v_mfma_f32_16x16x32_bf16 v[158:161], v[226:229], v[182:185], v[158:161]
	v_xor_b32_e32 v230, 0x10000, v230
	v_xor_b32_e32 v231, 0x10000, v231
	v_xor_b32_e32 v232, 0x10000, v232
	v_xor_b32_e32 v233, 0x10000, v233
	s_add_u32 s88, s88, 0x80
	s_addc_u32 s89, s89, 0
	s_add_u32 s90, s90, 0x80
	s_addc_u32 s91, s91, 0
	s_add_u32 s95, s95, 1
	s_cmp_lg_u32 s95, 14
	s_cbranch_scc1 .Lk_ffnup
	s_waitcnt vmcnt(0)
	s_barrier
	v_and_b32_e32 v255, 63, v166
	v_lshrrev_b32_e32 v254, 7, v166
	s_add_i32 s92, s2, s35
	v_lshl_or_b32 v255, v254, 6, v255
	v_add_u32_e32 v254, s35, v255
	v_add_u32_e32 v255, s92, v255
	v_cmp_gt_u32_e32 vcc, 0x1080, v254
	v_lshlrev_b32_e32 v255, 2, v255
	s_and_saveexec_b64 s[92:93], vcc
	global_load_dword v254, v255, s[8:9]
	s_mov_b64 exec, s[92:93]
	s_add_u32 m0, s94, 0x10000
	s_nop 0
	global_load_lds_dwordx4 v186, s[88:89]
	s_add_u32 m0, m0, 0x2000
	s_add_u32 s92, s88, 0x20000
	s_addc_u32 s93, s89, 0
	global_load_lds_dwordx4 v186, s[92:93]
	s_add_u32 m0, m0, 0x2000
	s_add_u32 s92, s88, 0x40000
	s_addc_u32 s93, s89, 0
	global_load_lds_dwordx4 v186, s[92:93]
	s_add_u32 m0, m0, 0x2000
	s_add_u32 s92, s88, 0x60000
	s_addc_u32 s93, s89, 0
	global_load_lds_dwordx4 v186, s[92:93]
	s_add_u32 m0, m0, 0x2000
	s_nop 0
	global_load_lds_dwordx4 v186, s[90:91]
	s_add_u32 m0, m0, 0x2000
	s_add_u32 s92, s90, 0x20000
	s_addc_u32 s93, s91, 0
	global_load_lds_dwordx4 v186, s[92:93]
	s_add_u32 m0, m0, 0x2000
	s_add_u32 s92, s90, 0x40000
	s_addc_u32 s93, s91, 0
	global_load_lds_dwordx4 v186, s[92:93]
	s_add_u32 m0, m0, 0x2000
	s_add_u32 s92, s90, 0x60000
	s_addc_u32 s93, s91, 0
	global_load_lds_dwordx4 v186, s[92:93]
	v_add_u32_e32 v138, v175, v176
	ds_read_b128 v[110:113], v138 offset:32768
	v_add_u32_e32 v134, v174, v176
	ds_read_b128 v[118:121], v134
	ds_read_b128 v[122:125], v134 offset:2048
	ds_read_b128 v[126:129], v138 offset:34816
	ds_read_b128 v[130:133], v134 offset:4096
	ds_read_b128 v[134:137], v134 offset:6144
	s_waitcnt lgkmcnt(4)
	v_mfma_f32_16x16x32_bf16 v[114:117], v[110:113], v[118:121], v[114:117]
	v_or_b32_e32 v186, 0x18000, v175
	v_add_u32_e32 v187, v186, v176
	v_add_u32_e32 v190, 0x10000, v174
	s_waitcnt lgkmcnt(3)
	v_mfma_f32_16x16x32_bf16 v[106:109], v[110:113], v[122:125], v[106:109]
	v_add_u32_e32 v194, v186, v173
	s_movk_i32 s4, 0x1080
	s_waitcnt lgkmcnt(1)
	v_mfma_f32_16x16x32_bf16 v[102:105], v[110:113], v[130:133], v[102:105]
	s_waitcnt lgkmcnt(0)
	v_mfma_f32_16x16x32_bf16 v[98:101], v[110:113], v[134:137], v[98:101]
	v_mfma_f32_16x16x32_bf16 v[94:97], v[126:129], v[118:121], v[94:97]
	v_mfma_f32_16x16x32_bf16 v[90:93], v[126:129], v[122:125], v[90:93]
	v_mfma_f32_16x16x32_bf16 v[86:89], v[126:129], v[130:133], v[86:89]
	v_mfma_f32_16x16x32_bf16 v[82:85], v[126:129], v[134:137], v[82:85]
	ds_read_b128 v[110:113], v138 offset:36864
	ds_read_b128 v[126:129], v138 offset:38912
	s_waitcnt lgkmcnt(1)
	v_mfma_f32_16x16x32_bf16 v[78:81], v[110:113], v[118:121], v[78:81]
	v_mfma_f32_16x16x32_bf16 v[74:77], v[110:113], v[122:125], v[74:77]
	v_mfma_f32_16x16x32_bf16 v[70:73], v[110:113], v[130:133], v[70:73]
	v_mfma_f32_16x16x32_bf16 v[66:69], v[110:113], v[134:137], v[66:69]
	s_waitcnt lgkmcnt(0)
	v_mfma_f32_16x16x32_bf16 v[62:65], v[126:129], v[118:121], v[62:65]
	v_mfma_f32_16x16x32_bf16 v[58:61], v[126:129], v[122:125], v[58:61]
	v_mfma_f32_16x16x32_bf16 v[50:53], v[126:129], v[130:133], v[50:53]
	v_mfma_f32_16x16x32_bf16 v[46:49], v[126:129], v[134:137], v[46:49]
	ds_read_b128 v[110:113], v138 offset:40960
	ds_read_b128 v[126:129], v138 offset:43008
	s_waitcnt lgkmcnt(1)
	v_mfma_f32_16x16x32_bf16 v[42:45], v[110:113], v[118:121], v[42:45]
	v_mfma_f32_16x16x32_bf16 v[34:37], v[110:113], v[122:125], v[34:37]
	v_mfma_f32_16x16x32_bf16 v[22:25], v[110:113], v[130:133], v[22:25]
	v_mfma_f32_16x16x32_bf16 v[18:21], v[110:113], v[134:137], v[18:21]
	s_waitcnt lgkmcnt(0)
	v_mfma_f32_16x16x32_bf16 v[14:17], v[126:129], v[118:121], v[14:17]
	v_mfma_f32_16x16x32_bf16 v[6:9], v[126:129], v[122:125], v[6:9]
	v_mfma_f32_16x16x32_bf16 v[2:5], v[126:129], v[130:133], v[2:5]
	v_mfma_f32_16x16x32_bf16 v[30:33], v[126:129], v[134:137], v[30:33]
	ds_read_b128 v[110:113], v138 offset:45056
	ds_read_b128 v[126:129], v138 offset:47104
	s_waitcnt lgkmcnt(1)
	v_mfma_f32_16x16x32_bf16 v[10:13], v[110:113], v[118:121], v[10:13]
	v_mfma_f32_16x16x32_bf16 v[26:29], v[110:113], v[122:125], v[26:29]
	v_mfma_f32_16x16x32_bf16 v[38:41], v[110:113], v[130:133], v[38:41]
	v_mfma_f32_16x16x32_bf16 v[54:57], v[110:113], v[134:137], v[54:57]
	s_waitcnt lgkmcnt(0)
; DI f32x4 mfma16(bf16x8 a, bf16x8 b, f32x4 c) { return __builtin_amdgcn_mfma_f32_16x16x32_bf16(a, b, c, 0, 0, 0); }
; template <int MI, int NI>
; DI void gemm_kloop(const u16* Au, int lda, const u16* Bu, int ldb, int K, f32x4 (&acc)[NI][MI], unsigned char* smem) {
;     ...
;   for (int kt = 0; kt < nk; ++kt) {
;     __syncthreads();
;     if (kt + 1 < nk) {
;       SWRITE((kt + 1) & 1);
;       if (kt + 2 < nk) GLOAD((kt + 2) << 6);
;     }
;     {
;       const unsigned char* sa = smem + (kt & 1) * 65536;
;       const unsigned char* sb = sa + 32768;
; #pragma unroll
;       for (int ks = 0; ks < 2; ++ks) {
;         const int fo = ks ? fro1 : fro0;
;         bf16x8 af[MI];
; #pragma unroll
;         for (int i = 0; i < MI; ++i) af[i] = *(const bf16x8*)(sa + (wm * 16 * MI + i * 16) * 128 + fo);
; #pragma unroll
;         for (int nh = 0; nh < NI; nh += 4) {
;           bf16x8 wf[4];
; #pragma unroll
;           for (int i = 0; i < 4; ++i) wf[i] = *(const bf16x8*)(sb + (wn * 16 * NI + (nh + i) * 16) * 128 + fo);
; #pragma unroll
;           for (int ni = 0; ni < 4; ++ni)
; #pragma unroll
;             for (int mi = 0; mi < MI; ++mi) acc[nh + ni][mi] = mfma16(wf[ni], af[mi], acc[nh + ni][mi]);
;         }
	v_mfma_f32_16x16x32_bf16 v[110:113], v[126:129], v[118:121], v[146:149]
	v_mfma_f32_16x16x32_bf16 v[118:121], v[126:129], v[122:125], v[154:157]
	s_nop 2
	v_add_u32_e32 v154, v175, v173
	v_mfma_f32_16x16x32_bf16 v[122:125], v[126:129], v[130:133], v[150:153]
	ds_read_b128 v[130:133], v154 offset:32768
	s_nop 1
	v_add_u32_e32 v150, v174, v173
	v_mfma_f32_16x16x32_bf16 v[126:129], v[126:129], v[134:137], v[158:161]
	ds_read_b128 v[134:137], v150
	ds_read_b128 v[138:141], v150 offset:2048
	ds_read_b128 v[142:145], v154 offset:34816
	ds_read_b128 v[146:149], v150 offset:4096
	ds_read_b128 v[150:153], v150 offset:6144
	s_waitcnt lgkmcnt(4)
	v_mfma_f32_16x16x32_bf16 v[114:117], v[130:133], v[134:137], v[114:117]
	s_waitcnt lgkmcnt(3)
	v_mfma_f32_16x16x32_bf16 v[106:109], v[130:133], v[138:141], v[106:109]
	s_waitcnt lgkmcnt(1)
	v_mfma_f32_16x16x32_bf16 v[102:105], v[130:133], v[146:149], v[102:105]
	s_waitcnt lgkmcnt(0)
	v_mfma_f32_16x16x32_bf16 v[98:101], v[130:133], v[150:153], v[98:101]
	v_mfma_f32_16x16x32_bf16 v[94:97], v[142:145], v[134:137], v[94:97]
	v_mfma_f32_16x16x32_bf16 v[90:93], v[142:145], v[138:141], v[90:93]
	v_mfma_f32_16x16x32_bf16 v[86:89], v[142:145], v[146:149], v[86:89]
	v_mfma_f32_16x16x32_bf16 v[82:85], v[142:145], v[150:153], v[82:85]
	ds_read_b128 v[130:133], v154 offset:36864
	ds_read_b128 v[142:145], v154 offset:38912
	s_waitcnt lgkmcnt(1)
	v_mfma_f32_16x16x32_bf16 v[78:81], v[130:133], v[134:137], v[78:81]
	v_mfma_f32_16x16x32_bf16 v[74:77], v[130:133], v[138:141], v[74:77]
	v_mfma_f32_16x16x32_bf16 v[70:73], v[130:133], v[146:149], v[70:73]
	v_mfma_f32_16x16x32_bf16 v[66:69], v[130:133], v[150:153], v[66:69]
	s_waitcnt lgkmcnt(0)
	v_mfma_f32_16x16x32_bf16 v[62:65], v[142:145], v[134:137], v[62:65]
	v_mfma_f32_16x16x32_bf16 v[58:61], v[142:145], v[138:141], v[58:61]
	v_mfma_f32_16x16x32_bf16 v[50:53], v[142:145], v[146:149], v[50:53]
	v_mfma_f32_16x16x32_bf16 v[46:49], v[142:145], v[150:153], v[46:49]
	ds_read_b128 v[130:133], v154 offset:40960
	ds_read_b128 v[142:145], v154 offset:43008
	s_waitcnt lgkmcnt(1)
	v_mfma_f32_16x16x32_bf16 v[42:45], v[130:133], v[134:137], v[42:45]
	v_mfma_f32_16x16x32_bf16 v[34:37], v[130:133], v[138:141], v[34:37]
	v_mfma_f32_16x16x32_bf16 v[22:25], v[130:133], v[146:149], v[22:25]
	v_mfma_f32_16x16x32_bf16 v[18:21], v[130:133], v[150:153], v[18:21]
	s_waitcnt lgkmcnt(0)
	v_mfma_f32_16x16x32_bf16 v[14:17], v[142:145], v[134:137], v[14:17]
	v_mfma_f32_16x16x32_bf16 v[6:9], v[142:145], v[138:141], v[6:9]
	v_mfma_f32_16x16x32_bf16 v[2:5], v[142:145], v[146:149], v[2:5]
	v_mfma_f32_16x16x32_bf16 v[30:33], v[142:145], v[150:153], v[30:33]
	ds_read_b128 v[130:133], v154 offset:45056
	ds_read_b128 v[142:145], v154 offset:47104
	s_waitcnt vmcnt(0) lgkmcnt(0)
	s_barrier
	v_mfma_f32_16x16x32_bf16 v[10:13], v[130:133], v[134:137], v[10:13]
	v_mfma_f32_16x16x32_bf16 v[26:29], v[130:133], v[138:141], v[26:29]
	v_mfma_f32_16x16x32_bf16 v[38:41], v[130:133], v[146:149], v[38:41]
	v_mfma_f32_16x16x32_bf16 v[54:57], v[130:133], v[150:153], v[54:57]
	ds_read_b128 v[130:133], v187
	v_mfma_f32_16x16x32_bf16 v[122:125], v[142:145], v[146:149], v[122:125]
	v_add_u32_e32 v146, v190, v176
	v_mfma_f32_16x16x32_bf16 v[110:113], v[142:145], v[134:137], v[110:113]
	ds_read_b128 v[134:137], v146
	v_mfma_f32_16x16x32_bf16 v[118:121], v[142:145], v[138:141], v[118:121]
	ds_read_b128 v[138:141], v146 offset:2048
	v_mfma_f32_16x16x32_bf16 v[126:129], v[142:145], v[150:153], v[126:129]
	ds_read_b128 v[142:145], v146 offset:4096
	ds_read_b128 v[146:149], v146 offset:6144
	s_waitcnt lgkmcnt(3)
	v_mfma_f32_16x16x32_bf16 v[114:117], v[130:133], v[134:137], v[114:117]
	s_waitcnt lgkmcnt(2)
	v_mfma_f32_16x16x32_bf16 v[106:109], v[130:133], v[138:141], v[106:109]
	s_waitcnt lgkmcnt(1)
	v_mfma_f32_16x16x32_bf16 v[102:105], v[130:133], v[142:145], v[102:105]
	s_waitcnt lgkmcnt(0)
	v_mfma_f32_16x16x32_bf16 v[98:101], v[130:133], v[146:149], v[98:101]
	ds_read_b128 v[130:133], v187 offset:2048
	s_waitcnt lgkmcnt(0)
	v_mfma_f32_16x16x32_bf16 v[94:97], v[130:133], v[134:137], v[94:97]
	v_mfma_f32_16x16x32_bf16 v[90:93], v[130:133], v[138:141], v[90:93]
	v_mfma_f32_16x16x32_bf16 v[86:89], v[130:133], v[142:145], v[86:89]
	v_mfma_f32_16x16x32_bf16 v[82:85], v[130:133], v[146:149], v[82:85]
	ds_read_b128 v[130:133], v187 offset:4096
	s_waitcnt lgkmcnt(0)
	v_mfma_f32_16x16x32_bf16 v[78:81], v[130:133], v[134:137], v[78:81]
	v_mfma_f32_16x16x32_bf16 v[74:77], v[130:133], v[138:141], v[74:77]
	v_mfma_f32_16x16x32_bf16 v[70:73], v[130:133], v[142:145], v[70:73]
	v_mfma_f32_16x16x32_bf16 v[66:69], v[130:133], v[146:149], v[66:69]
	ds_read_b128 v[130:133], v187 offset:6144
	s_waitcnt lgkmcnt(0)
	v_mfma_f32_16x16x32_bf16 v[154:157], v[130:133], v[146:149], v[46:49]
	s_nop 2
	ds_read_b128 v[46:49], v187 offset:8192
	s_waitcnt lgkmcnt(0)
	v_mfma_f32_16x16x32_bf16 v[158:161], v[46:49], v[146:149], v[18:21]
	s_nop 2
	ds_read_b128 v[18:21], v187 offset:10240
	s_waitcnt lgkmcnt(0)
	v_mfma_f32_16x16x32_bf16 v[168:171], v[18:21], v[138:141], v[6:9]
	s_nop 2
	ds_read_b128 v[6:9], v187 offset:12288
	s_waitcnt lgkmcnt(0)
	v_mfma_f32_16x16x32_bf16 v[10:13], v[6:9], v[134:137], v[10:13]
	v_mfma_f32_16x16x32_bf16 v[174:177], v[6:9], v[138:141], v[26:29]
	v_mfma_f32_16x16x32_bf16 v[178:181], v[6:9], v[142:145], v[38:41]
	v_mfma_f32_16x16x32_bf16 v[182:185], v[6:9], v[146:149], v[54:57]
	ds_read_b128 v[6:9], v187 offset:14336
	s_nop 0
	ds_read_b128 v[38:41], v194
	v_mfma_f32_16x16x32_bf16 v[42:45], v[46:49], v[134:137], v[42:45]
	v_mfma_f32_16x16x32_bf16 v[34:37], v[46:49], v[138:141], v[34:37]
	v_mfma_f32_16x16x32_bf16 v[22:25], v[46:49], v[142:145], v[22:25]
	v_add_u32_e32 v46, v190, v173
	ds_read_b128 v[190:193], v46 offset:2048
	ds_read_b128 v[226:229], v46 offset:4096
	ds_read_b128 v[230:233], v46 offset:6144
	v_mfma_f32_16x16x32_bf16 v[30:33], v[18:21], v[146:149], v[30:33]
	s_waitcnt lgkmcnt(4)
; DI void phase_ffnup(const Params& p, int layer, unsigned char* smem) {
;     ...
;     gemm_kloop<4, 8>(p.hb + ((ptrdiff_t)(b * TP + tbase)) * DM, DM, W + (size_t)(nt * 256) * DM, DM, DM, acc, smem);
;     int r0 = wm * 64 + lm, gc0 = 64 * wn + 4 * lg;
;     asm volatile("" : "+v"(r0), "+v"(gc0));
;     int tt[4];
; #pragma unroll
;     for (int mi = 0; mi < 4; ++mi) {
;       const int r = r0 + mi * 16;
;       tt[mi] = tbase + r;
;       float rs = (tt[mi] >= 0 && tt[mi] < TP) ? rsqrtf(rowss[b * TP + tt[mi]] * (1.f / DM) + EPS) : 0.f;
; #pragma unroll
;       for (int ni = 0; ni < 8; ++ni) acc[ni][mi] *= rs;
	v_mfma_f32_16x16x32_bf16 v[126:129], v[6:9], v[146:149], v[126:129]
	ds_read_b128 v[146:149], v46
	v_mfma_f32_16x16x32_bf16 v[62:65], v[130:133], v[134:137], v[62:65]
	v_mfma_f32_16x16x32_bf16 v[150:153], v[130:133], v[138:141], v[58:61]
	v_mfma_f32_16x16x32_bf16 v[162:165], v[18:21], v[134:137], v[14:17]
	v_mfma_f32_16x16x32_bf16 v[2:5], v[18:21], v[142:145], v[2:5]
	v_mfma_f32_16x16x32_bf16 v[134:137], v[6:9], v[134:137], v[110:113]
	v_mfma_f32_16x16x32_bf16 v[138:141], v[6:9], v[138:141], v[118:121]
	v_mfma_f32_16x16x32_bf16 v[186:189], v[6:9], v[142:145], v[122:125]
	s_waitcnt lgkmcnt(0)
	v_mfma_f32_16x16x32_bf16 v[26:29], v[38:41], v[146:149], v[114:117]
	v_mfma_f32_16x16x32_bf16 v[18:21], v[38:41], v[190:193], v[106:109]
	v_mfma_f32_16x16x32_bf16 v[14:17], v[38:41], v[226:229], v[102:105]
	v_mfma_f32_16x16x32_bf16 v[6:9], v[38:41], v[230:233], v[98:101]
	ds_read_b128 v[38:41], v194 offset:2048
	v_mfma_f32_16x16x32_bf16 v[50:53], v[130:133], v[142:145], v[50:53]
	s_waitcnt lgkmcnt(0)
	v_mfma_f32_16x16x32_bf16 v[142:145], v[38:41], v[146:149], v[94:97]
	v_mfma_f32_16x16x32_bf16 v[130:133], v[38:41], v[190:193], v[90:93]
	v_mfma_f32_16x16x32_bf16 v[106:109], v[38:41], v[226:229], v[86:89]
	v_mfma_f32_16x16x32_bf16 v[98:101], v[38:41], v[230:233], v[82:85]
	ds_read_b128 v[38:41], v194 offset:4096
	s_waitcnt lgkmcnt(0)
	v_mfma_f32_16x16x32_bf16 v[58:61], v[38:41], v[146:149], v[78:81]
	v_mfma_f32_16x16x32_bf16 v[54:57], v[38:41], v[190:193], v[74:77]
	v_mfma_f32_16x16x32_bf16 v[46:49], v[38:41], v[226:229], v[70:73]
	v_mfma_f32_16x16x32_bf16 v[38:41], v[38:41], v[230:233], v[66:69]
	s_nop 2
	ds_read_b128 v[66:69], v194 offset:6144
	s_waitcnt lgkmcnt(0)
	v_mfma_f32_16x16x32_bf16 v[74:77], v[66:69], v[226:229], v[50:53]
	s_nop 2
	ds_read_b128 v[50:53], v194 offset:8192
	s_waitcnt lgkmcnt(0)
	v_mfma_f32_16x16x32_bf16 v[70:73], v[50:53], v[226:229], v[22:25]
	s_nop 2
	ds_read_b128 v[22:25], v194 offset:10240
	v_mfma_f32_16x16x32_bf16 v[86:89], v[50:53], v[146:149], v[42:45]
	s_waitcnt lgkmcnt(0)
	v_mfma_f32_16x16x32_bf16 v[42:45], v[22:25], v[226:229], v[2:5]
	s_nop 2
	ds_read_b128 v[2:5], v194 offset:12288
	s_waitcnt lgkmcnt(0)
	v_mfma_f32_16x16x32_bf16 v[122:125], v[2:5], v[146:149], v[10:13]
	v_mfma_f32_16x16x32_bf16 v[118:121], v[2:5], v[190:193], v[174:177]
	v_mfma_f32_16x16x32_bf16 v[102:105], v[2:5], v[226:229], v[178:181]
	v_mfma_f32_16x16x32_bf16 v[114:117], v[2:5], v[230:233], v[182:185]
	ds_read_b128 v[2:5], v194 offset:14336
	s_waitcnt lgkmcnt(0)
	s_barrier
	v_mfma_f32_16x16x32_bf16 v[94:97], v[66:69], v[146:149], v[62:65]
	v_mfma_f32_16x16x32_bf16 v[82:85], v[66:69], v[190:193], v[150:153]
	v_mfma_f32_16x16x32_bf16 v[66:69], v[66:69], v[230:233], v[154:157]
	s_nop 1
	v_mov_b32_e32 v152, 0
	v_mfma_f32_16x16x32_bf16 v[78:81], v[50:53], v[190:193], v[34:37]
	v_mov_b32_e32 v154, 0
	v_mfma_f32_16x16x32_bf16 v[110:113], v[50:53], v[230:233], v[158:161]
	v_mfma_f32_16x16x32_bf16 v[62:65], v[22:25], v[146:149], v[162:165]
	s_nop 1
	v_mov_b32_e32 v160, v0
	v_mfma_f32_16x16x32_bf16 v[50:53], v[22:25], v[190:193], v[168:171]
	v_mfma_f32_16x16x32_bf16 v[34:37], v[22:25], v[230:233], v[30:33]
	s_nop 1
	v_mov_b32_e32 v168, v172
	v_mfma_f32_16x16x32_bf16 v[30:33], v[2:5], v[146:149], v[134:137]
	v_add_u32_e32 v162, s35, v160
	v_cmp_gt_u32_e32 vcc, s4, v162
	v_mfma_f32_16x16x32_bf16 v[22:25], v[2:5], v[190:193], v[138:141]
	v_mfma_f32_16x16x32_bf16 v[10:13], v[2:5], v[226:229], v[186:189]
	v_mfma_f32_16x16x32_bf16 v[2:5], v[2:5], v[230:233], v[126:129]
	s_waitcnt vmcnt(0)
	v_and_b32_e32 v152, 63, v166
	v_lshrrev_b32_e32 v154, 7, v166
	v_fmamk_f32 v254, v254, 0x3a800000, v199
	v_lshl_or_b32 v152, v154, 6, v152
	v_mul_f32_e32 v255, 0x4b800000, v254
	v_cmp_gt_f32_e32 vcc, s14, v254
	v_add_u32_e32 v152, s35, v152
	s_nop 0
	v_cndmask_b32_e32 v254, v254, v255, vcc
	s_nop 0
	v_rsq_f32_e32 v254, v254
	s_nop 0
	v_mul_f32_e32 v255, 0x45800000, v254
	v_cndmask_b32_e32 v254, v254, v255, vcc
	v_cmp_gt_u32_e32 vcc, 0x1080, v152
	v_and_b32_e32 v255, 15, v166
	s_nop 0
	v_cndmask_b32_e32 v254, 0, v254, vcc
	v_lshlrev_b32_e32 v255, 2, v255
	s_nop 0
	ds_bpermute_b32 v154, v255, v254
	ds_bpermute_b32 v152, v255, v254 offset:64
	ds_bpermute_b32 v150, v255, v254 offset:128
	ds_bpermute_b32 v148, v255, v254 offset:192
	s_waitcnt lgkmcnt(0)
; DI void phase_ffnup(const Params& p, int layer, unsigned char* smem) {
;     ...
;     for (int mi = 0; mi < 4; ++mi) {
;       const int r = r0 + mi * 16;
;       tt[mi] = tbase + r;
;       float rs = (tt[mi] >= 0 && tt[mi] < TP) ? rsqrtf(rowss[b * TP + tt[mi]] * (1.f / DM) + EPS) : 0.f;
; #pragma unroll
;       for (int ni = 0; ni < 8; ++ni) acc[ni][mi] *= rs;
; #pragma unroll
;       for (int n2 = 0; n2 < 4; ++n2) {
;         float4 g4 = make_float4(acc[2 * n2][mi][0], acc[2 * n2][mi][1], acc[2 * n2][mi][2], acc[2 * n2][mi][3]);
;         *(float4*)(G + r * 132 + gc0 + 16 * n2) = g4;
;       }
;     }
;     __syncthreads();
; #pragma unroll
;     for (int n2 = 0; n2 < 4; ++n2) {
;       const int gc = gc0 + 16 * n2;
;       const int ff = 128 * nt + gc;
;       const float4 w0 = *(const float4*)(cw + ff), w1 = *(const float4*)(cw + DFF + ff), w2 = *(const float4*)(cw + 2 * DFF + ff);
;       const float4 c4 = *(const float4*)(cb + ff);
; #pragma unroll
;       for (int mi = 0; mi < 4; ++mi) {
;         const int r = r0 + mi * 16;
;         if (r >= 2 && tt[mi] < TP) {
;           const float4 g1 = *(const float4*)(G + (r - 1) * 132 + gc);
;           const float4 g2 = *(const float4*)(G + (r - 2) * 132 + gc);
;           float cv[4];
;           cv[0] = c4.x + w0.x * g2.x + w1.x * g1.x + w2.x * acc[2 * n2][mi][0];
;           cv[1] = c4.y + w0.y * g2.y + w1.y * g1.y + w2.y * acc[2 * n2][mi][1];
;           cv[2] = c4.z + w0.z * g2.z + w1.z * g1.z + w2.z * acc[2 * n2][mi][2];
;           cv[3] = c4.w + w0.w * g2.w + w1.w * g1.w + w2.w * acc[2 * n2][mi][3];
;           float a[4];
; #pragma unroll
;           for (int e = 0; e < 4; ++e) a[e] = cv[e] / (1.f + __expf(-cv[e])) * acc[2 * n2 + 1][mi][e];
;           u32x2 pk = {pack2bf(a[0], a[1]), pack2bf(a[2], a[3])};
;           *(u32x2*)(p.act + (size_t)(b * TP + tt[mi]) * DFF + ff) = pk;
	s_movk_i32 s3, 0x210
	v_lshlrev_b32_e32 v146, 2, v168
	v_mul_lo_u32 v169, v160, s3
	v_add_u32_e32 v151, 16, v162
	s_movk_i32 s3, 0x1080
	v_pk_mul_f32 v[140:141], v[28:29], v[154:155] op_sel_hi:[1,0]
	v_pk_mul_f32 v[138:139], v[26:27], v[154:155] op_sel_hi:[1,0]
	v_pk_mul_f32 v[92:93], v[60:61], v[154:155] op_sel_hi:[1,0]
	v_pk_mul_f32 v[90:91], v[58:59], v[154:155] op_sel_hi:[1,0]
	v_pk_mul_f32 v[60:61], v[88:89], v[154:155] op_sel_hi:[1,0]
	v_pk_mul_f32 v[58:59], v[86:87], v[154:155] op_sel_hi:[1,0]
	v_pk_mul_f32 v[28:29], v[124:125], v[154:155] op_sel_hi:[1,0]
	v_pk_mul_f32 v[26:27], v[122:123], v[154:155] op_sel_hi:[1,0]
	v_add_u32_e32 v86, v146, v169
	v_cmp_gt_u32_e32 vcc, s3, v151
	v_ashrrev_i32_e32 v163, 31, v162
	ds_write_b128 v86, v[138:141]
	ds_write_b128 v86, v[90:93] offset:64
	ds_write_b128 v86, v[58:61] offset:128
	ds_write_b128 v86, v[26:29] offset:192
	v_add_u32_e32 v165, 0x2100, v169
	v_add_u32_e32 v149, 32, v162
	s_movk_i32 s3, 0x1080
	v_pk_mul_f32 v[136:137], v[20:21], v[152:153] op_sel_hi:[1,0]
	v_pk_mul_f32 v[134:135], v[18:19], v[152:153] op_sel_hi:[1,0]
	v_pk_mul_f32 v[88:89], v[56:57], v[152:153] op_sel_hi:[1,0]
	v_pk_mul_f32 v[86:87], v[54:55], v[152:153] op_sel_hi:[1,0]
	v_pk_mul_f32 v[56:57], v[80:81], v[152:153] op_sel_hi:[1,0]
	v_pk_mul_f32 v[54:55], v[78:79], v[152:153] op_sel_hi:[1,0]
	v_pk_mul_f32 v[20:21], v[120:121], v[152:153] op_sel_hi:[1,0]
	v_pk_mul_f32 v[18:19], v[118:119], v[152:153] op_sel_hi:[1,0]
	v_add_u32_e32 v78, v146, v165
	v_cmp_gt_u32_e32 vcc, s3, v149
	ds_write_b128 v78, v[134:137]
	ds_write_b128 v78, v[86:89] offset:64
	ds_write_b128 v78, v[54:57] offset:128
	ds_write_b128 v78, v[18:21] offset:192
	v_add_u32_e32 v164, 0x2100, v165
	v_add_u32_e32 v170, 48, v162
	s_movk_i32 s3, 0x1080
	v_pk_mul_f32 v[128:129], v[16:17], v[150:151] op_sel_hi:[1,0]
	v_pk_mul_f32 v[126:127], v[14:15], v[150:151] op_sel_hi:[1,0]
	v_pk_mul_f32 v[80:81], v[48:49], v[150:151] op_sel_hi:[1,0]
	v_pk_mul_f32 v[78:79], v[46:47], v[150:151] op_sel_hi:[1,0]
	v_pk_mul_f32 v[48:49], v[72:73], v[150:151] op_sel_hi:[1,0]
	v_pk_mul_f32 v[46:47], v[70:71], v[150:151] op_sel_hi:[1,0]
	v_pk_mul_f32 v[16:17], v[104:105], v[150:151] op_sel_hi:[1,0]
	v_pk_mul_f32 v[14:15], v[102:103], v[150:151] op_sel_hi:[1,0]
	v_add_u32_e32 v70, v146, v164
	v_cmp_gt_u32_e32 vcc, s3, v170
	ds_write_b128 v70, v[126:129]
	ds_write_b128 v70, v[78:81] offset:64
	ds_write_b128 v70, v[46:49] offset:128
	ds_write_b128 v70, v[14:17] offset:192
	v_add_u32_e32 v161, 0x2100, v164
	s_lshl_b32 s52, s34, 7
	v_pk_mul_f32 v[70:71], v[38:39], v[148:149] op_sel_hi:[1,0]
	v_pk_mul_f32 v[38:39], v[110:111], v[148:149] op_sel_hi:[1,0]
	v_add_u32_e32 v110, v146, v161
	v_add_u32_e32 v146, s52, v168
	v_pk_mul_f32 v[104:105], v[8:9], v[148:149] op_sel_hi:[1,0]
	v_pk_mul_f32 v[102:103], v[6:7], v[148:149] op_sel_hi:[1,0]
	v_ashrrev_i32_e32 v147, 31, v146
	v_pk_mul_f32 v[72:73], v[40:41], v[148:149] op_sel_hi:[1,0]
	v_pk_mul_f32 v[40:41], v[112:113], v[148:149] op_sel_hi:[1,0]
	v_pk_mul_f32 v[8:9], v[116:117], v[148:149] op_sel_hi:[1,0]
	v_pk_mul_f32 v[6:7], v[114:115], v[148:149] op_sel_hi:[1,0]
	ds_write_b128 v110, v[102:105]
	ds_write_b128 v110, v[70:73] offset:64
	ds_write_b128 v110, v[38:41] offset:128
	ds_write_b128 v110, v[6:9] offset:192
	v_lshlrev_b64 v[110:111], 2, v[146:147]
	v_lshl_add_u64 v[158:159], s[40:41], 0, v[110:111]
	v_lshl_add_u64 v[114:115], s[44:45], 0, v[110:111]
	v_lshl_add_u64 v[118:119], s[46:47], 0, v[110:111]
	s_waitcnt lgkmcnt(0)
	s_barrier
	v_lshl_add_u64 v[156:157], s[42:43], 0, v[110:111]
	global_load_dwordx4 v[110:113], v[158:159], off
	s_nop 0
	global_load_dwordx4 v[114:117], v[114:115], off
	s_nop 0
	global_load_dwordx4 v[118:121], v[118:119], off
	s_nop 0
	global_load_dwordx4 v[122:125], v[156:157], off
	s_movk_i32 s3, 0x1080
	v_cmp_lt_i32_e32 vcc, 1, v160
	v_cmp_gt_i32_e64 s[4:5], s3, v162
	v_mov_b32_e32 v155, v154
	s_and_b64 s[34:35], vcc, s[4:5]
	v_add_u32_e32 v162, s2, v162
	s_and_saveexec_b64 s[4:5], s[34:35]
	s_cbranch_execz .LBB0_35
	v_pk_mul_f32 v[180:181], v[142:143], v[154:155]
	v_lshl_add_u32 v142, v168, 2, v169
	v_mov_b32_e32 v174, v154
	v_mov_b32_e32 v175, v154
	v_add_u32_e32 v143, 0xfffffdf0, v142
	v_pk_mul_f32 v[178:179], v[144:145], v[174:175]
	v_add_u32_e32 v153, 0xfffffbe0, v142
	ds_read_b128 v[142:145], v143
	ds_read_b128 v[174:177], v153
	s_movk_i32 s3, 0x1600
	s_waitcnt vmcnt(0) lgkmcnt(0)
	v_pk_fma_f32 v[174:175], v[110:111], v[174:175], v[122:123]
	s_nop 0
	v_pk_fma_f32 v[142:143], v[114:115], v[142:143], v[174:175]
	s_nop 0
	v_pk_fma_f32 v[138:139], v[138:139], v[118:119], v[142:143]
	s_nop 0
	v_mul_f32_e32 v142, 0xbfb8aa3b, v138
	v_mul_f32_e32 v143, 0xbfb8aa3b, v139
	v_exp_f32_e32 v142, v142
	v_exp_f32_e32 v143, v143
	s_nop 0
	v_pk_add_f32 v[142:143], v[142:143], 1.0 op_sel_hi:[1,0]
	s_nop 0
	s_nop 0
	v_rcp_f32_e32 v153, v143
	s_nop 0
	v_mul_f32_e32 v139, v139, v153
	s_nop 0
	v_rcp_f32_e32 v143, v142
	s_nop 0
	v_mul_f32_e32 v138, v138, v143
	v_pk_fma_f32 v[142:143], v[112:113], v[176:177], v[124:125]
	v_pk_mul_f32 v[138:139], v[180:181], v[138:139]
	v_pk_fma_f32 v[142:143], v[116:117], v[144:145], v[142:143]
	v_cvt_pk_bf16_f32 v138, v138, v139
	v_pk_fma_f32 v[140:141], v[140:141], v[120:121], v[142:143]
	s_nop 0
	v_mul_f32_e32 v142, 0xbfb8aa3b, v140
	v_mul_f32_e32 v143, 0xbfb8aa3b, v141
	v_exp_f32_e32 v142, v142
	v_exp_f32_e32 v143, v143
	s_nop 0
	v_pk_add_f32 v[142:143], v[142:143], 1.0 op_sel_hi:[1,0]
	s_nop 0
	s_nop 0
	v_rcp_f32_e32 v144, v143
	s_nop 0
	v_mul_f32_e32 v141, v141, v144
	s_nop 0
	v_rcp_f32_e32 v143, v142
	s_nop 0
	v_mul_f32_e32 v140, v140, v143
	v_pk_mul_f32 v[140:141], v[178:179], v[140:141]
	s_nop 0
	v_cvt_pk_bf16_f32 v139, v140, v141
	v_mov_b64_e32 v[140:141], s[86:87]
	v_mad_i64_i32 v[140:141], s[48:49], v162, s3, v[140:141]
	v_lshl_add_u64 v[140:141], v[146:147], 1, v[140:141]
	global_store_dwordx2 v[140:141], v[138:139], off

; DI f32x4 mfma16(bf16x8 a, bf16x8 b, f32x4 c) { return __builtin_amdgcn_mfma_f32_16x16x32_bf16(a, b, c, 0, 0, 0); }
; template <int MI, int NI>
; DI void gemm_kloop(const u16* Au, int lda, const u16* Bu, int ldb, int K, f32x4 (&acc)[NI][MI], unsigned char* smem) {
;     ...
;   for (int kt = 0; kt < nk; ++kt) {
;     __syncthreads();
;     if (kt + 1 < nk) {
;       SWRITE((kt + 1) & 1);
;       if (kt + 2 < nk) GLOAD((kt + 2) << 6);
;     }
;     {
;       const unsigned char* sa = smem + (kt & 1) * 65536;
;       const unsigned char* sb = sa + 32768;
; #pragma unroll
;       for (int ks = 0; ks < 2; ++ks) {
;         const int fo = ks ? fro1 : fro0;
;         bf16x8 af[MI];
; #pragma unroll
;         for (int i = 0; i < MI; ++i) af[i] = *(const bf16x8*)(sa + (wm * 16 * MI + i * 16) * 128 + fo);
; #pragma unroll
;         for (int nh = 0; nh < NI; nh += 4) {
;           bf16x8 wf[4];
; #pragma unroll
;           for (int i = 0; i < 4; ++i) wf[i] = *(const bf16x8*)(sb + (wn * 16 * NI + (nh + i) * 16) * 128 + fo);
; #pragma unroll
;           for (int ni = 0; ni < 4; ++ni)
; #pragma unroll
;             for (int mi = 0; mi < MI; ++mi) acc[nh + ni][mi] = mfma16(wf[ni], af[mi], acc[nh + ni][mi]);
;         }
.Lk_outproj:
	s_waitcnt vmcnt(0) lgkmcnt(0)
	s_barrier
	ds_read_b128 v[162:165], v227 offset:32768
	ds_read_b128 v[122:125], v183
	ds_read_b128 v[126:129], v183 offset:2048
	ds_read_b128 v[130:133], v183 offset:4096
	ds_read_b128 v[138:141], v183 offset:6144
	ds_read_b128 v[184:187], v227 offset:34816
	ds_read_b128 v[188:191], v227 offset:36864
	s_and_b32 s92, s95, 1
	s_xor_b32 s92, s92, 1
	s_lshl_b32 s92, s92, 16
	s_waitcnt lgkmcnt(5)
	v_mfma_f32_16x16x32_bf16 v[134:137], v[162:165], v[122:125], v[134:137]
	ds_read_b128 v[192:195], v227 offset:38912
	s_waitcnt lgkmcnt(5)
	v_mfma_f32_16x16x32_bf16 v[118:121], v[162:165], v[126:129], v[118:121]
	s_waitcnt lgkmcnt(4)
	v_mfma_f32_16x16x32_bf16 v[114:117], v[162:165], v[130:133], v[114:117]
	s_add_u32 m0, s92, s94
	s_nop 0
	global_load_lds_dwordx4 v255, s[88:89]
	s_waitcnt lgkmcnt(3)
	v_mfma_f32_16x16x32_bf16 v[110:113], v[162:165], v[138:141], v[110:113]
	s_waitcnt lgkmcnt(2)
	v_mfma_f32_16x16x32_bf16 v[106:109], v[184:187], v[122:125], v[106:109]
	ds_read_b128 v[162:165], v227 offset:40960
	v_mfma_f32_16x16x32_bf16 v[102:105], v[184:187], v[126:129], v[102:105]
	ds_read_b128 v[142:145], v226
	v_mfma_f32_16x16x32_bf16 v[98:101], v[184:187], v[130:133], v[98:101]
	s_add_u32 m0, m0, 0x2000
	s_add_u32 s92, s88, 0x20000
	s_addc_u32 s93, s89, 0
	global_load_lds_dwordx4 v255, s[92:93]
	v_mfma_f32_16x16x32_bf16 v[94:97], v[184:187], v[138:141], v[94:97]
	s_waitcnt lgkmcnt(3)
	v_mfma_f32_16x16x32_bf16 v[90:93], v[188:191], v[122:125], v[90:93]
	ds_read_b128 v[184:187], v227 offset:43008
	v_mfma_f32_16x16x32_bf16 v[86:89], v[188:191], v[126:129], v[86:89]
	ds_read_b128 v[146:149], v226 offset:2048
	v_mfma_f32_16x16x32_bf16 v[78:81], v[188:191], v[130:133], v[78:81]
	s_add_u32 m0, m0, 0x2000
	s_add_u32 s92, s88, 0x40000
	s_addc_u32 s93, s89, 0
	global_load_lds_dwordx4 v255, s[92:93]
	v_mfma_f32_16x16x32_bf16 v[70:73], v[188:191], v[138:141], v[70:73]
	s_waitcnt lgkmcnt(4)
	v_mfma_f32_16x16x32_bf16 v[58:61], v[192:195], v[122:125], v[58:61]
	ds_read_b128 v[188:191], v227 offset:45056
	v_mfma_f32_16x16x32_bf16 v[54:57], v[192:195], v[126:129], v[54:57]
	ds_read_b128 v[150:153], v226 offset:4096
	v_mfma_f32_16x16x32_bf16 v[50:53], v[192:195], v[130:133], v[50:53]
	s_add_u32 m0, m0, 0x2000
	s_add_u32 s92, s88, 0x60000
	s_addc_u32 s93, s89, 0
	global_load_lds_dwordx4 v255, s[92:93]
	v_mfma_f32_16x16x32_bf16 v[46:49], v[192:195], v[138:141], v[46:49]
	s_waitcnt lgkmcnt(5)
	v_mfma_f32_16x16x32_bf16 v[42:45], v[162:165], v[122:125], v[42:45]
	ds_read_b128 v[192:195], v227 offset:47104
	v_mfma_f32_16x16x32_bf16 v[34:37], v[162:165], v[126:129], v[34:37]
	ds_read_b128 v[154:157], v226 offset:6144
	v_mfma_f32_16x16x32_bf16 v[22:25], v[162:165], v[130:133], v[22:25]
	s_add_u32 m0, m0, 0x2000
	s_nop 0
	global_load_lds_dwordx4 v255, s[90:91]
	v_mfma_f32_16x16x32_bf16 v[18:21], v[162:165], v[138:141], v[18:21]
	s_waitcnt lgkmcnt(5)
	v_mfma_f32_16x16x32_bf16 v[14:17], v[184:187], v[122:125], v[14:17]
	ds_read_b128 v[162:165], v254 offset:32768
	v_mfma_f32_16x16x32_bf16 v[6:9], v[184:187], v[126:129], v[6:9]
	v_mfma_f32_16x16x32_bf16 v[2:5], v[184:187], v[130:133], v[2:5]
	s_add_u32 m0, m0, 0x2000
	s_add_u32 s92, s90, 0x20000
	s_addc_u32 s93, s91, 0
	global_load_lds_dwordx4 v255, s[92:93]
	v_mfma_f32_16x16x32_bf16 v[30:33], v[184:187], v[138:141], v[30:33]
	s_waitcnt lgkmcnt(4)
	v_mfma_f32_16x16x32_bf16 v[10:13], v[188:191], v[122:125], v[10:13]
	ds_read_b128 v[184:187], v254 offset:34816
	v_mfma_f32_16x16x32_bf16 v[26:29], v[188:191], v[126:129], v[26:29]
	v_mfma_f32_16x16x32_bf16 v[38:41], v[188:191], v[130:133], v[38:41]
	s_add_u32 m0, m0, 0x2000
	s_add_u32 s92, s90, 0x40000
	s_addc_u32 s93, s91, 0
	global_load_lds_dwordx4 v255, s[92:93]
	v_mfma_f32_16x16x32_bf16 v[66:69], v[188:191], v[138:141], v[66:69]
	s_waitcnt lgkmcnt(3)
	v_mfma_f32_16x16x32_bf16 v[82:85], v[192:195], v[122:125], v[82:85]
	ds_read_b128 v[188:191], v254 offset:36864
	v_mfma_f32_16x16x32_bf16 v[74:77], v[192:195], v[126:129], v[74:77]
	v_mfma_f32_16x16x32_bf16 v[62:65], v[192:195], v[130:133], v[62:65]
	s_add_u32 m0, m0, 0x2000
	s_add_u32 s92, s90, 0x60000
	s_addc_u32 s93, s91, 0
	global_load_lds_dwordx4 v255, s[92:93]
	v_mfma_f32_16x16x32_bf16 v[158:161], v[192:195], v[138:141], v[158:161]
	s_waitcnt lgkmcnt(2)
	v_mfma_f32_16x16x32_bf16 v[134:137], v[162:165], v[142:145], v[134:137]
	ds_read_b128 v[192:195], v254 offset:38912
	v_mfma_f32_16x16x32_bf16 v[118:121], v[162:165], v[146:149], v[118:121]
	v_mfma_f32_16x16x32_bf16 v[114:117], v[162:165], v[150:153], v[114:117]
	v_mfma_f32_16x16x32_bf16 v[110:113], v[162:165], v[154:157], v[110:113]
	s_waitcnt lgkmcnt(2)
	v_mfma_f32_16x16x32_bf16 v[106:109], v[184:187], v[142:145], v[106:109]
	ds_read_b128 v[162:165], v254 offset:40960
	v_mfma_f32_16x16x32_bf16 v[102:105], v[184:187], v[146:149], v[102:105]
	v_mfma_f32_16x16x32_bf16 v[98:101], v[184:187], v[150:153], v[98:101]
	v_mfma_f32_16x16x32_bf16 v[94:97], v[184:187], v[154:157], v[94:97]
	s_waitcnt lgkmcnt(2)
	v_mfma_f32_16x16x32_bf16 v[90:93], v[188:191], v[142:145], v[90:93]
	ds_read_b128 v[184:187], v254 offset:43008
	v_mfma_f32_16x16x32_bf16 v[86:89], v[188:191], v[146:149], v[86:89]
	v_mfma_f32_16x16x32_bf16 v[78:81], v[188:191], v[150:153], v[78:81]
	v_mfma_f32_16x16x32_bf16 v[70:73], v[188:191], v[154:157], v[70:73]
	s_waitcnt lgkmcnt(2)
	v_mfma_f32_16x16x32_bf16 v[58:61], v[192:195], v[142:145], v[58:61]
	ds_read_b128 v[188:191], v254 offset:45056
	v_mfma_f32_16x16x32_bf16 v[54:57], v[192:195], v[146:149], v[54:57]
	v_mfma_f32_16x16x32_bf16 v[50:53], v[192:195], v[150:153], v[50:53]
	v_mfma_f32_16x16x32_bf16 v[46:49], v[192:195], v[154:157], v[46:49]
	s_waitcnt lgkmcnt(2)
; DI f32x4 mfma16(bf16x8 a, bf16x8 b, f32x4 c) { return __builtin_amdgcn_mfma_f32_16x16x32_bf16(a, b, c, 0, 0, 0); }
; template <int MI, int NI>
; DI void gemm_kloop(const u16* Au, int lda, const u16* Bu, int ldb, int K, f32x4 (&acc)[NI][MI], unsigned char* smem) {
;     ...
;   for (int kt = 0; kt < nk; ++kt) {
;     __syncthreads();
;     if (kt + 1 < nk) {
;       SWRITE((kt + 1) & 1);
;       if (kt + 2 < nk) GLOAD((kt + 2) << 6);
;     }
;     {
;       const unsigned char* sa = smem + (kt & 1) * 65536;
;       const unsigned char* sb = sa + 32768;
; #pragma unroll
;       for (int ks = 0; ks < 2; ++ks) {
;         const int fo = ks ? fro1 : fro0;
;         bf16x8 af[MI];
; #pragma unroll
;         for (int i = 0; i < MI; ++i) af[i] = *(const bf16x8*)(sa + (wm * 16 * MI + i * 16) * 128 + fo);
; #pragma unroll
;         for (int nh = 0; nh < NI; nh += 4) {
;           bf16x8 wf[4];
; #pragma unroll
;           for (int i = 0; i < 4; ++i) wf[i] = *(const bf16x8*)(sb + (wn * 16 * NI + (nh + i) * 16) * 128 + fo);
; #pragma unroll
;           for (int ni = 0; ni < 4; ++ni)
; #pragma unroll
;             for (int mi = 0; mi < MI; ++mi) acc[nh + ni][mi] = mfma16(wf[ni], af[mi], acc[nh + ni][mi]);
;         }
	v_mfma_f32_16x16x32_bf16 v[42:45], v[162:165], v[142:145], v[42:45]
	ds_read_b128 v[192:195], v254 offset:47104
	v_mfma_f32_16x16x32_bf16 v[34:37], v[162:165], v[146:149], v[34:37]
	v_mfma_f32_16x16x32_bf16 v[22:25], v[162:165], v[150:153], v[22:25]
	v_mfma_f32_16x16x32_bf16 v[18:21], v[162:165], v[154:157], v[18:21]
	s_waitcnt lgkmcnt(2)
	v_mfma_f32_16x16x32_bf16 v[14:17], v[184:187], v[142:145], v[14:17]
	v_mfma_f32_16x16x32_bf16 v[6:9], v[184:187], v[146:149], v[6:9]
	v_mfma_f32_16x16x32_bf16 v[2:5], v[184:187], v[150:153], v[2:5]
	v_mfma_f32_16x16x32_bf16 v[30:33], v[184:187], v[154:157], v[30:33]
	s_waitcnt lgkmcnt(1)
	v_mfma_f32_16x16x32_bf16 v[10:13], v[188:191], v[142:145], v[10:13]
	v_mfma_f32_16x16x32_bf16 v[26:29], v[188:191], v[146:149], v[26:29]
	v_mfma_f32_16x16x32_bf16 v[38:41], v[188:191], v[150:153], v[38:41]
	v_mfma_f32_16x16x32_bf16 v[66:69], v[188:191], v[154:157], v[66:69]
	s_waitcnt lgkmcnt(0)
	v_mfma_f32_16x16x32_bf16 v[82:85], v[192:195], v[142:145], v[82:85]
	v_mfma_f32_16x16x32_bf16 v[74:77], v[192:195], v[146:149], v[74:77]
	v_mfma_f32_16x16x32_bf16 v[62:65], v[192:195], v[150:153], v[62:65]
	v_mfma_f32_16x16x32_bf16 v[158:161], v[192:195], v[154:157], v[158:161]
	v_xor_b32_e32 v183, 0x10000, v183
	v_xor_b32_e32 v226, 0x10000, v226
	v_xor_b32_e32 v227, 0x10000, v227
	v_xor_b32_e32 v254, 0x10000, v254
	s_add_u32 s88, s88, 0x80
	s_addc_u32 s89, s89, 0
	s_add_u32 s90, s90, 0x80
	s_addc_u32 s91, s91, 0
	s_add_u32 s95, s95, 1
	s_cmp_lg_u32 s95, 14
	s_cbranch_scc1 .Lk_outproj
	s_waitcnt vmcnt(0)
	s_barrier
	s_add_u32 m0, s94, 0x10000
	s_nop 0
	global_load_lds_dwordx4 v255, s[88:89]
	s_add_u32 m0, m0, 0x2000
	s_add_u32 s92, s88, 0x20000
	s_addc_u32 s93, s89, 0
	global_load_lds_dwordx4 v255, s[92:93]
	s_add_u32 m0, m0, 0x2000
	s_add_u32 s92, s88, 0x40000
	s_addc_u32 s93, s89, 0
	global_load_lds_dwordx4 v255, s[92:93]
	s_add_u32 m0, m0, 0x2000
	s_add_u32 s92, s88, 0x60000
	s_addc_u32 s93, s89, 0
	global_load_lds_dwordx4 v255, s[92:93]
	s_add_u32 m0, m0, 0x2000
	s_nop 0
	global_load_lds_dwordx4 v255, s[90:91]
	s_add_u32 m0, m0, 0x2000
	s_add_u32 s92, s90, 0x20000
	s_addc_u32 s93, s91, 0
	global_load_lds_dwordx4 v255, s[92:93]
	s_add_u32 m0, m0, 0x2000
	s_add_u32 s92, s90, 0x40000
	s_addc_u32 s93, s91, 0
	global_load_lds_dwordx4 v255, s[92:93]
	s_add_u32 m0, m0, 0x2000
	s_add_u32 s92, s90, 0x60000
	s_addc_u32 s93, s91, 0
	global_load_lds_dwordx4 v255, s[92:93]
	v_add_u32_e32 v150, v181, v180
	ds_read_b128 v[122:125], v150 offset:32768
	v_add_u32_e32 v146, v179, v180
	ds_read_b128 v[126:129], v146
	ds_read_b128 v[130:133], v146 offset:2048
	ds_read_b128 v[138:141], v150 offset:34816
	ds_read_b128 v[142:145], v146 offset:4096
	ds_read_b128 v[146:149], v146 offset:6144
	s_waitcnt lgkmcnt(4)
	v_mfma_f32_16x16x32_bf16 v[134:137], v[122:125], v[126:129], v[134:137]
	v_add_u32_e32 v154, v181, v178
	v_or_b32_e32 v225, 0x18000, v181
	v_add_u32_e32 v192, v225, v180
	s_waitcnt lgkmcnt(3)
	v_mfma_f32_16x16x32_bf16 v[118:121], v[122:125], v[130:133], v[118:121]
	v_add_u32_e32 v225, v225, v178
	s_waitcnt lgkmcnt(1)
	v_mfma_f32_16x16x32_bf16 v[114:117], v[122:125], v[142:145], v[114:117]
	s_waitcnt lgkmcnt(0)
	v_mfma_f32_16x16x32_bf16 v[110:113], v[122:125], v[146:149], v[110:113]
	v_mfma_f32_16x16x32_bf16 v[106:109], v[138:141], v[126:129], v[106:109]
	v_mfma_f32_16x16x32_bf16 v[102:105], v[138:141], v[130:133], v[102:105]
	v_mfma_f32_16x16x32_bf16 v[98:101], v[138:141], v[142:145], v[98:101]
	v_mfma_f32_16x16x32_bf16 v[94:97], v[138:141], v[146:149], v[94:97]
	ds_read_b128 v[122:125], v150 offset:36864
	ds_read_b128 v[138:141], v150 offset:38912
	s_waitcnt lgkmcnt(1)
	v_mfma_f32_16x16x32_bf16 v[90:93], v[122:125], v[126:129], v[90:93]
	v_mfma_f32_16x16x32_bf16 v[86:89], v[122:125], v[130:133], v[86:89]
	v_mfma_f32_16x16x32_bf16 v[78:81], v[122:125], v[142:145], v[78:81]
	v_mfma_f32_16x16x32_bf16 v[70:73], v[122:125], v[146:149], v[70:73]
	s_waitcnt lgkmcnt(0)
	v_mfma_f32_16x16x32_bf16 v[58:61], v[138:141], v[126:129], v[58:61]
	v_mfma_f32_16x16x32_bf16 v[54:57], v[138:141], v[130:133], v[54:57]
	v_mfma_f32_16x16x32_bf16 v[50:53], v[138:141], v[142:145], v[50:53]
	v_mfma_f32_16x16x32_bf16 v[46:49], v[138:141], v[146:149], v[46:49]
	ds_read_b128 v[122:125], v150 offset:40960
	ds_read_b128 v[138:141], v150 offset:43008
	s_waitcnt lgkmcnt(1)
	v_mfma_f32_16x16x32_bf16 v[42:45], v[122:125], v[126:129], v[42:45]
	v_mfma_f32_16x16x32_bf16 v[34:37], v[122:125], v[130:133], v[34:37]
	v_mfma_f32_16x16x32_bf16 v[22:25], v[122:125], v[142:145], v[22:25]
	v_mfma_f32_16x16x32_bf16 v[18:21], v[122:125], v[146:149], v[18:21]
	s_waitcnt lgkmcnt(0)
	v_mfma_f32_16x16x32_bf16 v[14:17], v[138:141], v[126:129], v[14:17]
	v_mfma_f32_16x16x32_bf16 v[6:9], v[138:141], v[130:133], v[6:9]
	v_mfma_f32_16x16x32_bf16 v[2:5], v[138:141], v[142:145], v[2:5]
	v_mfma_f32_16x16x32_bf16 v[30:33], v[138:141], v[146:149], v[30:33]
	ds_read_b128 v[122:125], v150 offset:45056
	ds_read_b128 v[138:141], v150 offset:47104
	v_add_u32_e32 v150, v179, v178
	v_add_u32_e32 v179, 0x10000, v179
	s_waitcnt lgkmcnt(1)
	v_mfma_f32_16x16x32_bf16 v[10:13], v[122:125], v[126:129], v[10:13]
	v_mfma_f32_16x16x32_bf16 v[26:29], v[122:125], v[130:133], v[26:29]
	v_mfma_f32_16x16x32_bf16 v[38:41], v[122:125], v[142:145], v[38:41]
	v_mfma_f32_16x16x32_bf16 v[66:69], v[122:125], v[146:149], v[66:69]
	ds_read_b128 v[122:125], v154 offset:32768
	s_waitcnt lgkmcnt(1)
; DI f32x4 mfma16(bf16x8 a, bf16x8 b, f32x4 c) { return __builtin_amdgcn_mfma_f32_16x16x32_bf16(a, b, c, 0, 0, 0); }
; template <int MI, int NI>
; DI void gemm_kloop(const u16* Au, int lda, const u16* Bu, int ldb, int K, f32x4 (&acc)[NI][MI], unsigned char* smem) {
;     ...
;   for (int kt = 0; kt < nk; ++kt) {
;     __syncthreads();
;     if (kt + 1 < nk) {
;       SWRITE((kt + 1) & 1);
;       if (kt + 2 < nk) GLOAD((kt + 2) << 6);
;     }
;     {
;       const unsigned char* sa = smem + (kt & 1) * 65536;
;       const unsigned char* sb = sa + 32768;
; #pragma unroll
;       for (int ks = 0; ks < 2; ++ks) {
;         const int fo = ks ? fro1 : fro0;
;         bf16x8 af[MI];
; #pragma unroll
;         for (int i = 0; i < MI; ++i) af[i] = *(const bf16x8*)(sa + (wm * 16 * MI + i * 16) * 128 + fo);
; #pragma unroll
;         for (int nh = 0; nh < NI; nh += 4) {
;           bf16x8 wf[4];
; #pragma unroll
;           for (int i = 0; i < 4; ++i) wf[i] = *(const bf16x8*)(sb + (wn * 16 * NI + (nh + i) * 16) * 128 + fo);
; #pragma unroll
;           for (int ni = 0; ni < 4; ++ni)
; #pragma unroll
;             for (int mi = 0; mi < MI; ++mi) acc[nh + ni][mi] = mfma16(wf[ni], af[mi], acc[nh + ni][mi]);
;         }
;       }
;     }
;   }
;   __syncthreads();
	v_mfma_f32_16x16x32_bf16 v[82:85], v[138:141], v[126:129], v[82:85]
	v_mfma_f32_16x16x32_bf16 v[74:77], v[138:141], v[130:133], v[74:77]
	v_mfma_f32_16x16x32_bf16 v[62:65], v[138:141], v[142:145], v[62:65]
	v_mfma_f32_16x16x32_bf16 v[126:129], v[138:141], v[146:149], v[158:161]
	ds_read_b128 v[130:133], v150
	ds_read_b128 v[138:141], v150 offset:2048
	ds_read_b128 v[142:145], v154 offset:34816
	ds_read_b128 v[146:149], v150 offset:4096
	ds_read_b128 v[150:153], v150 offset:6144
	s_waitcnt lgkmcnt(4)
	v_mfma_f32_16x16x32_bf16 v[134:137], v[122:125], v[130:133], v[134:137]
	s_waitcnt lgkmcnt(3)
	v_mfma_f32_16x16x32_bf16 v[118:121], v[122:125], v[138:141], v[118:121]
	s_waitcnt lgkmcnt(1)
	v_mfma_f32_16x16x32_bf16 v[114:117], v[122:125], v[146:149], v[114:117]
	s_waitcnt lgkmcnt(0)
	v_mfma_f32_16x16x32_bf16 v[110:113], v[122:125], v[150:153], v[110:113]
	v_mfma_f32_16x16x32_bf16 v[106:109], v[142:145], v[130:133], v[106:109]
	v_mfma_f32_16x16x32_bf16 v[102:105], v[142:145], v[138:141], v[102:105]
	v_mfma_f32_16x16x32_bf16 v[98:101], v[142:145], v[146:149], v[98:101]
	v_mfma_f32_16x16x32_bf16 v[94:97], v[142:145], v[150:153], v[94:97]
	ds_read_b128 v[122:125], v154 offset:36864
	ds_read_b128 v[142:145], v154 offset:38912
	s_waitcnt lgkmcnt(1)
	v_mfma_f32_16x16x32_bf16 v[90:93], v[122:125], v[130:133], v[90:93]
	v_mfma_f32_16x16x32_bf16 v[86:89], v[122:125], v[138:141], v[86:89]
	v_mfma_f32_16x16x32_bf16 v[78:81], v[122:125], v[146:149], v[78:81]
	v_mfma_f32_16x16x32_bf16 v[70:73], v[122:125], v[150:153], v[70:73]
	s_waitcnt lgkmcnt(0)
	v_mfma_f32_16x16x32_bf16 v[58:61], v[142:145], v[130:133], v[58:61]
	v_mfma_f32_16x16x32_bf16 v[54:57], v[142:145], v[138:141], v[54:57]
	v_mfma_f32_16x16x32_bf16 v[50:53], v[142:145], v[146:149], v[50:53]
	v_mfma_f32_16x16x32_bf16 v[46:49], v[142:145], v[150:153], v[46:49]
	ds_read_b128 v[122:125], v154 offset:40960
	ds_read_b128 v[142:145], v154 offset:43008
	s_waitcnt lgkmcnt(1)
	v_mfma_f32_16x16x32_bf16 v[42:45], v[122:125], v[130:133], v[42:45]
	v_mfma_f32_16x16x32_bf16 v[34:37], v[122:125], v[138:141], v[34:37]
	v_mfma_f32_16x16x32_bf16 v[22:25], v[122:125], v[146:149], v[22:25]
	v_mfma_f32_16x16x32_bf16 v[18:21], v[122:125], v[150:153], v[18:21]
	s_waitcnt lgkmcnt(0)
	v_mfma_f32_16x16x32_bf16 v[14:17], v[142:145], v[130:133], v[14:17]
	v_mfma_f32_16x16x32_bf16 v[6:9], v[142:145], v[138:141], v[6:9]
	v_mfma_f32_16x16x32_bf16 v[2:5], v[142:145], v[146:149], v[2:5]
	v_mfma_f32_16x16x32_bf16 v[30:33], v[142:145], v[150:153], v[30:33]
	ds_read_b128 v[122:125], v154 offset:45056
	ds_read_b128 v[142:145], v154 offset:47104
	s_waitcnt vmcnt(0) lgkmcnt(0)
	s_barrier
	v_mfma_f32_16x16x32_bf16 v[10:13], v[122:125], v[130:133], v[10:13]
	v_mfma_f32_16x16x32_bf16 v[26:29], v[122:125], v[138:141], v[26:29]
	v_mfma_f32_16x16x32_bf16 v[38:41], v[122:125], v[146:149], v[38:41]
	v_mfma_f32_16x16x32_bf16 v[66:69], v[122:125], v[150:153], v[66:69]
	ds_read_b128 v[122:125], v192
	v_mfma_f32_16x16x32_bf16 v[126:129], v[142:145], v[150:153], v[126:129]
	v_add_u32_e32 v150, v179, v180
	v_mfma_f32_16x16x32_bf16 v[82:85], v[142:145], v[130:133], v[82:85]
	v_mfma_f32_16x16x32_bf16 v[74:77], v[142:145], v[138:141], v[74:77]
	v_mfma_f32_16x16x32_bf16 v[62:65], v[142:145], v[146:149], v[62:65]
	ds_read_b128 v[130:133], v150
	ds_read_b128 v[138:141], v150 offset:2048
	ds_read_b128 v[142:145], v192 offset:2048
	ds_read_b128 v[146:149], v150 offset:4096
	ds_read_b128 v[150:153], v150 offset:6144
	s_waitcnt lgkmcnt(4)
	v_mfma_f32_16x16x32_bf16 v[134:137], v[122:125], v[130:133], v[134:137]
	s_waitcnt lgkmcnt(3)
	v_mfma_f32_16x16x32_bf16 v[118:121], v[122:125], v[138:141], v[118:121]
	s_waitcnt lgkmcnt(1)
	v_mfma_f32_16x16x32_bf16 v[114:117], v[122:125], v[146:149], v[114:117]
	s_waitcnt lgkmcnt(0)
	v_mfma_f32_16x16x32_bf16 v[110:113], v[122:125], v[150:153], v[110:113]
	v_mfma_f32_16x16x32_bf16 v[106:109], v[142:145], v[130:133], v[106:109]
	v_mfma_f32_16x16x32_bf16 v[102:105], v[142:145], v[138:141], v[102:105]
	v_mfma_f32_16x16x32_bf16 v[98:101], v[142:145], v[146:149], v[98:101]
	v_mfma_f32_16x16x32_bf16 v[142:145], v[142:145], v[150:153], v[94:97]
	s_nop 2
	ds_read_b128 v[94:97], v192 offset:4096
	ds_read_b128 v[122:125], v192 offset:6144
	s_waitcnt lgkmcnt(0)
	v_mfma_f32_16x16x32_bf16 v[158:161], v[122:125], v[130:133], v[58:61]
	v_mfma_f32_16x16x32_bf16 v[162:165], v[122:125], v[138:141], v[54:57]
	s_nop 2
	ds_read_b128 v[54:57], v192 offset:8192
	ds_read_b128 v[58:61], v192 offset:10240
	s_waitcnt lgkmcnt(1)
	v_mfma_f32_16x16x32_bf16 v[180:183], v[54:57], v[150:153], v[18:21]
	s_waitcnt lgkmcnt(0)
	v_mfma_f32_16x16x32_bf16 v[184:187], v[58:61], v[130:133], v[14:17]
	s_nop 2
	ds_read_b128 v[14:17], v192 offset:12288
	ds_read_b128 v[18:21], v192 offset:14336
	s_waitcnt lgkmcnt(1)
	v_mfma_f32_16x16x32_bf16 v[192:195], v[14:17], v[130:133], v[10:13]
	s_nop 2
	ds_read_b128 v[10:13], v225
	v_mfma_f32_16x16x32_bf16 v[154:157], v[94:97], v[130:133], v[90:93]
	v_mfma_f32_16x16x32_bf16 v[86:89], v[94:97], v[138:141], v[86:89]
	v_mfma_f32_16x16x32_bf16 v[78:81], v[94:97], v[146:149], v[78:81]
	v_mfma_f32_16x16x32_bf16 v[70:73], v[94:97], v[150:153], v[70:73]
	v_mfma_f32_16x16x32_bf16 v[50:53], v[122:125], v[146:149], v[50:53]
	v_mfma_f32_16x16x32_bf16 v[46:49], v[122:125], v[150:153], v[46:49]
	v_mfma_f32_16x16x32_bf16 v[42:45], v[54:57], v[130:133], v[42:45]
	v_mfma_f32_16x16x32_bf16 v[34:37], v[54:57], v[138:141], v[34:37]
	v_mfma_f32_16x16x32_bf16 v[168:171], v[54:57], v[146:149], v[22:25]
	v_mfma_f32_16x16x32_bf16 v[6:9], v[58:61], v[138:141], v[6:9]
	v_mfma_f32_16x16x32_bf16 v[2:5], v[58:61], v[146:149], v[2:5]
	v_mfma_f32_16x16x32_bf16 v[188:191], v[58:61], v[150:153], v[30:33]
	v_mfma_f32_16x16x32_bf16 v[226:229], v[14:17], v[138:141], v[26:29]
	v_mfma_f32_16x16x32_bf16 v[38:41], v[14:17], v[146:149], v[38:41]
	v_mfma_f32_16x16x32_bf16 v[66:69], v[14:17], v[150:153], v[66:69]
	s_waitcnt lgkmcnt(1)
; DI f32x4 mfma16(bf16x8 a, bf16x8 b, f32x4 c) { return __builtin_amdgcn_mfma_f32_16x16x32_bf16(a, b, c, 0, 0, 0); }
; template <int MI, int NI>
; DI void gemm_kloop(const u16* Au, int lda, const u16* Bu, int ldb, int K, f32x4 (&acc)[NI][MI], unsigned char* smem) {
;     ...
;       for (int ks = 0; ks < 2; ++ks) {
;         const int fo = ks ? fro1 : fro0;
;         bf16x8 af[MI];
; #pragma unroll
;         for (int i = 0; i < MI; ++i) af[i] = *(const bf16x8*)(sa + (wm * 16 * MI + i * 16) * 128 + fo);
; #pragma unroll
;         for (int nh = 0; nh < NI; nh += 4) {
;           bf16x8 wf[4];
; #pragma unroll
;           for (int i = 0; i < 4; ++i) wf[i] = *(const bf16x8*)(sb + (wn * 16 * NI + (nh + i) * 16) * 128 + fo);
; #pragma unroll
;           for (int ni = 0; ni < 4; ++ni)
; #pragma unroll
;             for (int mi = 0; mi < MI; ++mi) acc[nh + ni][mi] = mfma16(wf[ni], af[mi], acc[nh + ni][mi]);
;         }
; template <int MI, int NI>
; DI void resid_epilogue(const Params& p, int from_x, const f32x4 (&acc)[NI][MI], int row0, int n0, float* rowss_next, bool last, int lm, int lg) {
; #pragma unroll
;   for (int mi = 0; mi < MI; ++mi) {
;     const int m = row0 + mi * 16 + lm;
;     const float* hr = hrow_r(p, from_x == 1 ? 0 : 1, m);
;     float* hw = hrow_w(p, m);
;     u16* hbr = p.hb + (size_t)m * DM;
;     float ss = 0.f;
; #pragma unroll
;     for (int ni = 0; ni < NI; ++ni) {
;       const int n = n0 + ni * 16 + lg * 4;
;       float4 h;
;       if (from_x >= 2) {
;         const u32x2 pk = *(const u32x2*)(hbr + n);
;         h = make_float4(__uint_as_float(pk[0] << 16), __uint_as_float(pk[0] & 0xffff0000u), __uint_as_float(pk[1] << 16), __uint_as_float(pk[1] & 0xffff0000u));
;       } else h = *(const float4*)(hr + n);
	v_mfma_f32_16x16x32_bf16 v[130:133], v[18:21], v[130:133], v[82:85]
	v_mfma_f32_16x16x32_bf16 v[138:141], v[18:21], v[138:141], v[74:77]
	v_mfma_f32_16x16x32_bf16 v[146:149], v[18:21], v[146:149], v[62:65]
	v_mfma_f32_16x16x32_bf16 v[150:153], v[18:21], v[150:153], v[126:129]
	v_add_u32_e32 v18, v179, v178
	ds_read_b128 v[230:233], v18
	ds_read_b128 v[234:237], v18 offset:2048
	ds_read_b128 v[14:17], v225 offset:2048
	ds_read_b128 v[238:241], v18 offset:4096
	ds_read_b128 v[248:251], v18 offset:6144
	s_waitcnt lgkmcnt(4)
	v_mfma_f32_16x16x32_bf16 v[126:129], v[10:13], v[230:233], v[134:137]
	s_nop 2
	v_add_u32_e32 v136, s34, v176
	s_waitcnt lgkmcnt(3)
	v_mfma_f32_16x16x32_bf16 v[94:97], v[10:13], v[234:237], v[118:121]
	s_waitcnt lgkmcnt(1)
	v_mfma_f32_16x16x32_bf16 v[62:65], v[10:13], v[238:241], v[114:117]
	s_waitcnt lgkmcnt(0)
	v_mfma_f32_16x16x32_bf16 v[30:33], v[10:13], v[248:251], v[110:113]
	v_mfma_f32_16x16x32_bf16 v[122:125], v[14:17], v[230:233], v[106:109]
	v_mfma_f32_16x16x32_bf16 v[90:93], v[14:17], v[234:237], v[102:105]
	v_mfma_f32_16x16x32_bf16 v[58:61], v[14:17], v[238:241], v[98:101]
	v_mfma_f32_16x16x32_bf16 v[26:29], v[14:17], v[248:251], v[142:145]
	ds_read_b128 v[10:13], v225 offset:4096
	ds_read_b128 v[14:17], v225 offset:6144
	s_waitcnt lgkmcnt(1)
	v_mfma_f32_16x16x32_bf16 v[118:121], v[10:13], v[230:233], v[154:157]
	v_mfma_f32_16x16x32_bf16 v[86:89], v[10:13], v[234:237], v[86:89]
	v_mfma_f32_16x16x32_bf16 v[54:57], v[10:13], v[238:241], v[78:81]
	v_mfma_f32_16x16x32_bf16 v[22:25], v[10:13], v[248:251], v[70:73]
	ds_read_b128 v[10:13], v225 offset:8192
	s_nop 1
	ds_read_b128 v[70:73], v225 offset:10240
	s_waitcnt lgkmcnt(1)
	v_mfma_f32_16x16x32_bf16 v[110:113], v[10:13], v[230:233], v[42:45]
	s_waitcnt lgkmcnt(0)
	v_mfma_f32_16x16x32_bf16 v[42:45], v[70:73], v[238:241], v[2:5]
	s_nop 2
	ds_read_b128 v[2:5], v225 offset:12288
	ds_read_b128 v[142:145], v225 offset:14336
	s_waitcnt lgkmcnt(0)
	s_barrier
	v_mfma_f32_16x16x32_bf16 v[114:117], v[14:17], v[230:233], v[158:161]
	v_mfma_f32_16x16x32_bf16 v[82:85], v[14:17], v[234:237], v[162:165]
	v_mfma_f32_16x16x32_bf16 v[50:53], v[14:17], v[238:241], v[50:53]
	v_mfma_f32_16x16x32_bf16 v[18:21], v[14:17], v[248:251], v[46:49]
	v_mfma_f32_16x16x32_bf16 v[78:81], v[10:13], v[234:237], v[34:37]
	v_mfma_f32_16x16x32_bf16 v[46:49], v[10:13], v[238:241], v[168:171]
	v_mfma_f32_16x16x32_bf16 v[14:17], v[10:13], v[248:251], v[180:183]
	v_mfma_f32_16x16x32_bf16 v[106:109], v[70:73], v[230:233], v[184:187]
	v_mfma_f32_16x16x32_bf16 v[74:77], v[70:73], v[234:237], v[6:9]
	v_mfma_f32_16x16x32_bf16 v[10:13], v[70:73], v[248:251], v[188:191]
	v_mfma_f32_16x16x32_bf16 v[102:105], v[2:5], v[230:233], v[192:195]
	v_mfma_f32_16x16x32_bf16 v[70:73], v[2:5], v[234:237], v[226:229]
	v_mfma_f32_16x16x32_bf16 v[38:41], v[2:5], v[238:241], v[38:41]
	v_mfma_f32_16x16x32_bf16 v[6:9], v[2:5], v[248:251], v[66:69]
	v_mul_hi_i32 v2, v136, s81
	v_lshrrev_b32_e32 v3, 31, v2
	v_ashrrev_i32_e32 v2, 10, v2
	v_mfma_f32_16x16x32_bf16 v[98:101], v[142:145], v[230:233], v[130:133]
	v_mfma_f32_16x16x32_bf16 v[66:69], v[142:145], v[234:237], v[138:141]
	s_nop 1
	v_add_u32_e32 v132, v2, v3
	v_mad_i32_i24 v130, v132, s82, v136
	v_add_u32_e32 v133, -16, v130
	v_mfma_f32_16x16x32_bf16 v[34:37], v[142:145], v[238:241], v[146:149]
	v_cmp_lt_u32_e32 vcc, s83, v133
	v_mfma_f32_16x16x32_bf16 v[2:5], v[142:145], v[248:251], v[150:153]
	s_load_dwordx2 s[56:57], s[0:1], 0xc8
	s_load_dwordx2 s[58:59], s[0:1], 0xd8
	s_lshr_b32 s2, s49, 4
	s_lshl_b32 s2, s2, 2
	s_and_b32 s3, s49, 3
	s_or_b32 s2, s2, s3
	s_lshl_b32 s2, s2, 8
	s_lshr_b32 s3, s49, 2
	s_and_b32 s3, s3, 3
	s_lshl_b32 s3, s3, 8
	v_add_u32_e32 v130, s2, v176
	v_or_b32_e32 v131, s3, v177
	s_and_b64 vcc, exec, s[4:5]
	s_cbranch_vccnz .Lre_outproj_T
	s_load_dwordx2 s[60:61], s[0:1], 0x0
	s_waitcnt lgkmcnt(0)
	v_add_u32_e32 v168, 0, v130
	v_lshlrev_b32_e32 v168, 11, v168
	v_lshl_add_u32 v242, v131, 1, v168
	v_add_u32_e32 v168, 0, v130
	v_mul_hi_i32 v169, v168, s81
	v_lshrrev_b32_e32 v170, 31, v169
	v_ashrrev_i32_e32 v169, 10, v169
	v_add_u32_e32 v169, v169, v170
	v_mad_i32_i24 v170, v169, s82, v168
	v_add_u32_e32 v171, -16, v170
	v_cmp_lt_u32_e32 vcc, s83, v171
	v_lshl_add_u32 v171, v169, 12, v171
	v_add_u32_e32 v168, 0xfffff000, v170
	v_cmp_gt_i32_e64 s[2:3], 16, v170
	s_nop 1
	v_cndmask_b32_e64 v168, v168, v170, s[2:3]
	v_lshl_add_u32 v168, v169, 7, v168
	v_cndmask_b32_e32 v168, v171, v168, vcc
	v_mov_b32_e32 v169, s60
	v_mov_b32_e32 v170, s58
	v_cndmask_b32_e32 v248, v169, v170, vcc
	v_mov_b32_e32 v169, s61
	v_mov_b32_e32 v170, s59
	v_cndmask_b32_e32 v249, v169, v170, vcc
	v_lshlrev_b32_e32 v168, 12, v168
	v_lshl_add_u32 v168, v131, 2, v168
	v_add_co_u32_e32 v248, vcc, v248, v168
	s_nop 1
	v_addc_co_u32_e32 v249, vcc, 0, v249, vcc
	global_load_dwordx4 v[132:135], v[248:249], off offset:0
	global_load_dwordx4 v[136:139], v[248:249], off offset:64
	global_load_dwordx4 v[140:143], v[248:249], off offset:128
	global_load_dwordx4 v[144:147], v[248:249], off offset:192
	global_load_dwordx4 v[148:151], v[248:249], off offset:256
	global_load_dwordx4 v[152:155], v[248:249], off offset:320
	global_load_dwordx4 v[156:159], v[248:249], off offset:384
	global_load_dwordx4 v[160:163], v[248:249], off offset:448
	v_add_u32_e32 v168, 16, v130
	v_lshlrev_b32_e32 v168, 11, v168
	v_lshl_add_u32 v243, v131, 1, v168
	v_add_u32_e32 v168, 16, v130
	v_mul_hi_i32 v169, v168, s81
	v_lshrrev_b32_e32 v170, 31, v169
	v_ashrrev_i32_e32 v169, 10, v169
	v_add_u32_e32 v169, v169, v170
	v_mad_i32_i24 v170, v169, s82, v168
	v_add_u32_e32 v171, -16, v170
	v_cmp_lt_u32_e32 vcc, s83, v171
	v_lshl_add_u32 v171, v169, 12, v171
	v_add_u32_e32 v168, 0xfffff000, v170
	v_cmp_gt_i32_e64 s[2:3], 16, v170
	s_nop 1
	v_cndmask_b32_e64 v168, v168, v170, s[2:3]
	v_lshl_add_u32 v168, v169, 7, v168
	v_cndmask_b32_e32 v168, v171, v168, vcc
	v_mov_b32_e32 v169, s60
	v_mov_b32_e32 v170, s58
	v_cndmask_b32_e32 v250, v169, v170, vcc
	v_mov_b32_e32 v169, s61
	v_mov_b32_e32 v170, s59
	v_cndmask_b32_e32 v251, v169, v170, vcc
	v_lshlrev_b32_e32 v168, 12, v168
	v_lshl_add_u32 v168, v131, 2, v168
	v_add_co_u32_e32 v250, vcc, v250, v168
	s_nop 1
	v_addc_co_u32_e32 v251, vcc, 0, v251, vcc
	global_load_dwordx4 v[178:181], v[250:251], off offset:0
	global_load_dwordx4 v[182:185], v[250:251], off offset:64
	global_load_dwordx4 v[186:189], v[250:251], off offset:128
	global_load_dwordx4 v[190:193], v[250:251], off offset:192
	global_load_dwordx4 v[226:229], v[250:251], off offset:256
	global_load_dwordx4 v[230:233], v[250:251], off offset:320
	global_load_dwordx4 v[234:237], v[250:251], off offset:384
	global_load_dwordx4 v[238:241], v[250:251], off offset:448
	s_waitcnt vmcnt(15)
; template <int MI, int NI>
; DI void resid_epilogue(const Params& p, int from_x, const f32x4 (&acc)[NI][MI], int row0, int n0, float* rowss_next, bool last, int lm, int lg) {
;     ...
;     for (int ni = 0; ni < NI; ++ni) {
;       const int n = n0 + ni * 16 + lg * 4;
;       float4 h;
;       if (from_x >= 2) {
;         const u32x2 pk = *(const u32x2*)(hbr + n);
;         h = make_float4(__uint_as_float(pk[0] << 16), __uint_as_float(pk[0] & 0xffff0000u), __uint_as_float(pk[1] << 16), __uint_as_float(pk[1] & 0xffff0000u));
;       } else h = *(const float4*)(hr + n);
;       h.x += acc[ni][mi][0]; h.y += acc[ni][mi][1]; h.z += acc[ni][mi][2]; h.w += acc[ni][mi][3];
;       if (last) *(float4*)(hw + n) = h;
;       if (!last) {
;         u32x2 pk = {pack2bf(h.x, h.y), pack2bf(h.z, h.w)};
;         *(u32x2*)(hbr + n) = pk;
;         ss += h.x * h.x + h.y * h.y + h.z * h.z + h.w * h.w;
;       }
;     }
;     if (!last) {
;       ss += __shfl_xor(ss, 16);
;       ss += __shfl_xor(ss, 32);
;       if (lg == 0) atomicAdd(rowss_next + m, ss);
	v_pk_add_f32 v[194:195], v[126:127], v[132:133]
	v_pk_add_f32 v[254:255], v[128:129], v[134:135]
	v_cvt_pk_bf16_f32 v168, v194, v195
	v_cvt_pk_bf16_f32 v169, v254, v255
	global_store_dwordx2 v242, v[168:169], s[56:57] offset:0
	v_pk_mul_f32 v[194:195], v[194:195], v[194:195]
	v_pk_mul_f32 v[254:255], v[254:255], v[254:255]
	v_add_f32_e32 v170, v195, v194
	v_add_f32_e32 v170, v254, v170
	v_add_f32_e32 v170, v255, v170
	v_mov_b32_e32 v164, v170
	s_waitcnt vmcnt(15)
	v_pk_add_f32 v[194:195], v[122:123], v[136:137]
	v_pk_add_f32 v[254:255], v[124:125], v[138:139]
	v_cvt_pk_bf16_f32 v168, v194, v195
	v_cvt_pk_bf16_f32 v169, v254, v255
	global_store_dwordx2 v242, v[168:169], s[56:57] offset:32
	v_pk_mul_f32 v[194:195], v[194:195], v[194:195]
	v_pk_mul_f32 v[254:255], v[254:255], v[254:255]
	v_add_f32_e32 v170, v195, v194
	v_add_f32_e32 v170, v254, v170
	v_add_f32_e32 v170, v255, v170
	v_add_f32_e32 v164, v164, v170
	s_waitcnt vmcnt(15)
	v_pk_add_f32 v[194:195], v[118:119], v[140:141]
	v_pk_add_f32 v[254:255], v[120:121], v[142:143]
	v_cvt_pk_bf16_f32 v168, v194, v195
	v_cvt_pk_bf16_f32 v169, v254, v255
	global_store_dwordx2 v242, v[168:169], s[56:57] offset:64
	v_pk_mul_f32 v[194:195], v[194:195], v[194:195]
	v_pk_mul_f32 v[254:255], v[254:255], v[254:255]
	v_add_f32_e32 v170, v195, v194
	v_add_f32_e32 v170, v254, v170
	v_add_f32_e32 v170, v255, v170
	v_add_f32_e32 v164, v164, v170
	s_waitcnt vmcnt(15)
	v_pk_add_f32 v[194:195], v[114:115], v[144:145]
	v_pk_add_f32 v[254:255], v[116:117], v[146:147]
	v_cvt_pk_bf16_f32 v168, v194, v195
	v_cvt_pk_bf16_f32 v169, v254, v255
	global_store_dwordx2 v242, v[168:169], s[56:57] offset:96
	v_pk_mul_f32 v[194:195], v[194:195], v[194:195]
	v_pk_mul_f32 v[254:255], v[254:255], v[254:255]
	v_add_f32_e32 v170, v195, v194
	v_add_f32_e32 v170, v254, v170
	v_add_f32_e32 v170, v255, v170
	v_add_f32_e32 v164, v164, v170
	s_waitcnt vmcnt(15)
	v_pk_add_f32 v[194:195], v[110:111], v[148:149]
	v_pk_add_f32 v[254:255], v[112:113], v[150:151]
	v_cvt_pk_bf16_f32 v168, v194, v195
	v_cvt_pk_bf16_f32 v169, v254, v255
	global_store_dwordx2 v242, v[168:169], s[56:57] offset:128
	v_pk_mul_f32 v[194:195], v[194:195], v[194:195]
	v_pk_mul_f32 v[254:255], v[254:255], v[254:255]
	v_add_f32_e32 v170, v195, v194
	v_add_f32_e32 v170, v254, v170
	v_add_f32_e32 v170, v255, v170
	v_add_f32_e32 v164, v164, v170
	s_waitcnt vmcnt(15)
	v_pk_add_f32 v[194:195], v[106:107], v[152:153]
	v_pk_add_f32 v[254:255], v[108:109], v[154:155]
	v_cvt_pk_bf16_f32 v168, v194, v195
	v_cvt_pk_bf16_f32 v169, v254, v255
	global_store_dwordx2 v242, v[168:169], s[56:57] offset:160
	v_pk_mul_f32 v[194:195], v[194:195], v[194:195]
	v_pk_mul_f32 v[254:255], v[254:255], v[254:255]
	v_add_f32_e32 v170, v195, v194
	v_add_f32_e32 v170, v254, v170
	v_add_f32_e32 v170, v255, v170
	v_add_f32_e32 v164, v164, v170
	s_waitcnt vmcnt(15)
	v_pk_add_f32 v[194:195], v[102:103], v[156:157]
	v_pk_add_f32 v[254:255], v[104:105], v[158:159]
	v_cvt_pk_bf16_f32 v168, v194, v195
	v_cvt_pk_bf16_f32 v169, v254, v255
	global_store_dwordx2 v242, v[168:169], s[56:57] offset:192
	v_pk_mul_f32 v[194:195], v[194:195], v[194:195]
	v_pk_mul_f32 v[254:255], v[254:255], v[254:255]
	v_add_f32_e32 v170, v195, v194
	v_add_f32_e32 v170, v254, v170
	v_add_f32_e32 v170, v255, v170
	v_add_f32_e32 v164, v164, v170
	s_waitcnt vmcnt(15)
	v_pk_add_f32 v[194:195], v[98:99], v[160:161]
	v_pk_add_f32 v[254:255], v[100:101], v[162:163]
	v_cvt_pk_bf16_f32 v168, v194, v195
	v_cvt_pk_bf16_f32 v169, v254, v255
	global_store_dwordx2 v242, v[168:169], s[56:57] offset:224
	v_pk_mul_f32 v[194:195], v[194:195], v[194:195]
	v_pk_mul_f32 v[254:255], v[254:255], v[254:255]
	v_add_f32_e32 v170, v195, v194
	v_add_f32_e32 v170, v254, v170
	v_add_f32_e32 v170, v255, v170
	v_add_f32_e32 v164, v164, v170
	v_xor_b32_e32 v168, 16, v207
	v_lshlrev_b32_e32 v168, 2, v168
	ds_bpermute_b32 v169, v168, v164
	v_xor_b32_e32 v168, 32, v207
	v_lshlrev_b32_e32 v168, 2, v168
	s_waitcnt lgkmcnt(0)
	v_add_f32_e32 v164, v164, v169
	ds_bpermute_b32 v169, v168, v164
	v_add_u32_e32 v170, 0, v130
	v_lshlrev_b32_e32 v170, 2, v170
	v_and_b32_e32 v171, 63, v207
	v_cmp_gt_u32_e32 vcc, 16, v171
	s_waitcnt lgkmcnt(0)
	v_add_f32_e32 v164, v164, v169
	s_and_saveexec_b64 s[2:3], vcc
	global_atomic_add_f32 v170, v164, s[8:9]
	s_or_b64 exec, exec, s[2:3]
	v_add_u32_e32 v168, 32, v130
	v_lshlrev_b32_e32 v168, 11, v168
	v_lshl_add_u32 v242, v131, 1, v168
	v_add_u32_e32 v168, 32, v130
	v_mul_hi_i32 v169, v168, s81
	v_lshrrev_b32_e32 v170, 31, v169
	v_ashrrev_i32_e32 v169, 10, v169
	v_add_u32_e32 v169, v169, v170
	v_mad_i32_i24 v170, v169, s82, v168
	v_add_u32_e32 v171, -16, v170
	v_cmp_lt_u32_e32 vcc, s83, v171
	v_lshl_add_u32 v171, v169, 12, v171
	v_add_u32_e32 v168, 0xfffff000, v170
	v_cmp_gt_i32_e64 s[2:3], 16, v170
	s_nop 1
	v_cndmask_b32_e64 v168, v168, v170, s[2:3]
	v_lshl_add_u32 v168, v169, 7, v168
	v_cndmask_b32_e32 v168, v171, v168, vcc
	v_mov_b32_e32 v169, s60
	v_mov_b32_e32 v170, s58
	v_cndmask_b32_e32 v248, v169, v170, vcc
	v_mov_b32_e32 v169, s61
	v_mov_b32_e32 v170, s59
	v_cndmask_b32_e32 v249, v169, v170, vcc
	v_lshlrev_b32_e32 v168, 12, v168
	v_lshl_add_u32 v168, v131, 2, v168
	v_add_co_u32_e32 v248, vcc, v248, v168
	s_nop 1
	v_addc_co_u32_e32 v249, vcc, 0, v249, vcc
	global_load_dwordx4 v[132:135], v[248:249], off offset:0
	global_load_dwordx4 v[136:139], v[248:249], off offset:64
	global_load_dwordx4 v[140:143], v[248:249], off offset:128
	global_load_dwordx4 v[144:147], v[248:249], off offset:192
	global_load_dwordx4 v[148:151], v[248:249], off offset:256
	global_load_dwordx4 v[152:155], v[248:249], off offset:320
	global_load_dwordx4 v[156:159], v[248:249], off offset:384
	global_load_dwordx4 v[160:163], v[248:249], off offset:448
	s_waitcnt vmcnt(24)
; template <int MI, int NI>
; DI void resid_epilogue(const Params& p, int from_x, const f32x4 (&acc)[NI][MI], int row0, int n0, float* rowss_next, bool last, int lm, int lg) {
;     ...
;     for (int ni = 0; ni < NI; ++ni) {
;       const int n = n0 + ni * 16 + lg * 4;
;       float4 h;
;       if (from_x >= 2) {
;         const u32x2 pk = *(const u32x2*)(hbr + n);
;         h = make_float4(__uint_as_float(pk[0] << 16), __uint_as_float(pk[0] & 0xffff0000u), __uint_as_float(pk[1] << 16), __uint_as_float(pk[1] & 0xffff0000u));
;       } else h = *(const float4*)(hr + n);
;       h.x += acc[ni][mi][0]; h.y += acc[ni][mi][1]; h.z += acc[ni][mi][2]; h.w += acc[ni][mi][3];
;       if (last) *(float4*)(hw + n) = h;
;       if (!last) {
;         u32x2 pk = {pack2bf(h.x, h.y), pack2bf(h.z, h.w)};
;         *(u32x2*)(hbr + n) = pk;
;         ss += h.x * h.x + h.y * h.y + h.z * h.z + h.w * h.w;
;       }
;     }
;     if (!last) {
;       ss += __shfl_xor(ss, 16);
;       ss += __shfl_xor(ss, 32);
;       if (lg == 0) atomicAdd(rowss_next + m, ss);
	v_pk_add_f32 v[194:195], v[94:95], v[178:179]
	v_pk_add_f32 v[254:255], v[96:97], v[180:181]
	v_cvt_pk_bf16_f32 v168, v194, v195
	v_cvt_pk_bf16_f32 v169, v254, v255
	global_store_dwordx2 v243, v[168:169], s[56:57] offset:0
	v_pk_mul_f32 v[194:195], v[194:195], v[194:195]
	v_pk_mul_f32 v[254:255], v[254:255], v[254:255]
	v_add_f32_e32 v170, v195, v194
	v_add_f32_e32 v170, v254, v170
	v_add_f32_e32 v170, v255, v170
	v_mov_b32_e32 v164, v170
	s_waitcnt vmcnt(24)
	v_pk_add_f32 v[194:195], v[90:91], v[182:183]
	v_pk_add_f32 v[254:255], v[92:93], v[184:185]
	v_cvt_pk_bf16_f32 v168, v194, v195
	v_cvt_pk_bf16_f32 v169, v254, v255
	global_store_dwordx2 v243, v[168:169], s[56:57] offset:32
	v_pk_mul_f32 v[194:195], v[194:195], v[194:195]
	v_pk_mul_f32 v[254:255], v[254:255], v[254:255]
	v_add_f32_e32 v170, v195, v194
	v_add_f32_e32 v170, v254, v170
	v_add_f32_e32 v170, v255, v170
	v_add_f32_e32 v164, v164, v170
	s_waitcnt vmcnt(24)
	v_pk_add_f32 v[194:195], v[86:87], v[186:187]
	v_pk_add_f32 v[254:255], v[88:89], v[188:189]
	v_cvt_pk_bf16_f32 v168, v194, v195
	v_cvt_pk_bf16_f32 v169, v254, v255
	global_store_dwordx2 v243, v[168:169], s[56:57] offset:64
	v_pk_mul_f32 v[194:195], v[194:195], v[194:195]
	v_pk_mul_f32 v[254:255], v[254:255], v[254:255]
	v_add_f32_e32 v170, v195, v194
	v_add_f32_e32 v170, v254, v170
	v_add_f32_e32 v170, v255, v170
	v_add_f32_e32 v164, v164, v170
	s_waitcnt vmcnt(24)
	v_pk_add_f32 v[194:195], v[82:83], v[190:191]
	v_pk_add_f32 v[254:255], v[84:85], v[192:193]
	v_cvt_pk_bf16_f32 v168, v194, v195
	v_cvt_pk_bf16_f32 v169, v254, v255
	global_store_dwordx2 v243, v[168:169], s[56:57] offset:96
	v_pk_mul_f32 v[194:195], v[194:195], v[194:195]
	v_pk_mul_f32 v[254:255], v[254:255], v[254:255]
	v_add_f32_e32 v170, v195, v194
	v_add_f32_e32 v170, v254, v170
	v_add_f32_e32 v170, v255, v170
	v_add_f32_e32 v164, v164, v170
	s_waitcnt vmcnt(24)
	v_pk_add_f32 v[194:195], v[78:79], v[226:227]
	v_pk_add_f32 v[254:255], v[80:81], v[228:229]
	v_cvt_pk_bf16_f32 v168, v194, v195
	v_cvt_pk_bf16_f32 v169, v254, v255
	global_store_dwordx2 v243, v[168:169], s[56:57] offset:128
	v_pk_mul_f32 v[194:195], v[194:195], v[194:195]
	v_pk_mul_f32 v[254:255], v[254:255], v[254:255]
	v_add_f32_e32 v170, v195, v194
	v_add_f32_e32 v170, v254, v170
	v_add_f32_e32 v170, v255, v170
	v_add_f32_e32 v164, v164, v170
	s_waitcnt vmcnt(24)
	v_pk_add_f32 v[194:195], v[74:75], v[230:231]
	v_pk_add_f32 v[254:255], v[76:77], v[232:233]
	v_cvt_pk_bf16_f32 v168, v194, v195
	v_cvt_pk_bf16_f32 v169, v254, v255
	global_store_dwordx2 v243, v[168:169], s[56:57] offset:160
	v_pk_mul_f32 v[194:195], v[194:195], v[194:195]
	v_pk_mul_f32 v[254:255], v[254:255], v[254:255]
	v_add_f32_e32 v170, v195, v194
	v_add_f32_e32 v170, v254, v170
	v_add_f32_e32 v170, v255, v170
	v_add_f32_e32 v164, v164, v170
	s_waitcnt vmcnt(24)
	v_pk_add_f32 v[194:195], v[70:71], v[234:235]
	v_pk_add_f32 v[254:255], v[72:73], v[236:237]
	v_cvt_pk_bf16_f32 v168, v194, v195
	v_cvt_pk_bf16_f32 v169, v254, v255
	global_store_dwordx2 v243, v[168:169], s[56:57] offset:192
	v_pk_mul_f32 v[194:195], v[194:195], v[194:195]
	v_pk_mul_f32 v[254:255], v[254:255], v[254:255]
	v_add_f32_e32 v170, v195, v194
	v_add_f32_e32 v170, v254, v170
	v_add_f32_e32 v170, v255, v170
	v_add_f32_e32 v164, v164, v170
	s_waitcnt vmcnt(24)
	v_pk_add_f32 v[194:195], v[66:67], v[238:239]
	v_pk_add_f32 v[254:255], v[68:69], v[240:241]
	v_cvt_pk_bf16_f32 v168, v194, v195
	v_cvt_pk_bf16_f32 v169, v254, v255
	global_store_dwordx2 v243, v[168:169], s[56:57] offset:224
	v_pk_mul_f32 v[194:195], v[194:195], v[194:195]
	v_pk_mul_f32 v[254:255], v[254:255], v[254:255]
	v_add_f32_e32 v170, v195, v194
	v_add_f32_e32 v170, v254, v170
	v_add_f32_e32 v170, v255, v170
	v_add_f32_e32 v164, v164, v170
	v_xor_b32_e32 v168, 16, v207
	v_lshlrev_b32_e32 v168, 2, v168
	ds_bpermute_b32 v169, v168, v164
	v_xor_b32_e32 v168, 32, v207
	v_lshlrev_b32_e32 v168, 2, v168
	s_waitcnt lgkmcnt(0)
	v_add_f32_e32 v164, v164, v169
	ds_bpermute_b32 v169, v168, v164
	v_add_u32_e32 v170, 16, v130
	v_lshlrev_b32_e32 v170, 2, v170
	v_and_b32_e32 v171, 63, v207
	v_cmp_gt_u32_e32 vcc, 16, v171
	s_waitcnt lgkmcnt(0)
	v_add_f32_e32 v164, v164, v169
	s_and_saveexec_b64 s[2:3], vcc
	global_atomic_add_f32 v170, v164, s[8:9]
	s_or_b64 exec, exec, s[2:3]
	v_add_u32_e32 v168, 48, v130
	v_lshlrev_b32_e32 v168, 11, v168
	v_lshl_add_u32 v243, v131, 1, v168
	v_add_u32_e32 v168, 48, v130
	v_mul_hi_i32 v169, v168, s81
	v_lshrrev_b32_e32 v170, 31, v169
	v_ashrrev_i32_e32 v169, 10, v169
	v_add_u32_e32 v169, v169, v170
	v_mad_i32_i24 v170, v169, s82, v168
	v_add_u32_e32 v171, -16, v170
	v_cmp_lt_u32_e32 vcc, s83, v171
	v_lshl_add_u32 v171, v169, 12, v171
	v_add_u32_e32 v168, 0xfffff000, v170
	v_cmp_gt_i32_e64 s[2:3], 16, v170
	s_nop 1
	v_cndmask_b32_e64 v168, v168, v170, s[2:3]
	v_lshl_add_u32 v168, v169, 7, v168
	v_cndmask_b32_e32 v168, v171, v168, vcc
	v_mov_b32_e32 v169, s60
	v_mov_b32_e32 v170, s58
	v_cndmask_b32_e32 v250, v169, v170, vcc
	v_mov_b32_e32 v169, s61
	v_mov_b32_e32 v170, s59
	v_cndmask_b32_e32 v251, v169, v170, vcc
	v_lshlrev_b32_e32 v168, 12, v168
	v_lshl_add_u32 v168, v131, 2, v168
	v_add_co_u32_e32 v250, vcc, v250, v168
	s_nop 1
	v_addc_co_u32_e32 v251, vcc, 0, v251, vcc
	global_load_dwordx4 v[178:181], v[250:251], off offset:0
	global_load_dwordx4 v[182:185], v[250:251], off offset:64
	global_load_dwordx4 v[186:189], v[250:251], off offset:128
	global_load_dwordx4 v[190:193], v[250:251], off offset:192
	global_load_dwordx4 v[226:229], v[250:251], off offset:256
	global_load_dwordx4 v[230:233], v[250:251], off offset:320
	global_load_dwordx4 v[234:237], v[250:251], off offset:384
	global_load_dwordx4 v[238:241], v[250:251], off offset:448
	s_waitcnt vmcnt(24)
; template <int MI, int NI>
; DI void resid_epilogue(const Params& p, int from_x, const f32x4 (&acc)[NI][MI], int row0, int n0, float* rowss_next, bool last, int lm, int lg) {
;     ...
;     for (int ni = 0; ni < NI; ++ni) {
;       const int n = n0 + ni * 16 + lg * 4;
;       float4 h;
;       if (from_x >= 2) {
;         const u32x2 pk = *(const u32x2*)(hbr + n);
;         h = make_float4(__uint_as_float(pk[0] << 16), __uint_as_float(pk[0] & 0xffff0000u), __uint_as_float(pk[1] << 16), __uint_as_float(pk[1] & 0xffff0000u));
;       } else h = *(const float4*)(hr + n);
;       h.x += acc[ni][mi][0]; h.y += acc[ni][mi][1]; h.z += acc[ni][mi][2]; h.w += acc[ni][mi][3];
;       if (last) *(float4*)(hw + n) = h;
;       if (!last) {
;         u32x2 pk = {pack2bf(h.x, h.y), pack2bf(h.z, h.w)};
;         *(u32x2*)(hbr + n) = pk;
;         ss += h.x * h.x + h.y * h.y + h.z * h.z + h.w * h.w;
;       }
;     }
;     if (!last) {
;       ss += __shfl_xor(ss, 16);
;       ss += __shfl_xor(ss, 32);
;       if (lg == 0) atomicAdd(rowss_next + m, ss);
	v_pk_add_f32 v[194:195], v[62:63], v[132:133]
	v_pk_add_f32 v[254:255], v[64:65], v[134:135]
	v_cvt_pk_bf16_f32 v168, v194, v195
	v_cvt_pk_bf16_f32 v169, v254, v255
	global_store_dwordx2 v242, v[168:169], s[56:57] offset:0
	v_pk_mul_f32 v[194:195], v[194:195], v[194:195]
	v_pk_mul_f32 v[254:255], v[254:255], v[254:255]
	v_add_f32_e32 v170, v195, v194
	v_add_f32_e32 v170, v254, v170
	v_add_f32_e32 v170, v255, v170
	v_mov_b32_e32 v164, v170
	s_waitcnt vmcnt(24)
	v_pk_add_f32 v[194:195], v[58:59], v[136:137]
	v_pk_add_f32 v[254:255], v[60:61], v[138:139]
	v_cvt_pk_bf16_f32 v168, v194, v195
	v_cvt_pk_bf16_f32 v169, v254, v255
	global_store_dwordx2 v242, v[168:169], s[56:57] offset:32
	v_pk_mul_f32 v[194:195], v[194:195], v[194:195]
	v_pk_mul_f32 v[254:255], v[254:255], v[254:255]
	v_add_f32_e32 v170, v195, v194
	v_add_f32_e32 v170, v254, v170
	v_add_f32_e32 v170, v255, v170
	v_add_f32_e32 v164, v164, v170
	s_waitcnt vmcnt(24)
	v_pk_add_f32 v[194:195], v[54:55], v[140:141]
	v_pk_add_f32 v[254:255], v[56:57], v[142:143]
	v_cvt_pk_bf16_f32 v168, v194, v195
	v_cvt_pk_bf16_f32 v169, v254, v255
	global_store_dwordx2 v242, v[168:169], s[56:57] offset:64
	v_pk_mul_f32 v[194:195], v[194:195], v[194:195]
	v_pk_mul_f32 v[254:255], v[254:255], v[254:255]
	v_add_f32_e32 v170, v195, v194
	v_add_f32_e32 v170, v254, v170
	v_add_f32_e32 v170, v255, v170
	v_add_f32_e32 v164, v164, v170
	s_waitcnt vmcnt(24)
	v_pk_add_f32 v[194:195], v[50:51], v[144:145]
	v_pk_add_f32 v[254:255], v[52:53], v[146:147]
	v_cvt_pk_bf16_f32 v168, v194, v195
	v_cvt_pk_bf16_f32 v169, v254, v255
	global_store_dwordx2 v242, v[168:169], s[56:57] offset:96
	v_pk_mul_f32 v[194:195], v[194:195], v[194:195]
	v_pk_mul_f32 v[254:255], v[254:255], v[254:255]
	v_add_f32_e32 v170, v195, v194
	v_add_f32_e32 v170, v254, v170
	v_add_f32_e32 v170, v255, v170
	v_add_f32_e32 v164, v164, v170
	s_waitcnt vmcnt(24)
	v_pk_add_f32 v[194:195], v[46:47], v[148:149]
	v_pk_add_f32 v[254:255], v[48:49], v[150:151]
	v_cvt_pk_bf16_f32 v168, v194, v195
	v_cvt_pk_bf16_f32 v169, v254, v255
	global_store_dwordx2 v242, v[168:169], s[56:57] offset:128
	v_pk_mul_f32 v[194:195], v[194:195], v[194:195]
	v_pk_mul_f32 v[254:255], v[254:255], v[254:255]
	v_add_f32_e32 v170, v195, v194
	v_add_f32_e32 v170, v254, v170
	v_add_f32_e32 v170, v255, v170
	v_add_f32_e32 v164, v164, v170
	s_waitcnt vmcnt(24)
	v_pk_add_f32 v[194:195], v[42:43], v[152:153]
	v_pk_add_f32 v[254:255], v[44:45], v[154:155]
	v_cvt_pk_bf16_f32 v168, v194, v195
	v_cvt_pk_bf16_f32 v169, v254, v255
	global_store_dwordx2 v242, v[168:169], s[56:57] offset:160
	v_pk_mul_f32 v[194:195], v[194:195], v[194:195]
	v_pk_mul_f32 v[254:255], v[254:255], v[254:255]
	v_add_f32_e32 v170, v195, v194
	v_add_f32_e32 v170, v254, v170
	v_add_f32_e32 v170, v255, v170
	v_add_f32_e32 v164, v164, v170
	s_waitcnt vmcnt(24)
	v_pk_add_f32 v[194:195], v[38:39], v[156:157]
	v_pk_add_f32 v[254:255], v[40:41], v[158:159]
	v_cvt_pk_bf16_f32 v168, v194, v195
	v_cvt_pk_bf16_f32 v169, v254, v255
	global_store_dwordx2 v242, v[168:169], s[56:57] offset:192
	v_pk_mul_f32 v[194:195], v[194:195], v[194:195]
	v_pk_mul_f32 v[254:255], v[254:255], v[254:255]
	v_add_f32_e32 v170, v195, v194
	v_add_f32_e32 v170, v254, v170
	v_add_f32_e32 v170, v255, v170
	v_add_f32_e32 v164, v164, v170
	s_waitcnt vmcnt(24)
	v_pk_add_f32 v[194:195], v[34:35], v[160:161]
	v_pk_add_f32 v[254:255], v[36:37], v[162:163]
	v_cvt_pk_bf16_f32 v168, v194, v195
	v_cvt_pk_bf16_f32 v169, v254, v255
	global_store_dwordx2 v242, v[168:169], s[56:57] offset:224
	v_pk_mul_f32 v[194:195], v[194:195], v[194:195]
	v_pk_mul_f32 v[254:255], v[254:255], v[254:255]
	v_add_f32_e32 v170, v195, v194
	v_add_f32_e32 v170, v254, v170
	v_add_f32_e32 v170, v255, v170
	v_add_f32_e32 v164, v164, v170
	v_xor_b32_e32 v168, 16, v207
	v_lshlrev_b32_e32 v168, 2, v168
	ds_bpermute_b32 v169, v168, v164
	v_xor_b32_e32 v168, 32, v207
	v_lshlrev_b32_e32 v168, 2, v168
	s_waitcnt lgkmcnt(0)
	v_add_f32_e32 v164, v164, v169
	ds_bpermute_b32 v169, v168, v164
	v_add_u32_e32 v170, 32, v130
	v_lshlrev_b32_e32 v170, 2, v170
	v_and_b32_e32 v171, 63, v207
	v_cmp_gt_u32_e32 vcc, 16, v171
	s_waitcnt lgkmcnt(0)
	v_add_f32_e32 v164, v164, v169
	s_and_saveexec_b64 s[2:3], vcc
	global_atomic_add_f32 v170, v164, s[8:9]
	s_or_b64 exec, exec, s[2:3]
	s_waitcnt vmcnt(16)
; template <int MI, int NI>
; DI void resid_epilogue(const Params& p, int from_x, const f32x4 (&acc)[NI][MI], int row0, int n0, float* rowss_next, bool last, int lm, int lg) {
;     ...
;     for (int ni = 0; ni < NI; ++ni) {
;       const int n = n0 + ni * 16 + lg * 4;
;       float4 h;
;       if (from_x >= 2) {
;         const u32x2 pk = *(const u32x2*)(hbr + n);
;         h = make_float4(__uint_as_float(pk[0] << 16), __uint_as_float(pk[0] & 0xffff0000u), __uint_as_float(pk[1] << 16), __uint_as_float(pk[1] & 0xffff0000u));
;       } else h = *(const float4*)(hr + n);
;       h.x += acc[ni][mi][0]; h.y += acc[ni][mi][1]; h.z += acc[ni][mi][2]; h.w += acc[ni][mi][3];
;       if (last) *(float4*)(hw + n) = h;
;       if (!last) {
;         u32x2 pk = {pack2bf(h.x, h.y), pack2bf(h.z, h.w)};
;         *(u32x2*)(hbr + n) = pk;
;         ss += h.x * h.x + h.y * h.y + h.z * h.z + h.w * h.w;
;       }
;     }
;     if (!last) {
;       ss += __shfl_xor(ss, 16);
;       ss += __shfl_xor(ss, 32);
;       if (lg == 0) atomicAdd(rowss_next + m, ss);
;     }
;   }
; DI void phase_resid(const Params& p, int from_x, const u16* A, int K, const u16* W, float* rowss_next, bool last,
;                     unsigned char* smem) {
;     ...
;   for (int it = vblock(); it < nfull; it += gridDim.x) {
;     const int g = it / (4 * NT), rem = it - g * (4 * NT), nt = rem >> 2, mt = g * 4 + (rem & 3);
;     f32x4 acc[8][4];
;     zero_acc<4, 8>(acc);
;     gemm_kloop<4, 8>(A + (size_t)(mt * 256) * K, K, W + (size_t)(nt * 256) * K, K, K, acc, smem);
;     resid_epilogue<4, 8>(p, from_x, acc, mt * 256 + wm * 64, nt * 256 + wn * 128, rowss_next, last, lm, lg);
;   }
	v_pk_add_f32 v[194:195], v[30:31], v[178:179]
	v_pk_add_f32 v[254:255], v[32:33], v[180:181]
	v_cvt_pk_bf16_f32 v168, v194, v195
	v_cvt_pk_bf16_f32 v169, v254, v255
	global_store_dwordx2 v243, v[168:169], s[56:57] offset:0
	v_pk_mul_f32 v[194:195], v[194:195], v[194:195]
	v_pk_mul_f32 v[254:255], v[254:255], v[254:255]
	v_add_f32_e32 v170, v195, v194
	v_add_f32_e32 v170, v254, v170
	v_add_f32_e32 v170, v255, v170
	v_mov_b32_e32 v164, v170
	s_waitcnt vmcnt(16)
	v_pk_add_f32 v[194:195], v[26:27], v[182:183]
	v_pk_add_f32 v[254:255], v[28:29], v[184:185]
	v_cvt_pk_bf16_f32 v168, v194, v195
	v_cvt_pk_bf16_f32 v169, v254, v255
	global_store_dwordx2 v243, v[168:169], s[56:57] offset:32
	v_pk_mul_f32 v[194:195], v[194:195], v[194:195]
	v_pk_mul_f32 v[254:255], v[254:255], v[254:255]
	v_add_f32_e32 v170, v195, v194
	v_add_f32_e32 v170, v254, v170
	v_add_f32_e32 v170, v255, v170
	v_add_f32_e32 v164, v164, v170
	s_waitcnt vmcnt(16)
	v_pk_add_f32 v[194:195], v[22:23], v[186:187]
	v_pk_add_f32 v[254:255], v[24:25], v[188:189]
	v_cvt_pk_bf16_f32 v168, v194, v195
	v_cvt_pk_bf16_f32 v169, v254, v255
	global_store_dwordx2 v243, v[168:169], s[56:57] offset:64
	v_pk_mul_f32 v[194:195], v[194:195], v[194:195]
	v_pk_mul_f32 v[254:255], v[254:255], v[254:255]
	v_add_f32_e32 v170, v195, v194
	v_add_f32_e32 v170, v254, v170
	v_add_f32_e32 v170, v255, v170
	v_add_f32_e32 v164, v164, v170
	s_waitcnt vmcnt(16)
	v_pk_add_f32 v[194:195], v[18:19], v[190:191]
	v_pk_add_f32 v[254:255], v[20:21], v[192:193]
	v_cvt_pk_bf16_f32 v168, v194, v195
	v_cvt_pk_bf16_f32 v169, v254, v255
	global_store_dwordx2 v243, v[168:169], s[56:57] offset:96
	v_pk_mul_f32 v[194:195], v[194:195], v[194:195]
	v_pk_mul_f32 v[254:255], v[254:255], v[254:255]
	v_add_f32_e32 v170, v195, v194
	v_add_f32_e32 v170, v254, v170
	v_add_f32_e32 v170, v255, v170
	v_add_f32_e32 v164, v164, v170
	s_waitcnt vmcnt(16)
	v_pk_add_f32 v[194:195], v[14:15], v[226:227]
	v_pk_add_f32 v[254:255], v[16:17], v[228:229]
	v_cvt_pk_bf16_f32 v168, v194, v195
	v_cvt_pk_bf16_f32 v169, v254, v255
	global_store_dwordx2 v243, v[168:169], s[56:57] offset:128
	v_pk_mul_f32 v[194:195], v[194:195], v[194:195]
	v_pk_mul_f32 v[254:255], v[254:255], v[254:255]
	v_add_f32_e32 v170, v195, v194
	v_add_f32_e32 v170, v254, v170
	v_add_f32_e32 v170, v255, v170
	v_add_f32_e32 v164, v164, v170
	s_waitcnt vmcnt(16)
	v_pk_add_f32 v[194:195], v[10:11], v[230:231]
	v_pk_add_f32 v[254:255], v[12:13], v[232:233]
	v_cvt_pk_bf16_f32 v168, v194, v195
	v_cvt_pk_bf16_f32 v169, v254, v255
	global_store_dwordx2 v243, v[168:169], s[56:57] offset:160
	v_pk_mul_f32 v[194:195], v[194:195], v[194:195]
	v_pk_mul_f32 v[254:255], v[254:255], v[254:255]
	v_add_f32_e32 v170, v195, v194
	v_add_f32_e32 v170, v254, v170
	v_add_f32_e32 v170, v255, v170
	v_add_f32_e32 v164, v164, v170
	s_waitcnt vmcnt(16)
	v_pk_add_f32 v[194:195], v[6:7], v[234:235]
	v_pk_add_f32 v[254:255], v[8:9], v[236:237]
	v_cvt_pk_bf16_f32 v168, v194, v195
	v_cvt_pk_bf16_f32 v169, v254, v255
	global_store_dwordx2 v243, v[168:169], s[56:57] offset:192
	v_pk_mul_f32 v[194:195], v[194:195], v[194:195]
	v_pk_mul_f32 v[254:255], v[254:255], v[254:255]
	v_add_f32_e32 v170, v195, v194
	v_add_f32_e32 v170, v254, v170
	v_add_f32_e32 v170, v255, v170
	v_add_f32_e32 v164, v164, v170
	s_waitcnt vmcnt(16)
	v_pk_add_f32 v[194:195], v[2:3], v[238:239]
	v_pk_add_f32 v[254:255], v[4:5], v[240:241]
	v_cvt_pk_bf16_f32 v168, v194, v195
	v_cvt_pk_bf16_f32 v169, v254, v255
	global_store_dwordx2 v243, v[168:169], s[56:57] offset:224
	v_pk_mul_f32 v[194:195], v[194:195], v[194:195]
	v_pk_mul_f32 v[254:255], v[254:255], v[254:255]
	v_add_f32_e32 v170, v195, v194
	v_add_f32_e32 v170, v254, v170
	v_add_f32_e32 v170, v255, v170
	v_add_f32_e32 v164, v164, v170
	v_xor_b32_e32 v168, 16, v207
	v_lshlrev_b32_e32 v168, 2, v168
	ds_bpermute_b32 v169, v168, v164
	v_xor_b32_e32 v168, 32, v207
	v_lshlrev_b32_e32 v168, 2, v168
	s_waitcnt lgkmcnt(0)
	v_add_f32_e32 v164, v164, v169
	ds_bpermute_b32 v169, v168, v164
	v_add_u32_e32 v170, 48, v130
	v_lshlrev_b32_e32 v170, 2, v170
	v_and_b32_e32 v171, 63, v207
	v_cmp_gt_u32_e32 vcc, 16, v171
	s_waitcnt lgkmcnt(0)
	v_add_f32_e32 v164, v164, v169
	s_and_saveexec_b64 s[2:3], vcc
	global_atomic_add_f32 v170, v164, s[8:9]
	s_or_b64 exec, exec, s[2:3]
	s_branch .Lresid_next_outproj

; DI f32x4 mfma16(bf16x8 a, bf16x8 b, f32x4 c) { return __builtin_amdgcn_mfma_f32_16x16x32_bf16(a, b, c, 0, 0, 0); }
; template <int MI, int NI>
; DI void gemm_kloop(const u16* Au, int lda, const u16* Bu, int ldb, int K, f32x4 (&acc)[NI][MI], unsigned char* smem) {
;     ...
;   for (int kt = 0; kt < nk; ++kt) {
;     __syncthreads();
;     if (kt + 1 < nk) {
;       SWRITE((kt + 1) & 1);
;       if (kt + 2 < nk) GLOAD((kt + 2) << 6);
;     }
;     {
;       const unsigned char* sa = smem + (kt & 1) * 65536;
;       const unsigned char* sb = sa + 32768;
; #pragma unroll
;       for (int ks = 0; ks < 2; ++ks) {
;         const int fo = ks ? fro1 : fro0;
;         bf16x8 af[MI];
; #pragma unroll
;         for (int i = 0; i < MI; ++i) af[i] = *(const bf16x8*)(sa + (wm * 16 * MI + i * 16) * 128 + fo);
; #pragma unroll
;         for (int nh = 0; nh < NI; nh += 4) {
;           bf16x8 wf[4];
; #pragma unroll
;           for (int i = 0; i < 4; ++i) wf[i] = *(const bf16x8*)(sb + (wn * 16 * NI + (nh + i) * 16) * 128 + fo);
; #pragma unroll
;           for (int ni = 0; ni < 4; ++ni)
; #pragma unroll
;             for (int mi = 0; mi < MI; ++mi) acc[nh + ni][mi] = mfma16(wf[ni], af[mi], acc[nh + ni][mi]);
;         }
.Lk_down:
	s_waitcnt vmcnt(0) lgkmcnt(0)
	s_barrier
	ds_read_b128 v[162:165], v227 offset:32768
	ds_read_b128 v[122:125], v183
	ds_read_b128 v[126:129], v183 offset:2048
	ds_read_b128 v[130:133], v183 offset:4096
	ds_read_b128 v[134:137], v183 offset:6144
	ds_read_b128 v[184:187], v227 offset:34816
	ds_read_b128 v[188:191], v227 offset:36864
	s_and_b32 s92, s95, 1
	s_xor_b32 s92, s92, 1
	s_lshl_b32 s92, s92, 16
	s_waitcnt lgkmcnt(5)
	v_mfma_f32_16x16x32_bf16 v[150:153], v[162:165], v[122:125], v[150:153]
	ds_read_b128 v[192:195], v227 offset:38912
	s_waitcnt lgkmcnt(5)
	v_mfma_f32_16x16x32_bf16 v[118:121], v[162:165], v[126:129], v[118:121]
	s_waitcnt lgkmcnt(4)
	v_mfma_f32_16x16x32_bf16 v[114:117], v[162:165], v[130:133], v[114:117]
	s_add_u32 m0, s92, s94
	s_nop 0
	global_load_lds_dwordx4 v255, s[88:89]
	s_waitcnt lgkmcnt(3)
	v_mfma_f32_16x16x32_bf16 v[110:113], v[162:165], v[134:137], v[110:113]
	s_waitcnt lgkmcnt(2)
	v_mfma_f32_16x16x32_bf16 v[106:109], v[184:187], v[122:125], v[106:109]
	ds_read_b128 v[162:165], v227 offset:40960
	v_mfma_f32_16x16x32_bf16 v[102:105], v[184:187], v[126:129], v[102:105]
	ds_read_b128 v[138:141], v226
	v_mfma_f32_16x16x32_bf16 v[98:101], v[184:187], v[130:133], v[98:101]
	s_add_u32 m0, m0, 0x2000
	s_add_u32 s92, s88, 0x58000
	s_addc_u32 s93, s89, 0
	global_load_lds_dwordx4 v255, s[92:93]
	v_mfma_f32_16x16x32_bf16 v[94:97], v[184:187], v[134:137], v[94:97]
	s_waitcnt lgkmcnt(3)
	v_mfma_f32_16x16x32_bf16 v[90:93], v[188:191], v[122:125], v[90:93]
	ds_read_b128 v[184:187], v227 offset:43008
	v_mfma_f32_16x16x32_bf16 v[86:89], v[188:191], v[126:129], v[86:89]
	ds_read_b128 v[142:145], v226 offset:2048
	v_mfma_f32_16x16x32_bf16 v[82:85], v[188:191], v[130:133], v[82:85]
	s_add_u32 m0, m0, 0x2000
	s_add_u32 s92, s88, 0xb0000
	s_addc_u32 s93, s89, 0
	global_load_lds_dwordx4 v255, s[92:93]
	v_mfma_f32_16x16x32_bf16 v[70:73], v[188:191], v[134:137], v[70:73]
	s_waitcnt lgkmcnt(4)
	v_mfma_f32_16x16x32_bf16 v[66:69], v[192:195], v[122:125], v[66:69]
	ds_read_b128 v[188:191], v227 offset:45056
	v_mfma_f32_16x16x32_bf16 v[54:57], v[192:195], v[126:129], v[54:57]
	ds_read_b128 v[146:149], v226 offset:4096
	v_mfma_f32_16x16x32_bf16 v[50:53], v[192:195], v[130:133], v[50:53]
	s_add_u32 m0, m0, 0x2000
	s_add_u32 s92, s88, 0x108000
	s_addc_u32 s93, s89, 0
	global_load_lds_dwordx4 v255, s[92:93]
	v_mfma_f32_16x16x32_bf16 v[46:49], v[192:195], v[134:137], v[46:49]
	s_waitcnt lgkmcnt(5)
	v_mfma_f32_16x16x32_bf16 v[42:45], v[162:165], v[122:125], v[42:45]
	ds_read_b128 v[192:195], v227 offset:47104
	v_mfma_f32_16x16x32_bf16 v[34:37], v[162:165], v[126:129], v[34:37]
	ds_read_b128 v[154:157], v226 offset:6144
	v_mfma_f32_16x16x32_bf16 v[30:33], v[162:165], v[130:133], v[30:33]
	s_add_u32 m0, m0, 0x2000
	s_nop 0
	global_load_lds_dwordx4 v255, s[90:91]
	v_mfma_f32_16x16x32_bf16 v[26:29], v[162:165], v[134:137], v[26:29]
	s_waitcnt lgkmcnt(5)
	v_mfma_f32_16x16x32_bf16 v[22:25], v[184:187], v[122:125], v[22:25]
	ds_read_b128 v[162:165], v254 offset:32768
	v_mfma_f32_16x16x32_bf16 v[18:21], v[184:187], v[126:129], v[18:21]
	v_mfma_f32_16x16x32_bf16 v[14:17], v[184:187], v[130:133], v[14:17]
	s_add_u32 m0, m0, 0x2000
	s_add_u32 s92, s90, 0x58000
	s_addc_u32 s93, s91, 0
	global_load_lds_dwordx4 v255, s[92:93]
	v_mfma_f32_16x16x32_bf16 v[10:13], v[184:187], v[134:137], v[10:13]
	s_waitcnt lgkmcnt(4)
	v_mfma_f32_16x16x32_bf16 v[6:9], v[188:191], v[122:125], v[6:9]
	ds_read_b128 v[184:187], v254 offset:34816
	v_mfma_f32_16x16x32_bf16 v[2:5], v[188:191], v[126:129], v[2:5]
	v_mfma_f32_16x16x32_bf16 v[38:41], v[188:191], v[130:133], v[38:41]
	s_add_u32 m0, m0, 0x2000
	s_add_u32 s92, s90, 0xb0000
	s_addc_u32 s93, s91, 0
	global_load_lds_dwordx4 v255, s[92:93]
	v_mfma_f32_16x16x32_bf16 v[62:65], v[188:191], v[134:137], v[62:65]
	s_waitcnt lgkmcnt(3)
	v_mfma_f32_16x16x32_bf16 v[78:81], v[192:195], v[122:125], v[78:81]
	ds_read_b128 v[188:191], v254 offset:36864
	v_mfma_f32_16x16x32_bf16 v[74:77], v[192:195], v[126:129], v[74:77]
	v_mfma_f32_16x16x32_bf16 v[58:61], v[192:195], v[130:133], v[58:61]
	s_add_u32 m0, m0, 0x2000
	s_add_u32 s92, s90, 0x108000
	s_addc_u32 s93, s91, 0
	global_load_lds_dwordx4 v255, s[92:93]
	v_mfma_f32_16x16x32_bf16 v[158:161], v[192:195], v[134:137], v[158:161]
	s_waitcnt lgkmcnt(2)
	v_mfma_f32_16x16x32_bf16 v[150:153], v[162:165], v[138:141], v[150:153]
	ds_read_b128 v[192:195], v254 offset:38912
	v_mfma_f32_16x16x32_bf16 v[118:121], v[162:165], v[142:145], v[118:121]
	v_mfma_f32_16x16x32_bf16 v[114:117], v[162:165], v[146:149], v[114:117]
	v_mfma_f32_16x16x32_bf16 v[110:113], v[162:165], v[154:157], v[110:113]
	s_waitcnt lgkmcnt(2)
	v_mfma_f32_16x16x32_bf16 v[106:109], v[184:187], v[138:141], v[106:109]
	ds_read_b128 v[162:165], v254 offset:40960
	v_mfma_f32_16x16x32_bf16 v[102:105], v[184:187], v[142:145], v[102:105]
	v_mfma_f32_16x16x32_bf16 v[98:101], v[184:187], v[146:149], v[98:101]
	v_mfma_f32_16x16x32_bf16 v[94:97], v[184:187], v[154:157], v[94:97]
	s_waitcnt lgkmcnt(2)
	v_mfma_f32_16x16x32_bf16 v[90:93], v[188:191], v[138:141], v[90:93]
	ds_read_b128 v[184:187], v254 offset:43008
	v_mfma_f32_16x16x32_bf16 v[86:89], v[188:191], v[142:145], v[86:89]
	v_mfma_f32_16x16x32_bf16 v[82:85], v[188:191], v[146:149], v[82:85]
	v_mfma_f32_16x16x32_bf16 v[70:73], v[188:191], v[154:157], v[70:73]
	s_waitcnt lgkmcnt(2)
	v_mfma_f32_16x16x32_bf16 v[66:69], v[192:195], v[138:141], v[66:69]
	ds_read_b128 v[188:191], v254 offset:45056
	v_mfma_f32_16x16x32_bf16 v[54:57], v[192:195], v[142:145], v[54:57]
	v_mfma_f32_16x16x32_bf16 v[50:53], v[192:195], v[146:149], v[50:53]
	v_mfma_f32_16x16x32_bf16 v[46:49], v[192:195], v[154:157], v[46:49]
	s_waitcnt lgkmcnt(2)
; DI f32x4 mfma16(bf16x8 a, bf16x8 b, f32x4 c) { return __builtin_amdgcn_mfma_f32_16x16x32_bf16(a, b, c, 0, 0, 0); }
; template <int MI, int NI>
; DI void gemm_kloop(const u16* Au, int lda, const u16* Bu, int ldb, int K, f32x4 (&acc)[NI][MI], unsigned char* smem) {
;     ...
;   for (int kt = 0; kt < nk; ++kt) {
;     __syncthreads();
;     if (kt + 1 < nk) {
;       SWRITE((kt + 1) & 1);
;       if (kt + 2 < nk) GLOAD((kt + 2) << 6);
;     }
;     {
;       const unsigned char* sa = smem + (kt & 1) * 65536;
;       const unsigned char* sb = sa + 32768;
; #pragma unroll
;       for (int ks = 0; ks < 2; ++ks) {
;         const int fo = ks ? fro1 : fro0;
;         bf16x8 af[MI];
; #pragma unroll
;         for (int i = 0; i < MI; ++i) af[i] = *(const bf16x8*)(sa + (wm * 16 * MI + i * 16) * 128 + fo);
; #pragma unroll
;         for (int nh = 0; nh < NI; nh += 4) {
;           bf16x8 wf[4];
; #pragma unroll
;           for (int i = 0; i < 4; ++i) wf[i] = *(const bf16x8*)(sb + (wn * 16 * NI + (nh + i) * 16) * 128 + fo);
; #pragma unroll
;           for (int ni = 0; ni < 4; ++ni)
; #pragma unroll
;             for (int mi = 0; mi < MI; ++mi) acc[nh + ni][mi] = mfma16(wf[ni], af[mi], acc[nh + ni][mi]);
;         }
	v_mfma_f32_16x16x32_bf16 v[42:45], v[162:165], v[138:141], v[42:45]
	ds_read_b128 v[192:195], v254 offset:47104
	v_mfma_f32_16x16x32_bf16 v[34:37], v[162:165], v[142:145], v[34:37]
	v_mfma_f32_16x16x32_bf16 v[30:33], v[162:165], v[146:149], v[30:33]
	v_mfma_f32_16x16x32_bf16 v[26:29], v[162:165], v[154:157], v[26:29]
	s_waitcnt lgkmcnt(2)
	v_mfma_f32_16x16x32_bf16 v[22:25], v[184:187], v[138:141], v[22:25]
	v_mfma_f32_16x16x32_bf16 v[18:21], v[184:187], v[142:145], v[18:21]
	v_mfma_f32_16x16x32_bf16 v[14:17], v[184:187], v[146:149], v[14:17]
	v_mfma_f32_16x16x32_bf16 v[10:13], v[184:187], v[154:157], v[10:13]
	s_waitcnt lgkmcnt(1)
	v_mfma_f32_16x16x32_bf16 v[6:9], v[188:191], v[138:141], v[6:9]
	v_mfma_f32_16x16x32_bf16 v[2:5], v[188:191], v[142:145], v[2:5]
	v_mfma_f32_16x16x32_bf16 v[38:41], v[188:191], v[146:149], v[38:41]
	v_mfma_f32_16x16x32_bf16 v[62:65], v[188:191], v[154:157], v[62:65]
	s_waitcnt lgkmcnt(0)
	v_mfma_f32_16x16x32_bf16 v[78:81], v[192:195], v[138:141], v[78:81]
	v_mfma_f32_16x16x32_bf16 v[74:77], v[192:195], v[142:145], v[74:77]
	v_mfma_f32_16x16x32_bf16 v[58:61], v[192:195], v[146:149], v[58:61]
	v_mfma_f32_16x16x32_bf16 v[158:161], v[192:195], v[154:157], v[158:161]
	v_xor_b32_e32 v183, 0x10000, v183
	v_xor_b32_e32 v226, 0x10000, v226
	v_xor_b32_e32 v227, 0x10000, v227
	v_xor_b32_e32 v254, 0x10000, v254
	s_add_u32 s88, s88, 0x80
	s_addc_u32 s89, s89, 0
	s_add_u32 s90, s90, 0x80
	s_addc_u32 s91, s91, 0
	s_add_u32 s95, s95, 1
	s_cmp_lg_u32 s95, 42
	s_cbranch_scc1 .Lk_down
	s_waitcnt vmcnt(0)
	s_barrier
	s_add_u32 m0, s94, 0x10000
	s_nop 0
	global_load_lds_dwordx4 v255, s[88:89]
	s_add_u32 m0, m0, 0x2000
	s_add_u32 s92, s88, 0x58000
	s_addc_u32 s93, s89, 0
	global_load_lds_dwordx4 v255, s[92:93]
	s_add_u32 m0, m0, 0x2000
	s_add_u32 s92, s88, 0xb0000
	s_addc_u32 s93, s89, 0
	global_load_lds_dwordx4 v255, s[92:93]
	s_add_u32 m0, m0, 0x2000
	s_add_u32 s92, s88, 0x108000
	s_addc_u32 s93, s89, 0
	global_load_lds_dwordx4 v255, s[92:93]
	s_add_u32 m0, m0, 0x2000
	s_nop 0
	global_load_lds_dwordx4 v255, s[90:91]
	s_add_u32 m0, m0, 0x2000
	s_add_u32 s92, s90, 0x58000
	s_addc_u32 s93, s91, 0
	global_load_lds_dwordx4 v255, s[92:93]
	s_add_u32 m0, m0, 0x2000
	s_add_u32 s92, s90, 0xb0000
	s_addc_u32 s93, s91, 0
	global_load_lds_dwordx4 v255, s[92:93]
	s_add_u32 m0, m0, 0x2000
	s_add_u32 s92, s90, 0x108000
	s_addc_u32 s93, s91, 0
	global_load_lds_dwordx4 v255, s[92:93]
	v_add_u32_e32 v154, v181, v180
	ds_read_b128 v[122:125], v154 offset:32768
	v_add_u32_e32 v146, v179, v180
	ds_read_b128 v[126:129], v146
	ds_read_b128 v[130:133], v146 offset:2048
	ds_read_b128 v[134:137], v154 offset:34816
	ds_read_b128 v[142:145], v146 offset:4096
	ds_read_b128 v[146:149], v146 offset:6144
	s_waitcnt lgkmcnt(4)
	v_mfma_f32_16x16x32_bf16 v[138:141], v[122:125], v[126:129], v[150:153]
	s_nop 2
	v_add_u32_e32 v150, v179, v178
	v_or_b32_e32 v225, 0x18000, v181
	v_add_u32_e32 v192, v225, v180
	s_waitcnt lgkmcnt(3)
	v_mfma_f32_16x16x32_bf16 v[118:121], v[122:125], v[130:133], v[118:121]
	v_add_u32_e32 v179, 0x10000, v179
	v_add_u32_e32 v225, v225, v178
	s_waitcnt lgkmcnt(1)
	v_mfma_f32_16x16x32_bf16 v[114:117], v[122:125], v[142:145], v[114:117]
	s_waitcnt lgkmcnt(0)
	v_mfma_f32_16x16x32_bf16 v[110:113], v[122:125], v[146:149], v[110:113]
	v_mfma_f32_16x16x32_bf16 v[106:109], v[134:137], v[126:129], v[106:109]
	v_mfma_f32_16x16x32_bf16 v[102:105], v[134:137], v[130:133], v[102:105]
	v_mfma_f32_16x16x32_bf16 v[98:101], v[134:137], v[142:145], v[98:101]
	v_mfma_f32_16x16x32_bf16 v[94:97], v[134:137], v[146:149], v[94:97]
	ds_read_b128 v[122:125], v154 offset:36864
	ds_read_b128 v[134:137], v154 offset:38912
	s_waitcnt lgkmcnt(1)
	v_mfma_f32_16x16x32_bf16 v[90:93], v[122:125], v[126:129], v[90:93]
	v_mfma_f32_16x16x32_bf16 v[86:89], v[122:125], v[130:133], v[86:89]
	v_mfma_f32_16x16x32_bf16 v[82:85], v[122:125], v[142:145], v[82:85]
	v_mfma_f32_16x16x32_bf16 v[70:73], v[122:125], v[146:149], v[70:73]
	s_waitcnt lgkmcnt(0)
	v_mfma_f32_16x16x32_bf16 v[66:69], v[134:137], v[126:129], v[66:69]
	v_mfma_f32_16x16x32_bf16 v[54:57], v[134:137], v[130:133], v[54:57]
	v_mfma_f32_16x16x32_bf16 v[50:53], v[134:137], v[142:145], v[50:53]
	v_mfma_f32_16x16x32_bf16 v[46:49], v[134:137], v[146:149], v[46:49]
	ds_read_b128 v[122:125], v154 offset:40960
	ds_read_b128 v[134:137], v154 offset:43008
	s_waitcnt lgkmcnt(1)
	v_mfma_f32_16x16x32_bf16 v[42:45], v[122:125], v[126:129], v[42:45]
	v_mfma_f32_16x16x32_bf16 v[34:37], v[122:125], v[130:133], v[34:37]
	v_mfma_f32_16x16x32_bf16 v[30:33], v[122:125], v[142:145], v[30:33]
	v_mfma_f32_16x16x32_bf16 v[26:29], v[122:125], v[146:149], v[26:29]
	s_waitcnt lgkmcnt(0)
	v_mfma_f32_16x16x32_bf16 v[22:25], v[134:137], v[126:129], v[22:25]
	v_mfma_f32_16x16x32_bf16 v[18:21], v[134:137], v[130:133], v[18:21]
	v_mfma_f32_16x16x32_bf16 v[14:17], v[134:137], v[142:145], v[14:17]
	v_mfma_f32_16x16x32_bf16 v[10:13], v[134:137], v[146:149], v[10:13]
	ds_read_b128 v[122:125], v154 offset:45056
	ds_read_b128 v[134:137], v154 offset:47104
	v_add_u32_e32 v154, v181, v178
	s_waitcnt lgkmcnt(1)
	v_mfma_f32_16x16x32_bf16 v[6:9], v[122:125], v[126:129], v[6:9]
	v_mfma_f32_16x16x32_bf16 v[2:5], v[122:125], v[130:133], v[2:5]
	v_mfma_f32_16x16x32_bf16 v[38:41], v[122:125], v[142:145], v[38:41]
	v_mfma_f32_16x16x32_bf16 v[62:65], v[122:125], v[146:149], v[62:65]
	ds_read_b128 v[122:125], v154 offset:32768
	s_waitcnt lgkmcnt(1)
; DI f32x4 mfma16(bf16x8 a, bf16x8 b, f32x4 c) { return __builtin_amdgcn_mfma_f32_16x16x32_bf16(a, b, c, 0, 0, 0); }
; template <int MI, int NI>
; DI void gemm_kloop(const u16* Au, int lda, const u16* Bu, int ldb, int K, f32x4 (&acc)[NI][MI], unsigned char* smem) {
;     ...
;     {
;       const unsigned char* sa = smem + (kt & 1) * 65536;
;       const unsigned char* sb = sa + 32768;
; #pragma unroll
;       for (int ks = 0; ks < 2; ++ks) {
;         const int fo = ks ? fro1 : fro0;
;         bf16x8 af[MI];
; #pragma unroll
;         for (int i = 0; i < MI; ++i) af[i] = *(const bf16x8*)(sa + (wm * 16 * MI + i * 16) * 128 + fo);
; #pragma unroll
;         for (int nh = 0; nh < NI; nh += 4) {
;           bf16x8 wf[4];
; #pragma unroll
;           for (int i = 0; i < 4; ++i) wf[i] = *(const bf16x8*)(sb + (wn * 16 * NI + (nh + i) * 16) * 128 + fo);
; #pragma unroll
;           for (int ni = 0; ni < 4; ++ni)
; #pragma unroll
;             for (int mi = 0; mi < MI; ++mi) acc[nh + ni][mi] = mfma16(wf[ni], af[mi], acc[nh + ni][mi]);
;         }
;       }
;     }
;   }
;   __syncthreads();
	v_mfma_f32_16x16x32_bf16 v[78:81], v[134:137], v[126:129], v[78:81]
	v_mfma_f32_16x16x32_bf16 v[74:77], v[134:137], v[130:133], v[74:77]
	v_mfma_f32_16x16x32_bf16 v[58:61], v[134:137], v[142:145], v[58:61]
	v_mfma_f32_16x16x32_bf16 v[126:129], v[134:137], v[146:149], v[158:161]
	ds_read_b128 v[130:133], v150
	ds_read_b128 v[134:137], v150 offset:2048
	ds_read_b128 v[142:145], v154 offset:34816
	ds_read_b128 v[146:149], v150 offset:4096
	ds_read_b128 v[150:153], v150 offset:6144
	s_waitcnt lgkmcnt(4)
	v_mfma_f32_16x16x32_bf16 v[138:141], v[122:125], v[130:133], v[138:141]
	s_waitcnt lgkmcnt(3)
	v_mfma_f32_16x16x32_bf16 v[118:121], v[122:125], v[134:137], v[118:121]
	s_waitcnt lgkmcnt(1)
	v_mfma_f32_16x16x32_bf16 v[114:117], v[122:125], v[146:149], v[114:117]
	s_waitcnt lgkmcnt(0)
	v_mfma_f32_16x16x32_bf16 v[110:113], v[122:125], v[150:153], v[110:113]
	v_mfma_f32_16x16x32_bf16 v[106:109], v[142:145], v[130:133], v[106:109]
	v_mfma_f32_16x16x32_bf16 v[102:105], v[142:145], v[134:137], v[102:105]
	v_mfma_f32_16x16x32_bf16 v[98:101], v[142:145], v[146:149], v[98:101]
	v_mfma_f32_16x16x32_bf16 v[94:97], v[142:145], v[150:153], v[94:97]
	ds_read_b128 v[122:125], v154 offset:36864
	ds_read_b128 v[142:145], v154 offset:38912
	s_waitcnt lgkmcnt(1)
	v_mfma_f32_16x16x32_bf16 v[90:93], v[122:125], v[130:133], v[90:93]
	v_mfma_f32_16x16x32_bf16 v[86:89], v[122:125], v[134:137], v[86:89]
	v_mfma_f32_16x16x32_bf16 v[82:85], v[122:125], v[146:149], v[82:85]
	v_mfma_f32_16x16x32_bf16 v[70:73], v[122:125], v[150:153], v[70:73]
	s_waitcnt lgkmcnt(0)
	v_mfma_f32_16x16x32_bf16 v[66:69], v[142:145], v[130:133], v[66:69]
	v_mfma_f32_16x16x32_bf16 v[54:57], v[142:145], v[134:137], v[54:57]
	v_mfma_f32_16x16x32_bf16 v[50:53], v[142:145], v[146:149], v[50:53]
	v_mfma_f32_16x16x32_bf16 v[46:49], v[142:145], v[150:153], v[46:49]
	ds_read_b128 v[122:125], v154 offset:40960
	ds_read_b128 v[142:145], v154 offset:43008
	s_waitcnt lgkmcnt(1)
	v_mfma_f32_16x16x32_bf16 v[42:45], v[122:125], v[130:133], v[42:45]
	v_mfma_f32_16x16x32_bf16 v[34:37], v[122:125], v[134:137], v[34:37]
	v_mfma_f32_16x16x32_bf16 v[30:33], v[122:125], v[146:149], v[30:33]
	v_mfma_f32_16x16x32_bf16 v[26:29], v[122:125], v[150:153], v[26:29]
	s_waitcnt lgkmcnt(0)
	v_mfma_f32_16x16x32_bf16 v[22:25], v[142:145], v[130:133], v[22:25]
	v_mfma_f32_16x16x32_bf16 v[18:21], v[142:145], v[134:137], v[18:21]
	v_mfma_f32_16x16x32_bf16 v[14:17], v[142:145], v[146:149], v[14:17]
	v_mfma_f32_16x16x32_bf16 v[10:13], v[142:145], v[150:153], v[10:13]
	ds_read_b128 v[122:125], v154 offset:45056
	ds_read_b128 v[142:145], v154 offset:47104
	s_waitcnt vmcnt(0) lgkmcnt(0)
	s_barrier
	v_mfma_f32_16x16x32_bf16 v[6:9], v[122:125], v[130:133], v[6:9]
	v_mfma_f32_16x16x32_bf16 v[2:5], v[122:125], v[134:137], v[2:5]
	v_mfma_f32_16x16x32_bf16 v[38:41], v[122:125], v[146:149], v[38:41]
	v_mfma_f32_16x16x32_bf16 v[62:65], v[122:125], v[150:153], v[62:65]
	ds_read_b128 v[122:125], v192
	v_mfma_f32_16x16x32_bf16 v[126:129], v[142:145], v[150:153], v[126:129]
	v_add_u32_e32 v150, v179, v180
	v_mfma_f32_16x16x32_bf16 v[78:81], v[142:145], v[130:133], v[78:81]
	v_mfma_f32_16x16x32_bf16 v[74:77], v[142:145], v[134:137], v[74:77]
	v_mfma_f32_16x16x32_bf16 v[58:61], v[142:145], v[146:149], v[58:61]
	ds_read_b128 v[130:133], v150
	ds_read_b128 v[134:137], v150 offset:2048
	ds_read_b128 v[142:145], v192 offset:2048
	ds_read_b128 v[146:149], v150 offset:4096
	ds_read_b128 v[150:153], v150 offset:6144
	s_waitcnt lgkmcnt(4)
	v_mfma_f32_16x16x32_bf16 v[138:141], v[122:125], v[130:133], v[138:141]
	s_waitcnt lgkmcnt(3)
	v_mfma_f32_16x16x32_bf16 v[118:121], v[122:125], v[134:137], v[118:121]
	s_waitcnt lgkmcnt(1)
	v_mfma_f32_16x16x32_bf16 v[114:117], v[122:125], v[146:149], v[114:117]
	s_waitcnt lgkmcnt(0)
	v_mfma_f32_16x16x32_bf16 v[110:113], v[122:125], v[150:153], v[110:113]
	v_mfma_f32_16x16x32_bf16 v[106:109], v[142:145], v[130:133], v[106:109]
	v_mfma_f32_16x16x32_bf16 v[102:105], v[142:145], v[134:137], v[102:105]
	v_mfma_f32_16x16x32_bf16 v[98:101], v[142:145], v[146:149], v[98:101]
	v_mfma_f32_16x16x32_bf16 v[142:145], v[142:145], v[150:153], v[94:97]
	s_nop 2
	ds_read_b128 v[94:97], v192 offset:4096
	ds_read_b128 v[122:125], v192 offset:6144
	s_waitcnt lgkmcnt(1)
	v_mfma_f32_16x16x32_bf16 v[154:157], v[94:97], v[130:133], v[90:93]
	s_waitcnt lgkmcnt(0)
	v_mfma_f32_16x16x32_bf16 v[158:161], v[122:125], v[134:137], v[54:57]
	s_nop 2
	ds_read_b128 v[54:57], v192 offset:8192
	ds_read_b128 v[90:93], v192 offset:10240
	s_waitcnt lgkmcnt(0)
	v_mfma_f32_16x16x32_bf16 v[184:187], v[90:93], v[134:137], v[18:21]
	v_mfma_f32_16x16x32_bf16 v[188:191], v[90:93], v[146:149], v[14:17]
	s_nop 2
	ds_read_b128 v[14:17], v192 offset:12288
	ds_read_b128 v[18:21], v192 offset:14336
	s_waitcnt lgkmcnt(1)
	v_mfma_f32_16x16x32_bf16 v[6:9], v[14:17], v[130:133], v[6:9]
	v_mfma_f32_16x16x32_bf16 v[2:5], v[14:17], v[134:137], v[2:5]
	v_mfma_f32_16x16x32_bf16 v[38:41], v[14:17], v[146:149], v[38:41]
	v_mfma_f32_16x16x32_bf16 v[192:195], v[14:17], v[150:153], v[62:65]
	ds_read_b128 v[14:17], v225
	v_mfma_f32_16x16x32_bf16 v[180:183], v[90:93], v[130:133], v[22:25]
	s_nop 2
	v_add_u32_e32 v22, v179, v178
	v_mfma_f32_16x16x32_bf16 v[86:89], v[94:97], v[134:137], v[86:89]
	v_mfma_f32_16x16x32_bf16 v[82:85], v[94:97], v[146:149], v[82:85]
	v_mfma_f32_16x16x32_bf16 v[70:73], v[94:97], v[150:153], v[70:73]
	v_mfma_f32_16x16x32_bf16 v[66:69], v[122:125], v[130:133], v[66:69]
	v_mfma_f32_16x16x32_bf16 v[50:53], v[122:125], v[146:149], v[50:53]
	v_mfma_f32_16x16x32_bf16 v[46:49], v[122:125], v[150:153], v[46:49]
	v_mfma_f32_16x16x32_bf16 v[42:45], v[54:57], v[130:133], v[42:45]
	v_mfma_f32_16x16x32_bf16 v[34:37], v[54:57], v[134:137], v[34:37]
	v_mfma_f32_16x16x32_bf16 v[162:165], v[54:57], v[146:149], v[30:33]
	v_mfma_f32_16x16x32_bf16 v[168:171], v[54:57], v[150:153], v[26:29]
	v_mfma_f32_16x16x32_bf16 v[10:13], v[90:93], v[150:153], v[10:13]
	s_waitcnt lgkmcnt(1)
; DI f32x4 mfma16(bf16x8 a, bf16x8 b, f32x4 c) { return __builtin_amdgcn_mfma_f32_16x16x32_bf16(a, b, c, 0, 0, 0); }
; template <int MI, int NI>
; DI void gemm_kloop(const u16* Au, int lda, const u16* Bu, int ldb, int K, f32x4 (&acc)[NI][MI], unsigned char* smem) {
;     ...
;       for (int ks = 0; ks < 2; ++ks) {
;         const int fo = ks ? fro1 : fro0;
;         bf16x8 af[MI];
; #pragma unroll
;         for (int i = 0; i < MI; ++i) af[i] = *(const bf16x8*)(sa + (wm * 16 * MI + i * 16) * 128 + fo);
; #pragma unroll
;         for (int nh = 0; nh < NI; nh += 4) {
;           bf16x8 wf[4];
; #pragma unroll
;           for (int i = 0; i < 4; ++i) wf[i] = *(const bf16x8*)(sb + (wn * 16 * NI + (nh + i) * 16) * 128 + fo);
; #pragma unroll
;           for (int ni = 0; ni < 4; ++ni)
; #pragma unroll
;             for (int mi = 0; mi < MI; ++mi) acc[nh + ni][mi] = mfma16(wf[ni], af[mi], acc[nh + ni][mi]);
;         }
; template <int MI, int NI>
; DI void resid_epilogue(const Params& p, int from_x, const f32x4 (&acc)[NI][MI], int row0, int n0, float* rowss_next, bool last, int lm, int lg) {
; #pragma unroll
;   for (int mi = 0; mi < MI; ++mi) {
;     const int m = row0 + mi * 16 + lm;
;     const float* hr = hrow_r(p, from_x == 1 ? 0 : 1, m);
;     float* hw = hrow_w(p, m);
;     u16* hbr = p.hb + (size_t)m * DM;
;     float ss = 0.f;
; #pragma unroll
;     for (int ni = 0; ni < NI; ++ni) {
;       const int n = n0 + ni * 16 + lg * 4;
;       float4 h;
;       if (from_x >= 2) {
;         const u32x2 pk = *(const u32x2*)(hbr + n);
;         h = make_float4(__uint_as_float(pk[0] << 16), __uint_as_float(pk[0] & 0xffff0000u), __uint_as_float(pk[1] << 16), __uint_as_float(pk[1] & 0xffff0000u));
;       } else h = *(const float4*)(hr + n);
	v_mfma_f32_16x16x32_bf16 v[130:133], v[18:21], v[130:133], v[78:81]
	v_mfma_f32_16x16x32_bf16 v[134:137], v[18:21], v[134:137], v[74:77]
	v_mfma_f32_16x16x32_bf16 v[146:149], v[18:21], v[146:149], v[58:61]
	v_mfma_f32_16x16x32_bf16 v[150:153], v[18:21], v[150:153], v[126:129]
	ds_read_b128 v[226:229], v22
	ds_read_b128 v[230:233], v22 offset:2048
	ds_read_b128 v[18:21], v225 offset:2048
	s_waitcnt lgkmcnt(2)
	v_mfma_f32_16x16x32_bf16 v[126:129], v[14:17], v[226:229], v[138:141]
	s_nop 2
	ds_read_b128 v[138:141], v22 offset:4096
	ds_read_b128 v[234:237], v22 offset:6144
	s_waitcnt lgkmcnt(3)
	v_mfma_f32_16x16x32_bf16 v[94:97], v[14:17], v[230:233], v[118:121]
	s_waitcnt lgkmcnt(1)
	v_mfma_f32_16x16x32_bf16 v[62:65], v[14:17], v[138:141], v[114:117]
	s_waitcnt lgkmcnt(0)
	v_mfma_f32_16x16x32_bf16 v[30:33], v[14:17], v[234:237], v[110:113]
	v_mfma_f32_16x16x32_bf16 v[122:125], v[18:21], v[226:229], v[106:109]
	v_mfma_f32_16x16x32_bf16 v[90:93], v[18:21], v[230:233], v[102:105]
	v_mfma_f32_16x16x32_bf16 v[58:61], v[18:21], v[138:141], v[98:101]
	v_mfma_f32_16x16x32_bf16 v[26:29], v[18:21], v[234:237], v[142:145]
	ds_read_b128 v[14:17], v225 offset:4096
	ds_read_b128 v[18:21], v225 offset:6144
	s_waitcnt lgkmcnt(1)
	v_mfma_f32_16x16x32_bf16 v[118:121], v[14:17], v[226:229], v[154:157]
	v_mfma_f32_16x16x32_bf16 v[86:89], v[14:17], v[230:233], v[86:89]
	v_mfma_f32_16x16x32_bf16 v[54:57], v[14:17], v[138:141], v[82:85]
	v_mfma_f32_16x16x32_bf16 v[22:25], v[14:17], v[234:237], v[70:73]
	s_waitcnt lgkmcnt(0)
	v_mfma_f32_16x16x32_bf16 v[114:117], v[18:21], v[226:229], v[66:69]
	ds_read_b128 v[14:17], v225 offset:8192
	s_nop 1
	ds_read_b128 v[66:69], v225 offset:10240
	s_waitcnt lgkmcnt(1)
	v_mfma_f32_16x16x32_bf16 v[78:81], v[14:17], v[230:233], v[34:37]
	s_nop 2
	ds_read_b128 v[34:37], v225 offset:12288
	ds_read_b128 v[142:145], v225 offset:14336
	s_waitcnt lgkmcnt(0)
	s_barrier
	v_mfma_f32_16x16x32_bf16 v[98:101], v[142:145], v[226:229], v[130:133]
	s_nop 2
	v_add_u32_e32 v130, s43, v176
	v_mfma_f32_16x16x32_bf16 v[70:73], v[34:37], v[230:233], v[2:5]
	s_nop 2
	v_mul_hi_i32 v2, v130, s81
	v_lshrrev_b32_e32 v3, 31, v2
	v_ashrrev_i32_e32 v2, 10, v2
	v_mfma_f32_16x16x32_bf16 v[82:85], v[18:21], v[230:233], v[158:161]
	v_add_u32_e32 v131, v2, v3
	v_mad_i32_i24 v133, v131, s82, v130
	v_add_u32_e32 v132, -16, v133
	v_mfma_f32_16x16x32_bf16 v[50:53], v[18:21], v[138:141], v[50:53]
	v_cmp_lt_u32_e32 vcc, s83, v132
	v_mfma_f32_16x16x32_bf16 v[18:21], v[18:21], v[234:237], v[46:49]
	v_mfma_f32_16x16x32_bf16 v[110:113], v[14:17], v[226:229], v[42:45]
	v_mfma_f32_16x16x32_bf16 v[46:49], v[14:17], v[138:141], v[162:165]
	v_mfma_f32_16x16x32_bf16 v[14:17], v[14:17], v[234:237], v[168:171]
	v_mfma_f32_16x16x32_bf16 v[106:109], v[66:69], v[226:229], v[180:183]
	v_mfma_f32_16x16x32_bf16 v[74:77], v[66:69], v[230:233], v[184:187]
	v_mfma_f32_16x16x32_bf16 v[42:45], v[66:69], v[138:141], v[188:191]
	v_mfma_f32_16x16x32_bf16 v[10:13], v[66:69], v[234:237], v[10:13]
	v_mfma_f32_16x16x32_bf16 v[102:105], v[34:37], v[226:229], v[6:9]
	v_mfma_f32_16x16x32_bf16 v[38:41], v[34:37], v[138:141], v[38:41]
	v_mfma_f32_16x16x32_bf16 v[6:9], v[34:37], v[234:237], v[192:195]
	v_mfma_f32_16x16x32_bf16 v[66:69], v[142:145], v[230:233], v[134:137]
	v_mfma_f32_16x16x32_bf16 v[34:37], v[142:145], v[138:141], v[146:149]
	v_mfma_f32_16x16x32_bf16 v[2:5], v[142:145], v[234:237], v[150:153]
	s_load_dwordx2 s[56:57], s[0:1], 0xc8
	s_load_dwordx2 s[58:59], s[0:1], 0xd8
	s_lshr_b32 s2, s31, 4
	s_lshl_b32 s2, s2, 2
	s_and_b32 s3, s31, 3
	s_or_b32 s2, s2, s3
	s_lshl_b32 s2, s2, 8
	s_lshr_b32 s3, s31, 2
	s_and_b32 s3, s3, 3
	s_lshl_b32 s3, s3, 8
	v_add_u32_e32 v130, s2, v176
	v_or_b32_e32 v131, s3, v177
	s_and_b64 vcc, exec, s[6:7]
	s_cbranch_vccnz .Lre_down_T
	s_load_dwordx2 s[60:61], s[0:1], 0xc0
	s_waitcnt lgkmcnt(0)
	v_add_u32_e32 v168, 0, v130
	v_lshlrev_b32_e32 v168, 11, v168
	v_lshl_add_u32 v242, v131, 1, v168
	v_add_u32_e32 v168, 0, v130
	v_mul_hi_i32 v169, v168, s81
	v_lshrrev_b32_e32 v170, 31, v169
	v_ashrrev_i32_e32 v169, 10, v169
	v_add_u32_e32 v169, v169, v170
	v_mad_i32_i24 v170, v169, s82, v168
	v_add_u32_e32 v171, -16, v170
	v_cmp_lt_u32_e32 vcc, s83, v171
	v_lshl_add_u32 v171, v169, 12, v171
	v_add_u32_e32 v168, 0xfffff000, v170
	v_cmp_gt_i32_e64 s[2:3], 16, v170
	s_nop 1
	v_cndmask_b32_e64 v168, v168, v170, s[2:3]
	v_lshl_add_u32 v168, v169, 7, v168
	v_cndmask_b32_e32 v168, v171, v168, vcc
	v_mov_b32_e32 v169, s60
	v_mov_b32_e32 v170, s58
	v_cndmask_b32_e32 v248, v169, v170, vcc
	v_mov_b32_e32 v169, s61
	v_mov_b32_e32 v170, s59
	v_cndmask_b32_e32 v249, v169, v170, vcc
	v_lshlrev_b32_e32 v168, 12, v168
	v_lshl_add_u32 v168, v131, 2, v168
	v_add_co_u32_e32 v248, vcc, v248, v168
	s_nop 1
	v_addc_co_u32_e32 v249, vcc, 0, v249, vcc
	global_load_dwordx2 v[132:133], v242, s[56:57] offset:0
	global_load_dwordx2 v[134:135], v242, s[56:57] offset:32
	global_load_dwordx2 v[136:137], v242, s[56:57] offset:64
	global_load_dwordx2 v[138:139], v242, s[56:57] offset:96
	global_load_dwordx2 v[140:141], v242, s[56:57] offset:128
	global_load_dwordx2 v[142:143], v242, s[56:57] offset:160
	global_load_dwordx2 v[144:145], v242, s[56:57] offset:192
	global_load_dwordx2 v[146:147], v242, s[56:57] offset:224
	v_add_u32_e32 v168, 16, v130
	v_lshlrev_b32_e32 v168, 11, v168
	v_lshl_add_u32 v243, v131, 1, v168
	v_add_u32_e32 v168, 16, v130
	v_mul_hi_i32 v169, v168, s81
	v_lshrrev_b32_e32 v170, 31, v169
	v_ashrrev_i32_e32 v169, 10, v169
	v_add_u32_e32 v169, v169, v170
	v_mad_i32_i24 v170, v169, s82, v168
	v_add_u32_e32 v171, -16, v170
	v_cmp_lt_u32_e32 vcc, s83, v171
	v_lshl_add_u32 v171, v169, 12, v171
	v_add_u32_e32 v168, 0xfffff000, v170
	v_cmp_gt_i32_e64 s[2:3], 16, v170
	s_nop 1
	v_cndmask_b32_e64 v168, v168, v170, s[2:3]
	v_lshl_add_u32 v168, v169, 7, v168
	v_cndmask_b32_e32 v168, v171, v168, vcc
	v_mov_b32_e32 v169, s60
	v_mov_b32_e32 v170, s58
	v_cndmask_b32_e32 v250, v169, v170, vcc
	v_mov_b32_e32 v169, s61
	v_mov_b32_e32 v170, s59
	v_cndmask_b32_e32 v251, v169, v170, vcc
	v_lshlrev_b32_e32 v168, 12, v168
	v_lshl_add_u32 v168, v131, 2, v168
	v_add_co_u32_e32 v250, vcc, v250, v168
	s_nop 1
	v_addc_co_u32_e32 v251, vcc, 0, v251, vcc
	global_load_dwordx2 v[148:149], v243, s[56:57] offset:0
	global_load_dwordx2 v[150:151], v243, s[56:57] offset:32
	global_load_dwordx2 v[152:153], v243, s[56:57] offset:64
	global_load_dwordx2 v[154:155], v243, s[56:57] offset:96
	global_load_dwordx2 v[156:157], v243, s[56:57] offset:128
	global_load_dwordx2 v[158:159], v243, s[56:57] offset:160
	global_load_dwordx2 v[160:161], v243, s[56:57] offset:192
	global_load_dwordx2 v[162:163], v243, s[56:57] offset:224
	s_waitcnt vmcnt(15)
; template <int MI, int NI>
; DI void resid_epilogue(const Params& p, int from_x, const f32x4 (&acc)[NI][MI], int row0, int n0, float* rowss_next, bool last, int lm, int lg) {
;     ...
;     for (int ni = 0; ni < NI; ++ni) {
;       const int n = n0 + ni * 16 + lg * 4;
;       float4 h;
;       if (from_x >= 2) {
;         const u32x2 pk = *(const u32x2*)(hbr + n);
;         h = make_float4(__uint_as_float(pk[0] << 16), __uint_as_float(pk[0] & 0xffff0000u), __uint_as_float(pk[1] << 16), __uint_as_float(pk[1] & 0xffff0000u));
;       } else h = *(const float4*)(hr + n);
;       h.x += acc[ni][mi][0]; h.y += acc[ni][mi][1]; h.z += acc[ni][mi][2]; h.w += acc[ni][mi][3];
;       if (last) *(float4*)(hw + n) = h;
	v_lshlrev_b32_e32 v168, 16, v132
	v_and_b32_e32 v169, 0xffff0000, v132
	v_lshlrev_b32_e32 v170, 16, v133
	v_and_b32_e32 v171, 0xffff0000, v133
	v_pk_add_f32 v[192:193], v[126:127], v[168:169]
	v_pk_add_f32 v[194:195], v[128:129], v[170:171]
	s_nop 0
	global_store_dwordx4 v[248:249], v[192:195], off offset:0
	s_nop 1
	s_waitcnt vmcnt(15)
	v_lshlrev_b32_e32 v168, 16, v134
	v_and_b32_e32 v169, 0xffff0000, v134
	v_lshlrev_b32_e32 v170, 16, v135
	v_and_b32_e32 v171, 0xffff0000, v135
	v_pk_add_f32 v[192:193], v[122:123], v[168:169]
	v_pk_add_f32 v[194:195], v[124:125], v[170:171]
	s_nop 0
	global_store_dwordx4 v[248:249], v[192:195], off offset:64
	s_nop 1
	s_waitcnt vmcnt(15)
	v_lshlrev_b32_e32 v168, 16, v136
	v_and_b32_e32 v169, 0xffff0000, v136
	v_lshlrev_b32_e32 v170, 16, v137
	v_and_b32_e32 v171, 0xffff0000, v137
	v_pk_add_f32 v[192:193], v[118:119], v[168:169]
	v_pk_add_f32 v[194:195], v[120:121], v[170:171]
	s_nop 0
	global_store_dwordx4 v[248:249], v[192:195], off offset:128
	s_nop 1
	s_waitcnt vmcnt(15)
	v_lshlrev_b32_e32 v168, 16, v138
	v_and_b32_e32 v169, 0xffff0000, v138
	v_lshlrev_b32_e32 v170, 16, v139
	v_and_b32_e32 v171, 0xffff0000, v139
	v_pk_add_f32 v[192:193], v[114:115], v[168:169]
	v_pk_add_f32 v[194:195], v[116:117], v[170:171]
	s_nop 0
	global_store_dwordx4 v[248:249], v[192:195], off offset:192
	s_nop 1
	s_waitcnt vmcnt(15)
	v_lshlrev_b32_e32 v168, 16, v140
	v_and_b32_e32 v169, 0xffff0000, v140
	v_lshlrev_b32_e32 v170, 16, v141
	v_and_b32_e32 v171, 0xffff0000, v141
	v_pk_add_f32 v[192:193], v[110:111], v[168:169]
	v_pk_add_f32 v[194:195], v[112:113], v[170:171]
	s_nop 0
	global_store_dwordx4 v[248:249], v[192:195], off offset:256
	s_nop 1
	s_waitcnt vmcnt(15)
	v_lshlrev_b32_e32 v168, 16, v142
	v_and_b32_e32 v169, 0xffff0000, v142
	v_lshlrev_b32_e32 v170, 16, v143
	v_and_b32_e32 v171, 0xffff0000, v143
	v_pk_add_f32 v[192:193], v[106:107], v[168:169]
	v_pk_add_f32 v[194:195], v[108:109], v[170:171]
	s_nop 0
	global_store_dwordx4 v[248:249], v[192:195], off offset:320
	s_nop 1
	s_waitcnt vmcnt(15)
	v_lshlrev_b32_e32 v168, 16, v144
	v_and_b32_e32 v169, 0xffff0000, v144
	v_lshlrev_b32_e32 v170, 16, v145
	v_and_b32_e32 v171, 0xffff0000, v145
	v_pk_add_f32 v[192:193], v[102:103], v[168:169]
	v_pk_add_f32 v[194:195], v[104:105], v[170:171]
	s_nop 0
	global_store_dwordx4 v[248:249], v[192:195], off offset:384
	s_nop 1
	s_waitcnt vmcnt(15)
	v_lshlrev_b32_e32 v168, 16, v146
	v_and_b32_e32 v169, 0xffff0000, v146
	v_lshlrev_b32_e32 v170, 16, v147
	v_and_b32_e32 v171, 0xffff0000, v147
	v_pk_add_f32 v[192:193], v[98:99], v[168:169]
	v_pk_add_f32 v[194:195], v[100:101], v[170:171]
	s_nop 0
	global_store_dwordx4 v[248:249], v[192:195], off offset:448
	s_nop 1
	v_add_u32_e32 v168, 32, v130
	v_lshlrev_b32_e32 v168, 11, v168
	v_lshl_add_u32 v242, v131, 1, v168
	v_add_u32_e32 v168, 32, v130
	v_mul_hi_i32 v169, v168, s81
	v_lshrrev_b32_e32 v170, 31, v169
	v_ashrrev_i32_e32 v169, 10, v169
	v_add_u32_e32 v169, v169, v170
	v_mad_i32_i24 v170, v169, s82, v168
	v_add_u32_e32 v171, -16, v170
	v_cmp_lt_u32_e32 vcc, s83, v171
	v_lshl_add_u32 v171, v169, 12, v171
	v_add_u32_e32 v168, 0xfffff000, v170
	v_cmp_gt_i32_e64 s[2:3], 16, v170
	s_nop 1
	v_cndmask_b32_e64 v168, v168, v170, s[2:3]
	v_lshl_add_u32 v168, v169, 7, v168
	v_cndmask_b32_e32 v168, v171, v168, vcc
	v_mov_b32_e32 v169, s60
	v_mov_b32_e32 v170, s58
	v_cndmask_b32_e32 v248, v169, v170, vcc
	v_mov_b32_e32 v169, s61
	v_mov_b32_e32 v170, s59
	v_cndmask_b32_e32 v249, v169, v170, vcc
	v_lshlrev_b32_e32 v168, 12, v168
	v_lshl_add_u32 v168, v131, 2, v168
	v_add_co_u32_e32 v248, vcc, v248, v168
	s_nop 1
	v_addc_co_u32_e32 v249, vcc, 0, v249, vcc
	global_load_dwordx2 v[132:133], v242, s[56:57] offset:0
	global_load_dwordx2 v[134:135], v242, s[56:57] offset:32
	global_load_dwordx2 v[136:137], v242, s[56:57] offset:64
	global_load_dwordx2 v[138:139], v242, s[56:57] offset:96
	global_load_dwordx2 v[140:141], v242, s[56:57] offset:128
	global_load_dwordx2 v[142:143], v242, s[56:57] offset:160
	global_load_dwordx2 v[144:145], v242, s[56:57] offset:192
	global_load_dwordx2 v[146:147], v242, s[56:57] offset:224
	s_waitcnt vmcnt(23)
	v_lshlrev_b32_e32 v168, 16, v148
	v_and_b32_e32 v169, 0xffff0000, v148
	v_lshlrev_b32_e32 v170, 16, v149
	v_and_b32_e32 v171, 0xffff0000, v149
	v_pk_add_f32 v[192:193], v[94:95], v[168:169]
	v_pk_add_f32 v[194:195], v[96:97], v[170:171]
	s_nop 0
	global_store_dwordx4 v[250:251], v[192:195], off offset:0
	s_nop 1
	s_waitcnt vmcnt(23)
	v_lshlrev_b32_e32 v168, 16, v150
	v_and_b32_e32 v169, 0xffff0000, v150
	v_lshlrev_b32_e32 v170, 16, v151
	v_and_b32_e32 v171, 0xffff0000, v151
	v_pk_add_f32 v[192:193], v[90:91], v[168:169]
	v_pk_add_f32 v[194:195], v[92:93], v[170:171]
	s_nop 0
	global_store_dwordx4 v[250:251], v[192:195], off offset:64
	s_nop 1
	s_waitcnt vmcnt(23)
	v_lshlrev_b32_e32 v168, 16, v152
	v_and_b32_e32 v169, 0xffff0000, v152
	v_lshlrev_b32_e32 v170, 16, v153
	v_and_b32_e32 v171, 0xffff0000, v153
	v_pk_add_f32 v[192:193], v[86:87], v[168:169]
	v_pk_add_f32 v[194:195], v[88:89], v[170:171]
	s_nop 0
	global_store_dwordx4 v[250:251], v[192:195], off offset:128
	s_nop 1
	s_waitcnt vmcnt(23)
	v_lshlrev_b32_e32 v168, 16, v154
	v_and_b32_e32 v169, 0xffff0000, v154
	v_lshlrev_b32_e32 v170, 16, v155
	v_and_b32_e32 v171, 0xffff0000, v155
	v_pk_add_f32 v[192:193], v[82:83], v[168:169]
	v_pk_add_f32 v[194:195], v[84:85], v[170:171]
	s_nop 0
	global_store_dwordx4 v[250:251], v[192:195], off offset:192
	s_nop 1
	s_waitcnt vmcnt(23)
; template <int MI, int NI>
; DI void resid_epilogue(const Params& p, int from_x, const f32x4 (&acc)[NI][MI], int row0, int n0, float* rowss_next, bool last, int lm, int lg) {
;     ...
;     for (int ni = 0; ni < NI; ++ni) {
;       const int n = n0 + ni * 16 + lg * 4;
;       float4 h;
;       if (from_x >= 2) {
;         const u32x2 pk = *(const u32x2*)(hbr + n);
;         h = make_float4(__uint_as_float(pk[0] << 16), __uint_as_float(pk[0] & 0xffff0000u), __uint_as_float(pk[1] << 16), __uint_as_float(pk[1] & 0xffff0000u));
;       } else h = *(const float4*)(hr + n);
;       h.x += acc[ni][mi][0]; h.y += acc[ni][mi][1]; h.z += acc[ni][mi][2]; h.w += acc[ni][mi][3];
;       if (last) *(float4*)(hw + n) = h;
	v_lshlrev_b32_e32 v168, 16, v156
	v_and_b32_e32 v169, 0xffff0000, v156
	v_lshlrev_b32_e32 v170, 16, v157
	v_and_b32_e32 v171, 0xffff0000, v157
	v_pk_add_f32 v[192:193], v[78:79], v[168:169]
	v_pk_add_f32 v[194:195], v[80:81], v[170:171]
	s_nop 0
	global_store_dwordx4 v[250:251], v[192:195], off offset:256
	s_nop 1
	s_waitcnt vmcnt(23)
	v_lshlrev_b32_e32 v168, 16, v158
	v_and_b32_e32 v169, 0xffff0000, v158
	v_lshlrev_b32_e32 v170, 16, v159
	v_and_b32_e32 v171, 0xffff0000, v159
	v_pk_add_f32 v[192:193], v[74:75], v[168:169]
	v_pk_add_f32 v[194:195], v[76:77], v[170:171]
	s_nop 0
	global_store_dwordx4 v[250:251], v[192:195], off offset:320
	s_nop 1
	s_waitcnt vmcnt(23)
	v_lshlrev_b32_e32 v168, 16, v160
	v_and_b32_e32 v169, 0xffff0000, v160
	v_lshlrev_b32_e32 v170, 16, v161
	v_and_b32_e32 v171, 0xffff0000, v161
	v_pk_add_f32 v[192:193], v[70:71], v[168:169]
	v_pk_add_f32 v[194:195], v[72:73], v[170:171]
	s_nop 0
	global_store_dwordx4 v[250:251], v[192:195], off offset:384
	s_nop 1
	s_waitcnt vmcnt(23)
	v_lshlrev_b32_e32 v168, 16, v162
	v_and_b32_e32 v169, 0xffff0000, v162
	v_lshlrev_b32_e32 v170, 16, v163
	v_and_b32_e32 v171, 0xffff0000, v163
	v_pk_add_f32 v[192:193], v[66:67], v[168:169]
	v_pk_add_f32 v[194:195], v[68:69], v[170:171]
	s_nop 0
	global_store_dwordx4 v[250:251], v[192:195], off offset:448
	s_nop 1
	v_add_u32_e32 v168, 48, v130
	v_lshlrev_b32_e32 v168, 11, v168
	v_lshl_add_u32 v243, v131, 1, v168
	v_add_u32_e32 v168, 48, v130
	v_mul_hi_i32 v169, v168, s81
	v_lshrrev_b32_e32 v170, 31, v169
	v_ashrrev_i32_e32 v169, 10, v169
	v_add_u32_e32 v169, v169, v170
	v_mad_i32_i24 v170, v169, s82, v168
	v_add_u32_e32 v171, -16, v170
	v_cmp_lt_u32_e32 vcc, s83, v171
	v_lshl_add_u32 v171, v169, 12, v171
	v_add_u32_e32 v168, 0xfffff000, v170
	v_cmp_gt_i32_e64 s[2:3], 16, v170
	s_nop 1
	v_cndmask_b32_e64 v168, v168, v170, s[2:3]
	v_lshl_add_u32 v168, v169, 7, v168
	v_cndmask_b32_e32 v168, v171, v168, vcc
	v_mov_b32_e32 v169, s60
	v_mov_b32_e32 v170, s58
	v_cndmask_b32_e32 v250, v169, v170, vcc
	v_mov_b32_e32 v169, s61
	v_mov_b32_e32 v170, s59
	v_cndmask_b32_e32 v251, v169, v170, vcc
	v_lshlrev_b32_e32 v168, 12, v168
	v_lshl_add_u32 v168, v131, 2, v168
	v_add_co_u32_e32 v250, vcc, v250, v168
	s_nop 1
	v_addc_co_u32_e32 v251, vcc, 0, v251, vcc
	global_load_dwordx2 v[148:149], v243, s[56:57] offset:0
	global_load_dwordx2 v[150:151], v243, s[56:57] offset:32
	global_load_dwordx2 v[152:153], v243, s[56:57] offset:64
	global_load_dwordx2 v[154:155], v243, s[56:57] offset:96
	global_load_dwordx2 v[156:157], v243, s[56:57] offset:128
	global_load_dwordx2 v[158:159], v243, s[56:57] offset:160
	global_load_dwordx2 v[160:161], v243, s[56:57] offset:192
	global_load_dwordx2 v[162:163], v243, s[56:57] offset:224
	s_waitcnt vmcnt(23)
	v_lshlrev_b32_e32 v168, 16, v132
	v_and_b32_e32 v169, 0xffff0000, v132
	v_lshlrev_b32_e32 v170, 16, v133
	v_and_b32_e32 v171, 0xffff0000, v133
	v_pk_add_f32 v[192:193], v[62:63], v[168:169]
	v_pk_add_f32 v[194:195], v[64:65], v[170:171]
	s_nop 0
	global_store_dwordx4 v[248:249], v[192:195], off offset:0
	s_nop 1
	s_waitcnt vmcnt(23)
	v_lshlrev_b32_e32 v168, 16, v134
	v_and_b32_e32 v169, 0xffff0000, v134
	v_lshlrev_b32_e32 v170, 16, v135
	v_and_b32_e32 v171, 0xffff0000, v135
	v_pk_add_f32 v[192:193], v[58:59], v[168:169]
	v_pk_add_f32 v[194:195], v[60:61], v[170:171]
	s_nop 0
	global_store_dwordx4 v[248:249], v[192:195], off offset:64
	s_nop 1
	s_waitcnt vmcnt(23)
	v_lshlrev_b32_e32 v168, 16, v136
	v_and_b32_e32 v169, 0xffff0000, v136
	v_lshlrev_b32_e32 v170, 16, v137
	v_and_b32_e32 v171, 0xffff0000, v137
	v_pk_add_f32 v[192:193], v[54:55], v[168:169]
	v_pk_add_f32 v[194:195], v[56:57], v[170:171]
	s_nop 0
	global_store_dwordx4 v[248:249], v[192:195], off offset:128
	s_nop 1
	s_waitcnt vmcnt(23)
	v_lshlrev_b32_e32 v168, 16, v138
	v_and_b32_e32 v169, 0xffff0000, v138
	v_lshlrev_b32_e32 v170, 16, v139
	v_and_b32_e32 v171, 0xffff0000, v139
	v_pk_add_f32 v[192:193], v[50:51], v[168:169]
	v_pk_add_f32 v[194:195], v[52:53], v[170:171]
	s_nop 0
	global_store_dwordx4 v[248:249], v[192:195], off offset:192
	s_nop 1
	s_waitcnt vmcnt(23)
; template <int MI, int NI>
; DI void resid_epilogue(const Params& p, int from_x, const f32x4 (&acc)[NI][MI], int row0, int n0, float* rowss_next, bool last, int lm, int lg) {
;     ...
;     for (int ni = 0; ni < NI; ++ni) {
;       const int n = n0 + ni * 16 + lg * 4;
;       float4 h;
;       if (from_x >= 2) {
;         const u32x2 pk = *(const u32x2*)(hbr + n);
;         h = make_float4(__uint_as_float(pk[0] << 16), __uint_as_float(pk[0] & 0xffff0000u), __uint_as_float(pk[1] << 16), __uint_as_float(pk[1] & 0xffff0000u));
;       } else h = *(const float4*)(hr + n);
;       h.x += acc[ni][mi][0]; h.y += acc[ni][mi][1]; h.z += acc[ni][mi][2]; h.w += acc[ni][mi][3];
;       if (last) *(float4*)(hw + n) = h;
	v_lshlrev_b32_e32 v168, 16, v140
	v_and_b32_e32 v169, 0xffff0000, v140
	v_lshlrev_b32_e32 v170, 16, v141
	v_and_b32_e32 v171, 0xffff0000, v141
	v_pk_add_f32 v[192:193], v[46:47], v[168:169]
	v_pk_add_f32 v[194:195], v[48:49], v[170:171]
	s_nop 0
	global_store_dwordx4 v[248:249], v[192:195], off offset:256
	s_nop 1
	s_waitcnt vmcnt(23)
	v_lshlrev_b32_e32 v168, 16, v142
	v_and_b32_e32 v169, 0xffff0000, v142
	v_lshlrev_b32_e32 v170, 16, v143
	v_and_b32_e32 v171, 0xffff0000, v143
	v_pk_add_f32 v[192:193], v[42:43], v[168:169]
	v_pk_add_f32 v[194:195], v[44:45], v[170:171]
	s_nop 0
	global_store_dwordx4 v[248:249], v[192:195], off offset:320
	s_nop 1
	s_waitcnt vmcnt(23)
	v_lshlrev_b32_e32 v168, 16, v144
	v_and_b32_e32 v169, 0xffff0000, v144
	v_lshlrev_b32_e32 v170, 16, v145
	v_and_b32_e32 v171, 0xffff0000, v145
	v_pk_add_f32 v[192:193], v[38:39], v[168:169]
	v_pk_add_f32 v[194:195], v[40:41], v[170:171]
	s_nop 0
	global_store_dwordx4 v[248:249], v[192:195], off offset:384
	s_nop 1
	s_waitcnt vmcnt(23)
	v_lshlrev_b32_e32 v168, 16, v146
	v_and_b32_e32 v169, 0xffff0000, v146
	v_lshlrev_b32_e32 v170, 16, v147
	v_and_b32_e32 v171, 0xffff0000, v147
	v_pk_add_f32 v[192:193], v[34:35], v[168:169]
	v_pk_add_f32 v[194:195], v[36:37], v[170:171]
	s_nop 0
	global_store_dwordx4 v[248:249], v[192:195], off offset:448
	s_nop 1
	s_waitcnt vmcnt(15)
	v_lshlrev_b32_e32 v168, 16, v148
	v_and_b32_e32 v169, 0xffff0000, v148
	v_lshlrev_b32_e32 v170, 16, v149
	v_and_b32_e32 v171, 0xffff0000, v149
	v_pk_add_f32 v[192:193], v[30:31], v[168:169]
	v_pk_add_f32 v[194:195], v[32:33], v[170:171]
	s_nop 0
	global_store_dwordx4 v[250:251], v[192:195], off offset:0
	s_nop 1
	s_waitcnt vmcnt(15)
	v_lshlrev_b32_e32 v168, 16, v150
	v_and_b32_e32 v169, 0xffff0000, v150
	v_lshlrev_b32_e32 v170, 16, v151
	v_and_b32_e32 v171, 0xffff0000, v151
	v_pk_add_f32 v[192:193], v[26:27], v[168:169]
	v_pk_add_f32 v[194:195], v[28:29], v[170:171]
	s_nop 0
	global_store_dwordx4 v[250:251], v[192:195], off offset:64
	s_nop 1
	s_waitcnt vmcnt(15)
	v_lshlrev_b32_e32 v168, 16, v152
	v_and_b32_e32 v169, 0xffff0000, v152
	v_lshlrev_b32_e32 v170, 16, v153
	v_and_b32_e32 v171, 0xffff0000, v153
	v_pk_add_f32 v[192:193], v[22:23], v[168:169]
	v_pk_add_f32 v[194:195], v[24:25], v[170:171]
	s_nop 0
	global_store_dwordx4 v[250:251], v[192:195], off offset:128
	s_nop 1
	s_waitcnt vmcnt(15)
	v_lshlrev_b32_e32 v168, 16, v154
	v_and_b32_e32 v169, 0xffff0000, v154
	v_lshlrev_b32_e32 v170, 16, v155
	v_and_b32_e32 v171, 0xffff0000, v155
	v_pk_add_f32 v[192:193], v[18:19], v[168:169]
	v_pk_add_f32 v[194:195], v[20:21], v[170:171]
	s_nop 0
	global_store_dwordx4 v[250:251], v[192:195], off offset:192
	s_nop 1
	s_waitcnt vmcnt(15)
	v_lshlrev_b32_e32 v168, 16, v156
	v_and_b32_e32 v169, 0xffff0000, v156
	v_lshlrev_b32_e32 v170, 16, v157
	v_and_b32_e32 v171, 0xffff0000, v157
	v_pk_add_f32 v[192:193], v[14:15], v[168:169]
	v_pk_add_f32 v[194:195], v[16:17], v[170:171]
	s_nop 0
	global_store_dwordx4 v[250:251], v[192:195], off offset:256
	s_nop 1
	s_waitcnt vmcnt(15)
	v_lshlrev_b32_e32 v168, 16, v158
	v_and_b32_e32 v169, 0xffff0000, v158
	v_lshlrev_b32_e32 v170, 16, v159
	v_and_b32_e32 v171, 0xffff0000, v159
	v_pk_add_f32 v[192:193], v[10:11], v[168:169]
	v_pk_add_f32 v[194:195], v[12:13], v[170:171]
	s_nop 0
	global_store_dwordx4 v[250:251], v[192:195], off offset:320
	s_nop 1
	s_waitcnt vmcnt(15)
	v_lshlrev_b32_e32 v168, 16, v160
	v_and_b32_e32 v169, 0xffff0000, v160
	v_lshlrev_b32_e32 v170, 16, v161
	v_and_b32_e32 v171, 0xffff0000, v161
	v_pk_add_f32 v[192:193], v[6:7], v[168:169]
	v_pk_add_f32 v[194:195], v[8:9], v[170:171]
	s_nop 0
	global_store_dwordx4 v[250:251], v[192:195], off offset:384
	s_nop 1
	s_waitcnt vmcnt(15)
	v_lshlrev_b32_e32 v168, 16, v162
	v_and_b32_e32 v169, 0xffff0000, v162
	v_lshlrev_b32_e32 v170, 16, v163
	v_and_b32_e32 v171, 0xffff0000, v163
	v_pk_add_f32 v[192:193], v[2:3], v[168:169]
	v_pk_add_f32 v[194:195], v[4:5], v[170:171]
	s_nop 0
	global_store_dwordx4 v[250:251], v[192:195], off offset:448
	s_nop 1
	s_branch .LBB0_958

; DI f32x4 mfma16(bf16x8 a, bf16x8 b, f32x4 c) { return __builtin_amdgcn_mfma_f32_16x16x32_bf16(a, b, c, 0, 0, 0); }
; template <int MI, int NI>
; DI void gemm_kloop(const u16* Au, int lda, const u16* Bu, int ldb, int K, f32x4 (&acc)[NI][MI], unsigned char* smem) {
;     ...
;   for (int kt = 0; kt < nk; ++kt) {
;     __syncthreads();
;     if (kt + 1 < nk) {
;       SWRITE((kt + 1) & 1);
;       if (kt + 2 < nk) GLOAD((kt + 2) << 6);
;     }
;     {
;       const unsigned char* sa = smem + (kt & 1) * 65536;
;       const unsigned char* sb = sa + 32768;
; #pragma unroll
;       for (int ks = 0; ks < 2; ++ks) {
;         const int fo = ks ? fro1 : fro0;
;         bf16x8 af[MI];
; #pragma unroll
;         for (int i = 0; i < MI; ++i) af[i] = *(const bf16x8*)(sa + (wm * 16 * MI + i * 16) * 128 + fo);
; #pragma unroll
;         for (int nh = 0; nh < NI; nh += 4) {
;           bf16x8 wf[4];
; #pragma unroll
;           for (int i = 0; i < 4; ++i) wf[i] = *(const bf16x8*)(sb + (wn * 16 * NI + (nh + i) * 16) * 128 + fo);
; #pragma unroll
;           for (int ni = 0; ni < 4; ++ni)
; #pragma unroll
;             for (int mi = 0; mi < MI; ++mi) acc[nh + ni][mi] = mfma16(wf[ni], af[mi], acc[nh + ni][mi]);
;         }
.Lk_g1:
	s_waitcnt vmcnt(0) lgkmcnt(0)
	s_barrier
	ds_read_b128 v[180:183], v228 offset:32768
	ds_read_b128 v[82:85], v226
	ds_read_b128 v[86:89], v226 offset:2048
	ds_read_b128 v[90:93], v226 offset:4096
	ds_read_b128 v[94:97], v226 offset:6144
	ds_read_b128 v[184:187], v228 offset:34816
	ds_read_b128 v[188:191], v228 offset:36864
	s_and_b32 s92, s95, 1
	s_xor_b32 s92, s92, 1
	s_lshl_b32 s92, s92, 16
	s_waitcnt lgkmcnt(5)
	v_mfma_f32_16x16x32_bf16 v[142:145], v[180:183], v[82:85], v[142:145]
	ds_read_b128 v[192:195], v228 offset:38912
	s_waitcnt lgkmcnt(5)
	v_mfma_f32_16x16x32_bf16 v[138:141], v[180:183], v[86:89], v[138:141]
	s_waitcnt lgkmcnt(4)
	v_mfma_f32_16x16x32_bf16 v[134:137], v[180:183], v[90:93], v[134:137]
	s_add_u32 m0, s92, s94
	s_nop 0
	global_load_lds_dwordx4 v254, s[88:89]
	s_waitcnt lgkmcnt(3)
	v_mfma_f32_16x16x32_bf16 v[130:133], v[180:183], v[94:97], v[130:133]
	s_waitcnt lgkmcnt(2)
	v_mfma_f32_16x16x32_bf16 v[126:129], v[184:187], v[82:85], v[126:129]
	ds_read_b128 v[180:183], v228 offset:40960
	v_mfma_f32_16x16x32_bf16 v[122:125], v[184:187], v[86:89], v[122:125]
	ds_read_b128 v[98:101], v227
	v_mfma_f32_16x16x32_bf16 v[118:121], v[184:187], v[90:93], v[118:121]
	s_add_u32 m0, m0, 0x2000
	s_add_u32 s92, s88, 0x20000
	s_addc_u32 s93, s89, 0
	global_load_lds_dwordx4 v254, s[92:93]
	v_mfma_f32_16x16x32_bf16 v[102:105], v[184:187], v[94:97], v[102:105]
	s_waitcnt lgkmcnt(3)
	v_mfma_f32_16x16x32_bf16 v[78:81], v[188:191], v[82:85], v[78:81]
	ds_read_b128 v[184:187], v228 offset:43008
	v_mfma_f32_16x16x32_bf16 v[74:77], v[188:191], v[86:89], v[74:77]
	ds_read_b128 v[106:109], v227 offset:2048
	v_mfma_f32_16x16x32_bf16 v[70:73], v[188:191], v[90:93], v[70:73]
	s_add_u32 m0, m0, 0x2000
	s_add_u32 s92, s88, 0x40000
	s_addc_u32 s93, s89, 0
	global_load_lds_dwordx4 v254, s[92:93]
	v_mfma_f32_16x16x32_bf16 v[66:69], v[188:191], v[94:97], v[66:69]
	s_waitcnt lgkmcnt(4)
	v_mfma_f32_16x16x32_bf16 v[62:65], v[192:195], v[82:85], v[62:65]
	ds_read_b128 v[188:191], v228 offset:45056
	v_mfma_f32_16x16x32_bf16 v[58:61], v[192:195], v[86:89], v[58:61]
	ds_read_b128 v[110:113], v227 offset:4096
	v_mfma_f32_16x16x32_bf16 v[54:57], v[192:195], v[90:93], v[54:57]
	s_add_u32 m0, m0, 0x2000
	s_add_u32 s92, s88, 0x60000
	s_addc_u32 s93, s89, 0
	global_load_lds_dwordx4 v254, s[92:93]
	v_mfma_f32_16x16x32_bf16 v[50:53], v[192:195], v[94:97], v[50:53]
	s_waitcnt lgkmcnt(5)
	v_mfma_f32_16x16x32_bf16 v[46:49], v[180:183], v[82:85], v[46:49]
	ds_read_b128 v[192:195], v228 offset:47104
	v_mfma_f32_16x16x32_bf16 v[42:45], v[180:183], v[86:89], v[42:45]
	ds_read_b128 v[114:117], v227 offset:6144
	v_mfma_f32_16x16x32_bf16 v[38:41], v[180:183], v[90:93], v[38:41]
	s_add_u32 m0, m0, 0x2000
	s_nop 0
	global_load_lds_dwordx4 v254, s[90:91]
	v_mfma_f32_16x16x32_bf16 v[34:37], v[180:183], v[94:97], v[34:37]
	s_waitcnt lgkmcnt(5)
	v_mfma_f32_16x16x32_bf16 v[26:29], v[184:187], v[82:85], v[26:29]
	ds_read_b128 v[180:183], v229 offset:32768
	v_mfma_f32_16x16x32_bf16 v[18:21], v[184:187], v[86:89], v[18:21]
	v_mfma_f32_16x16x32_bf16 v[30:33], v[184:187], v[90:93], v[30:33]
	s_add_u32 m0, m0, 0x2000
	s_add_u32 s92, s90, 0x20000
	s_addc_u32 s93, s91, 0
	global_load_lds_dwordx4 v254, s[92:93]
	v_mfma_f32_16x16x32_bf16 v[22:25], v[184:187], v[94:97], v[22:25]
	s_waitcnt lgkmcnt(4)
	v_mfma_f32_16x16x32_bf16 v[6:9], v[188:191], v[82:85], v[6:9]
	ds_read_b128 v[184:187], v229 offset:34816
	v_mfma_f32_16x16x32_bf16 v[14:17], v[188:191], v[86:89], v[14:17]
	v_mfma_f32_16x16x32_bf16 v[10:13], v[188:191], v[90:93], v[10:13]
	s_add_u32 m0, m0, 0x2000
	s_add_u32 s92, s90, 0x40000
	s_addc_u32 s93, s91, 0
	global_load_lds_dwordx4 v254, s[92:93]
	v_mfma_f32_16x16x32_bf16 v[2:5], v[188:191], v[94:97], v[2:5]
	s_waitcnt lgkmcnt(3)
	v_mfma_f32_16x16x32_bf16 v[146:149], v[192:195], v[82:85], v[146:149]
	ds_read_b128 v[188:191], v229 offset:36864
	v_mfma_f32_16x16x32_bf16 v[154:157], v[192:195], v[86:89], v[154:157]
	v_mfma_f32_16x16x32_bf16 v[150:153], v[192:195], v[90:93], v[150:153]
	s_add_u32 m0, m0, 0x2000
	s_add_u32 s92, s90, 0x60000
	s_addc_u32 s93, s91, 0
	global_load_lds_dwordx4 v254, s[92:93]
	v_mfma_f32_16x16x32_bf16 v[158:161], v[192:195], v[94:97], v[158:161]
	s_waitcnt lgkmcnt(2)
	v_mfma_f32_16x16x32_bf16 v[142:145], v[180:183], v[98:101], v[142:145]
	ds_read_b128 v[192:195], v229 offset:38912
	v_mfma_f32_16x16x32_bf16 v[138:141], v[180:183], v[106:109], v[138:141]
	v_mfma_f32_16x16x32_bf16 v[134:137], v[180:183], v[110:113], v[134:137]
	v_mfma_f32_16x16x32_bf16 v[130:133], v[180:183], v[114:117], v[130:133]
	s_waitcnt lgkmcnt(2)
	v_mfma_f32_16x16x32_bf16 v[126:129], v[184:187], v[98:101], v[126:129]
	ds_read_b128 v[180:183], v229 offset:40960
	v_mfma_f32_16x16x32_bf16 v[122:125], v[184:187], v[106:109], v[122:125]
	v_mfma_f32_16x16x32_bf16 v[118:121], v[184:187], v[110:113], v[118:121]
	v_mfma_f32_16x16x32_bf16 v[102:105], v[184:187], v[114:117], v[102:105]
	s_waitcnt lgkmcnt(2)
	v_mfma_f32_16x16x32_bf16 v[78:81], v[188:191], v[98:101], v[78:81]
	ds_read_b128 v[184:187], v229 offset:43008
	v_mfma_f32_16x16x32_bf16 v[74:77], v[188:191], v[106:109], v[74:77]
	v_mfma_f32_16x16x32_bf16 v[70:73], v[188:191], v[110:113], v[70:73]
	v_mfma_f32_16x16x32_bf16 v[66:69], v[188:191], v[114:117], v[66:69]
	s_waitcnt lgkmcnt(2)
	v_mfma_f32_16x16x32_bf16 v[62:65], v[192:195], v[98:101], v[62:65]
	ds_read_b128 v[188:191], v229 offset:45056
	v_mfma_f32_16x16x32_bf16 v[58:61], v[192:195], v[106:109], v[58:61]
	v_mfma_f32_16x16x32_bf16 v[54:57], v[192:195], v[110:113], v[54:57]
	v_mfma_f32_16x16x32_bf16 v[50:53], v[192:195], v[114:117], v[50:53]
	s_waitcnt lgkmcnt(2)
; DI f32x4 mfma16(bf16x8 a, bf16x8 b, f32x4 c) { return __builtin_amdgcn_mfma_f32_16x16x32_bf16(a, b, c, 0, 0, 0); }
; template <int MI, int NI>
; DI void gemm_kloop(const u16* Au, int lda, const u16* Bu, int ldb, int K, f32x4 (&acc)[NI][MI], unsigned char* smem) {
;     ...
;   for (int kt = 0; kt < nk; ++kt) {
;     __syncthreads();
;     if (kt + 1 < nk) {
;       SWRITE((kt + 1) & 1);
;       if (kt + 2 < nk) GLOAD((kt + 2) << 6);
;     }
;     {
;       const unsigned char* sa = smem + (kt & 1) * 65536;
;       const unsigned char* sb = sa + 32768;
; #pragma unroll
;       for (int ks = 0; ks < 2; ++ks) {
;         const int fo = ks ? fro1 : fro0;
;         bf16x8 af[MI];
; #pragma unroll
;         for (int i = 0; i < MI; ++i) af[i] = *(const bf16x8*)(sa + (wm * 16 * MI + i * 16) * 128 + fo);
; #pragma unroll
;         for (int nh = 0; nh < NI; nh += 4) {
;           bf16x8 wf[4];
; #pragma unroll
;           for (int i = 0; i < 4; ++i) wf[i] = *(const bf16x8*)(sb + (wn * 16 * NI + (nh + i) * 16) * 128 + fo);
; #pragma unroll
;           for (int ni = 0; ni < 4; ++ni)
; #pragma unroll
;             for (int mi = 0; mi < MI; ++mi) acc[nh + ni][mi] = mfma16(wf[ni], af[mi], acc[nh + ni][mi]);
;         }
	v_mfma_f32_16x16x32_bf16 v[46:49], v[180:183], v[98:101], v[46:49]
	ds_read_b128 v[192:195], v229 offset:47104
	v_mfma_f32_16x16x32_bf16 v[42:45], v[180:183], v[106:109], v[42:45]
	v_mfma_f32_16x16x32_bf16 v[38:41], v[180:183], v[110:113], v[38:41]
	v_mfma_f32_16x16x32_bf16 v[34:37], v[180:183], v[114:117], v[34:37]
	s_waitcnt lgkmcnt(2)
	v_mfma_f32_16x16x32_bf16 v[26:29], v[184:187], v[98:101], v[26:29]
	v_mfma_f32_16x16x32_bf16 v[18:21], v[184:187], v[106:109], v[18:21]
	v_mfma_f32_16x16x32_bf16 v[30:33], v[184:187], v[110:113], v[30:33]
	v_mfma_f32_16x16x32_bf16 v[22:25], v[184:187], v[114:117], v[22:25]
	s_waitcnt lgkmcnt(1)
	v_mfma_f32_16x16x32_bf16 v[6:9], v[188:191], v[98:101], v[6:9]
	v_mfma_f32_16x16x32_bf16 v[14:17], v[188:191], v[106:109], v[14:17]
	v_mfma_f32_16x16x32_bf16 v[10:13], v[188:191], v[110:113], v[10:13]
	v_mfma_f32_16x16x32_bf16 v[2:5], v[188:191], v[114:117], v[2:5]
	s_waitcnt lgkmcnt(0)
	v_mfma_f32_16x16x32_bf16 v[146:149], v[192:195], v[98:101], v[146:149]
	v_mfma_f32_16x16x32_bf16 v[154:157], v[192:195], v[106:109], v[154:157]
	v_mfma_f32_16x16x32_bf16 v[150:153], v[192:195], v[110:113], v[150:153]
	v_mfma_f32_16x16x32_bf16 v[158:161], v[192:195], v[114:117], v[158:161]
	v_xor_b32_e32 v226, 0x10000, v226
	v_xor_b32_e32 v227, 0x10000, v227
	v_xor_b32_e32 v228, 0x10000, v228
	v_xor_b32_e32 v229, 0x10000, v229
	s_add_u32 s88, s88, 0x80
	s_addc_u32 s89, s89, 0
	s_add_u32 s90, s90, 0x80
	s_addc_u32 s91, s91, 0
	s_add_u32 s95, s95, 1
	s_cmp_lg_u32 s95, 14
	s_cbranch_scc1 .Lk_g1
	s_waitcnt vmcnt(0)
	s_barrier
	s_add_u32 m0, s94, 0x10000
	s_nop 0
	global_load_lds_dwordx4 v254, s[88:89]
	s_add_u32 m0, m0, 0x2000
	s_add_u32 s92, s88, 0x20000
	s_addc_u32 s93, s89, 0
	global_load_lds_dwordx4 v254, s[92:93]
	s_add_u32 m0, m0, 0x2000
	s_add_u32 s92, s88, 0x40000
	s_addc_u32 s93, s89, 0
	global_load_lds_dwordx4 v254, s[92:93]
	s_add_u32 m0, m0, 0x2000
	s_add_u32 s92, s88, 0x60000
	s_addc_u32 s93, s89, 0
	global_load_lds_dwordx4 v254, s[92:93]
	s_add_u32 m0, m0, 0x2000
	s_nop 0
	global_load_lds_dwordx4 v254, s[90:91]
	s_add_u32 m0, m0, 0x2000
	s_add_u32 s92, s90, 0x20000
	s_addc_u32 s93, s91, 0
	global_load_lds_dwordx4 v254, s[92:93]
	s_add_u32 m0, m0, 0x2000
	s_add_u32 s92, s90, 0x40000
	s_addc_u32 s93, s91, 0
	global_load_lds_dwordx4 v254, s[92:93]
	s_add_u32 m0, m0, 0x2000
	s_add_u32 s92, s90, 0x60000
	s_addc_u32 s93, s91, 0
	global_load_lds_dwordx4 v254, s[92:93]
	v_add_u32_e32 v164, v178, v177
	ds_read_b128 v[82:85], v164 offset:32768
	v_add_u32_e32 v114, v176, v177
	ds_read_b128 v[86:89], v114
	ds_read_b128 v[90:93], v114 offset:2048
	ds_read_b128 v[94:97], v164 offset:34816
	ds_read_b128 v[110:113], v114 offset:4096
	ds_read_b128 v[114:117], v114 offset:6144
	s_waitcnt lgkmcnt(4)
	v_mfma_f32_16x16x32_bf16 v[98:101], v[82:85], v[86:89], v[142:145]
	v_add_u32_e32 v168, 0x10000, v176
	s_cmp_lt_u32 s30, 4
	s_waitcnt lgkmcnt(3)
	v_mfma_f32_16x16x32_bf16 v[106:109], v[82:85], v[90:93], v[138:141]
	s_waitcnt lgkmcnt(1)
	v_mfma_f32_16x16x32_bf16 v[134:137], v[82:85], v[110:113], v[134:137]
	s_waitcnt lgkmcnt(0)
	v_mfma_f32_16x16x32_bf16 v[82:85], v[82:85], v[114:117], v[130:133]
	v_mfma_f32_16x16x32_bf16 v[126:129], v[94:97], v[86:89], v[126:129]
	v_mfma_f32_16x16x32_bf16 v[122:125], v[94:97], v[90:93], v[122:125]
	v_mfma_f32_16x16x32_bf16 v[118:121], v[94:97], v[110:113], v[118:121]
	v_mfma_f32_16x16x32_bf16 v[94:97], v[94:97], v[114:117], v[102:105]
	s_nop 2
	ds_read_b128 v[102:105], v164 offset:36864
	ds_read_b128 v[130:133], v164 offset:38912
	s_waitcnt lgkmcnt(1)
	v_mfma_f32_16x16x32_bf16 v[78:81], v[102:105], v[86:89], v[78:81]
	v_mfma_f32_16x16x32_bf16 v[74:77], v[102:105], v[90:93], v[74:77]
	v_mfma_f32_16x16x32_bf16 v[70:73], v[102:105], v[110:113], v[70:73]
	v_mfma_f32_16x16x32_bf16 v[66:69], v[102:105], v[114:117], v[66:69]
	s_waitcnt lgkmcnt(0)
	v_mfma_f32_16x16x32_bf16 v[62:65], v[130:133], v[86:89], v[62:65]
	v_mfma_f32_16x16x32_bf16 v[58:61], v[130:133], v[90:93], v[58:61]
	v_mfma_f32_16x16x32_bf16 v[54:57], v[130:133], v[110:113], v[54:57]
	v_mfma_f32_16x16x32_bf16 v[50:53], v[130:133], v[114:117], v[50:53]
	ds_read_b128 v[102:105], v164 offset:40960
	ds_read_b128 v[130:133], v164 offset:43008
	s_waitcnt lgkmcnt(1)
	v_mfma_f32_16x16x32_bf16 v[46:49], v[102:105], v[86:89], v[46:49]
	v_mfma_f32_16x16x32_bf16 v[42:45], v[102:105], v[90:93], v[42:45]
	v_mfma_f32_16x16x32_bf16 v[38:41], v[102:105], v[110:113], v[38:41]
	v_mfma_f32_16x16x32_bf16 v[34:37], v[102:105], v[114:117], v[34:37]
	s_waitcnt lgkmcnt(0)
	v_mfma_f32_16x16x32_bf16 v[26:29], v[130:133], v[86:89], v[26:29]
	v_mfma_f32_16x16x32_bf16 v[18:21], v[130:133], v[90:93], v[18:21]
	v_mfma_f32_16x16x32_bf16 v[30:33], v[130:133], v[110:113], v[30:33]
	v_mfma_f32_16x16x32_bf16 v[22:25], v[130:133], v[114:117], v[22:25]
	ds_read_b128 v[102:105], v164 offset:45056
	ds_read_b128 v[130:133], v164 offset:47104
	v_or_b32_e32 v164, 0x18000, v178
	v_add_u32_e32 v165, v164, v177
	s_waitcnt lgkmcnt(1)
	v_mfma_f32_16x16x32_bf16 v[14:17], v[102:105], v[90:93], v[14:17]
	v_add_u32_e32 v164, v164, v175
	s_waitcnt lgkmcnt(0)
	v_mfma_f32_16x16x32_bf16 v[90:93], v[130:133], v[90:93], v[154:157]
	s_nop 2
	v_add_u32_e32 v154, v178, v175
	v_mfma_f32_16x16x32_bf16 v[6:9], v[102:105], v[86:89], v[6:9]
	v_mfma_f32_16x16x32_bf16 v[10:13], v[102:105], v[110:113], v[10:13]
	v_mfma_f32_16x16x32_bf16 v[2:5], v[102:105], v[114:117], v[2:5]
	v_mfma_f32_16x16x32_bf16 v[102:105], v[130:133], v[110:113], v[150:153]
	ds_read_b128 v[110:113], v154 offset:32768
	s_nop 1
	v_add_u32_e32 v150, v176, v175
	v_mfma_f32_16x16x32_bf16 v[86:89], v[130:133], v[86:89], v[146:149]
	v_mfma_f32_16x16x32_bf16 v[114:117], v[130:133], v[114:117], v[158:161]
	ds_read_b128 v[130:133], v150
	ds_read_b128 v[138:141], v150 offset:2048
	ds_read_b128 v[142:145], v154 offset:34816
	ds_read_b128 v[146:149], v150 offset:4096
	ds_read_b128 v[150:153], v150 offset:6144
	s_waitcnt lgkmcnt(4)
; DI f32x4 mfma16(bf16x8 a, bf16x8 b, f32x4 c) { return __builtin_amdgcn_mfma_f32_16x16x32_bf16(a, b, c, 0, 0, 0); }
; template <int MI, int NI>
; DI void gemm_kloop(const u16* Au, int lda, const u16* Bu, int ldb, int K, f32x4 (&acc)[NI][MI], unsigned char* smem) {
;     ...
;     {
;       const unsigned char* sa = smem + (kt & 1) * 65536;
;       const unsigned char* sb = sa + 32768;
; #pragma unroll
;       for (int ks = 0; ks < 2; ++ks) {
;         const int fo = ks ? fro1 : fro0;
;         bf16x8 af[MI];
; #pragma unroll
;         for (int i = 0; i < MI; ++i) af[i] = *(const bf16x8*)(sa + (wm * 16 * MI + i * 16) * 128 + fo);
; #pragma unroll
;         for (int nh = 0; nh < NI; nh += 4) {
;           bf16x8 wf[4];
; #pragma unroll
;           for (int i = 0; i < 4; ++i) wf[i] = *(const bf16x8*)(sb + (wn * 16 * NI + (nh + i) * 16) * 128 + fo);
; #pragma unroll
;           for (int ni = 0; ni < 4; ++ni)
; #pragma unroll
;             for (int mi = 0; mi < MI; ++mi) acc[nh + ni][mi] = mfma16(wf[ni], af[mi], acc[nh + ni][mi]);
;         }
;       }
;     }
;   }
;   __syncthreads();
	v_mfma_f32_16x16x32_bf16 v[98:101], v[110:113], v[130:133], v[98:101]
	s_waitcnt lgkmcnt(3)
	v_mfma_f32_16x16x32_bf16 v[106:109], v[110:113], v[138:141], v[106:109]
	s_waitcnt lgkmcnt(1)
	v_mfma_f32_16x16x32_bf16 v[134:137], v[110:113], v[146:149], v[134:137]
	s_waitcnt lgkmcnt(0)
	v_mfma_f32_16x16x32_bf16 v[82:85], v[110:113], v[150:153], v[82:85]
	v_mfma_f32_16x16x32_bf16 v[110:113], v[142:145], v[130:133], v[126:129]
	v_mfma_f32_16x16x32_bf16 v[122:125], v[142:145], v[138:141], v[122:125]
	v_mfma_f32_16x16x32_bf16 v[118:121], v[142:145], v[146:149], v[118:121]
	v_mfma_f32_16x16x32_bf16 v[94:97], v[142:145], v[150:153], v[94:97]
	ds_read_b128 v[126:129], v154 offset:36864
	ds_read_b128 v[142:145], v154 offset:38912
	s_waitcnt lgkmcnt(1)
	v_mfma_f32_16x16x32_bf16 v[78:81], v[126:129], v[130:133], v[78:81]
	v_mfma_f32_16x16x32_bf16 v[74:77], v[126:129], v[138:141], v[74:77]
	v_mfma_f32_16x16x32_bf16 v[70:73], v[126:129], v[146:149], v[70:73]
	v_mfma_f32_16x16x32_bf16 v[66:69], v[126:129], v[150:153], v[66:69]
	s_waitcnt lgkmcnt(0)
	v_mfma_f32_16x16x32_bf16 v[62:65], v[142:145], v[130:133], v[62:65]
	v_mfma_f32_16x16x32_bf16 v[58:61], v[142:145], v[138:141], v[58:61]
	v_mfma_f32_16x16x32_bf16 v[54:57], v[142:145], v[146:149], v[54:57]
	v_mfma_f32_16x16x32_bf16 v[50:53], v[142:145], v[150:153], v[50:53]
	ds_read_b128 v[126:129], v154 offset:40960
	ds_read_b128 v[142:145], v154 offset:43008
	s_waitcnt lgkmcnt(1)
	v_mfma_f32_16x16x32_bf16 v[46:49], v[126:129], v[130:133], v[46:49]
	v_mfma_f32_16x16x32_bf16 v[42:45], v[126:129], v[138:141], v[42:45]
	v_mfma_f32_16x16x32_bf16 v[38:41], v[126:129], v[146:149], v[38:41]
	v_mfma_f32_16x16x32_bf16 v[34:37], v[126:129], v[150:153], v[34:37]
	s_waitcnt lgkmcnt(0)
	v_mfma_f32_16x16x32_bf16 v[26:29], v[142:145], v[130:133], v[26:29]
	v_mfma_f32_16x16x32_bf16 v[18:21], v[142:145], v[138:141], v[18:21]
	v_mfma_f32_16x16x32_bf16 v[30:33], v[142:145], v[146:149], v[30:33]
	v_mfma_f32_16x16x32_bf16 v[22:25], v[142:145], v[150:153], v[22:25]
	ds_read_b128 v[126:129], v154 offset:45056
	ds_read_b128 v[142:145], v154 offset:47104
	s_waitcnt vmcnt(0) lgkmcnt(0)
	s_barrier
	v_mfma_f32_16x16x32_bf16 v[6:9], v[126:129], v[130:133], v[6:9]
	v_mfma_f32_16x16x32_bf16 v[14:17], v[126:129], v[138:141], v[14:17]
	v_mfma_f32_16x16x32_bf16 v[10:13], v[126:129], v[146:149], v[10:13]
	v_mfma_f32_16x16x32_bf16 v[2:5], v[126:129], v[150:153], v[2:5]
	ds_read_b128 v[126:129], v165
	v_mfma_f32_16x16x32_bf16 v[102:105], v[142:145], v[146:149], v[102:105]
	v_add_u32_e32 v146, v168, v177
	v_mfma_f32_16x16x32_bf16 v[86:89], v[142:145], v[130:133], v[86:89]
	ds_read_b128 v[130:133], v146
	v_mfma_f32_16x16x32_bf16 v[90:93], v[142:145], v[138:141], v[90:93]
	ds_read_b128 v[138:141], v146 offset:2048
	v_mfma_f32_16x16x32_bf16 v[114:117], v[142:145], v[150:153], v[114:117]
	ds_read_b128 v[142:145], v146 offset:4096
	ds_read_b128 v[146:149], v146 offset:6144
	s_waitcnt lgkmcnt(3)
	v_mfma_f32_16x16x32_bf16 v[98:101], v[126:129], v[130:133], v[98:101]
	s_waitcnt lgkmcnt(2)
	v_mfma_f32_16x16x32_bf16 v[106:109], v[126:129], v[138:141], v[106:109]
	s_waitcnt lgkmcnt(1)
	v_mfma_f32_16x16x32_bf16 v[134:137], v[126:129], v[142:145], v[134:137]
	s_waitcnt lgkmcnt(0)
	v_mfma_f32_16x16x32_bf16 v[82:85], v[126:129], v[146:149], v[82:85]
	ds_read_b128 v[126:129], v165 offset:2048
	s_waitcnt lgkmcnt(0)
	v_mfma_f32_16x16x32_bf16 v[150:153], v[126:129], v[142:145], v[118:121]
	s_nop 2
	ds_read_b128 v[118:121], v165 offset:4096
	v_mfma_f32_16x16x32_bf16 v[110:113], v[126:129], v[130:133], v[110:113]
	v_mfma_f32_16x16x32_bf16 v[122:125], v[126:129], v[138:141], v[122:125]
	v_mfma_f32_16x16x32_bf16 v[94:97], v[126:129], v[146:149], v[94:97]
	s_waitcnt lgkmcnt(0)
	v_mfma_f32_16x16x32_bf16 v[126:129], v[118:121], v[142:145], v[70:73]
	s_nop 2
	ds_read_b128 v[70:73], v165 offset:6144
	s_waitcnt lgkmcnt(0)
	v_mfma_f32_16x16x32_bf16 v[154:157], v[70:73], v[146:149], v[50:53]
	s_nop 2
	ds_read_b128 v[50:53], v165 offset:8192
	s_waitcnt lgkmcnt(0)
	v_mfma_f32_16x16x32_bf16 v[176:179], v[50:53], v[142:145], v[38:41]
	s_nop 2
	ds_read_b128 v[38:41], v165 offset:10240
	s_waitcnt lgkmcnt(0)
	v_mfma_f32_16x16x32_bf16 v[180:183], v[38:41], v[146:149], v[22:25]
	s_nop 2
	ds_read_b128 v[22:25], v165 offset:12288
	s_waitcnt lgkmcnt(0)
; DI f32x4 mfma16(bf16x8 a, bf16x8 b, f32x4 c) { return __builtin_amdgcn_mfma_f32_16x16x32_bf16(a, b, c, 0, 0, 0); }
; template <int MI, int NI>
; DI void gemm_kloop(const u16* Au, int lda, const u16* Bu, int ldb, int K, f32x4 (&acc)[NI][MI], unsigned char* smem) {
;     ...
;       for (int ks = 0; ks < 2; ++ks) {
;         const int fo = ks ? fro1 : fro0;
;         bf16x8 af[MI];
; #pragma unroll
;         for (int i = 0; i < MI; ++i) af[i] = *(const bf16x8*)(sa + (wm * 16 * MI + i * 16) * 128 + fo);
; #pragma unroll
;         for (int nh = 0; nh < NI; nh += 4) {
;           bf16x8 wf[4];
; #pragma unroll
;           for (int i = 0; i < 4; ++i) wf[i] = *(const bf16x8*)(sb + (wn * 16 * NI + (nh + i) * 16) * 128 + fo);
; #pragma unroll
;           for (int ni = 0; ni < 4; ++ni)
; #pragma unroll
;             for (int mi = 0; mi < MI; ++mi) acc[nh + ni][mi] = mfma16(wf[ni], af[mi], acc[nh + ni][mi]);
;         }
; DI void phase_g1(const Params& p, int layer, unsigned char* smem) {
;     ...
;     int mrow[4];
; #pragma unroll
;     for (int mi = 0; mi < 4; ++mi) {
;       mrow[mi] = mt * 256 + wm * 64 + mi * 16 + lm;
;       float rs = rsqrtf(rowss[mrow[mi]] * (1.f / DM) + EPS);
; #pragma unroll
;       for (int ni = 0; ni < 8; ++ni) acc[ni][mi] *= rs;
;     }
;     int kind;
;     u16* dst = nullptr; int ld = 256, col0 = 0, vrows = 256; const float* gn = nullptr;
;     if (nt == 0) { kind = 0; dst = p.qsb; }
;     else if (nt == 1) { kind = 0; dst = p.ksb; }
;     else if (nt == 2) { kind = 2; dst = p.vtsb; vrows = 256; }
;     else if (nt == 3) { kind = 1; dst = p.qsp; gn = p.qn_sp + layer * 64; }
;     else if (nt == 4) { kind = 1; dst = p.ksp; gn = p.kn_sp + layer * 64; }
;     else if (nt == 5) { kind = 2; dst = p.vtsp; vrows = 256; }
;     else if (nt < 8) { kind = 1; dst = p.qdf; ld = 512; col0 = (nt - 6) * 256; gn = p.qn_df + layer * 64; }
;     else if (nt < 10) { kind = 1; dst = p.kdf; ld = 512; col0 = (nt - 8) * 256; gn = p.kn_df + layer * 64; }
;     else if (nt < 12) { kind = 2; dst = p.vtdf; col0 = (nt - 10) * 256; vrows = 512; }
;     else { kind = 0; dst = p.qix; }
	v_mfma_f32_16x16x32_bf16 v[226:229], v[22:25], v[146:149], v[2:5]
	s_nop 2
	ds_read_b128 v[2:5], v165 offset:14336
	v_mfma_f32_16x16x32_bf16 v[184:187], v[22:25], v[130:133], v[6:9]
	s_nop 2
	ds_read_b128 v[6:9], v164
	v_mfma_f32_16x16x32_bf16 v[192:195], v[22:25], v[142:145], v[10:13]
	s_nop 2
	v_add_u32_e32 v10, v168, v175
	v_mfma_f32_16x16x32_bf16 v[78:81], v[118:121], v[130:133], v[78:81]
	ds_read_b128 v[230:233], v10 offset:2048
	ds_read_b128 v[234:237], v10 offset:4096
	ds_read_b128 v[238:241], v10 offset:6144
	v_mfma_f32_16x16x32_bf16 v[74:77], v[118:121], v[138:141], v[74:77]
	v_mfma_f32_16x16x32_bf16 v[66:69], v[118:121], v[146:149], v[66:69]
	v_mfma_f32_16x16x32_bf16 v[62:65], v[70:73], v[130:133], v[62:65]
	v_mfma_f32_16x16x32_bf16 v[58:61], v[70:73], v[138:141], v[58:61]
	v_mfma_f32_16x16x32_bf16 v[54:57], v[70:73], v[142:145], v[54:57]
	v_mfma_f32_16x16x32_bf16 v[46:49], v[50:53], v[130:133], v[46:49]
	v_mfma_f32_16x16x32_bf16 v[158:161], v[50:53], v[138:141], v[42:45]
	v_mfma_f32_16x16x32_bf16 v[34:37], v[50:53], v[146:149], v[34:37]
	v_mfma_f32_16x16x32_bf16 v[26:29], v[38:41], v[130:133], v[26:29]
	v_mfma_f32_16x16x32_bf16 v[18:21], v[38:41], v[138:141], v[18:21]
	v_mfma_f32_16x16x32_bf16 v[30:33], v[38:41], v[142:145], v[30:33]
	v_mfma_f32_16x16x32_bf16 v[188:191], v[22:25], v[138:141], v[14:17]
	s_waitcnt lgkmcnt(4)
	v_mfma_f32_16x16x32_bf16 v[86:89], v[2:5], v[130:133], v[86:89]
	v_mfma_f32_16x16x32_bf16 v[130:133], v[2:5], v[138:141], v[90:93]
	v_mfma_f32_16x16x32_bf16 v[138:141], v[2:5], v[142:145], v[102:105]
	v_mfma_f32_16x16x32_bf16 v[142:145], v[2:5], v[146:149], v[114:117]
	ds_read_b128 v[146:149], v10
	ds_read_b128 v[10:13], v164 offset:6144
	s_waitcnt lgkmcnt(1)
	v_mfma_f32_16x16x32_bf16 v[102:105], v[6:9], v[146:149], v[98:101]
	v_mfma_f32_16x16x32_bf16 v[70:73], v[6:9], v[230:233], v[106:109]
	v_mfma_f32_16x16x32_bf16 v[38:41], v[6:9], v[234:237], v[134:137]
	v_mfma_f32_16x16x32_bf16 v[2:5], v[6:9], v[238:241], v[82:85]
	ds_read_b128 v[6:9], v164 offset:2048
	s_waitcnt lgkmcnt(0)
	v_mfma_f32_16x16x32_bf16 v[118:121], v[6:9], v[146:149], v[110:113]
	v_mfma_f32_16x16x32_bf16 v[82:85], v[6:9], v[230:233], v[122:125]
	v_mfma_f32_16x16x32_bf16 v[50:53], v[6:9], v[234:237], v[150:153]
	v_mfma_f32_16x16x32_bf16 v[14:17], v[6:9], v[238:241], v[94:97]
	ds_read_b128 v[6:9], v164 offset:4096
	v_mfma_f32_16x16x32_bf16 v[122:125], v[10:13], v[146:149], v[62:65]
	v_mfma_f32_16x16x32_bf16 v[90:93], v[10:13], v[230:233], v[58:61]
	v_mfma_f32_16x16x32_bf16 v[54:57], v[10:13], v[234:237], v[54:57]
	v_mfma_f32_16x16x32_bf16 v[22:25], v[10:13], v[238:241], v[154:157]
	ds_read_b128 v[10:13], v164 offset:8192
	s_waitcnt lgkmcnt(1)
	v_mfma_f32_16x16x32_bf16 v[110:113], v[6:9], v[146:149], v[78:81]
	s_waitcnt lgkmcnt(0)
	v_mfma_f32_16x16x32_bf16 v[114:117], v[10:13], v[146:149], v[46:49]
	v_mfma_f32_16x16x32_bf16 v[78:81], v[10:13], v[230:233], v[158:161]
	v_mfma_f32_16x16x32_bf16 v[46:49], v[10:13], v[234:237], v[176:179]
	v_mfma_f32_16x16x32_bf16 v[10:13], v[10:13], v[238:241], v[34:37]
	s_nop 2
	ds_read_b128 v[34:37], v164 offset:10240
	s_waitcnt lgkmcnt(0)
	v_mfma_f32_16x16x32_bf16 v[94:97], v[34:37], v[230:233], v[18:21]
	s_nop 2
	ds_read_b128 v[18:21], v164 offset:12288
	v_mfma_f32_16x16x32_bf16 v[58:61], v[34:37], v[234:237], v[30:33]
	s_nop 2
	ds_read_b128 v[30:33], v164 offset:14336
	s_waitcnt lgkmcnt(0)
	v_mfma_f32_16x16x32_bf16 v[106:109], v[30:33], v[146:149], v[86:89]
	s_barrier
	v_mfma_f32_16x16x32_bf16 v[86:89], v[30:33], v[230:233], v[130:133]
	s_nop 2
	v_add_u32_e32 v130, s2, v173
	v_ashrrev_i32_e32 v131, 31, v130
	v_lshl_add_u64 v[136:137], v[130:131], 2, s[6:7]
	global_load_dword v133, v[136:137], off
	global_load_dword v132, v[136:137], off offset:64
	global_load_dword v135, v[136:137], off offset:128
	global_load_dword v134, v[136:137], off offset:192
	v_mfma_f32_16x16x32_bf16 v[74:77], v[6:9], v[230:233], v[74:77]
	v_mfma_f32_16x16x32_bf16 v[42:45], v[6:9], v[234:237], v[126:129]
	v_mfma_f32_16x16x32_bf16 v[6:9], v[6:9], v[238:241], v[66:69]
	v_mfma_f32_16x16x32_bf16 v[126:129], v[34:37], v[146:149], v[26:29]
	v_mfma_f32_16x16x32_bf16 v[26:29], v[34:37], v[238:241], v[180:183]
	v_mfma_f32_16x16x32_bf16 v[98:101], v[18:21], v[146:149], v[184:187]
	v_mfma_f32_16x16x32_bf16 v[66:69], v[18:21], v[230:233], v[188:191]
	v_mfma_f32_16x16x32_bf16 v[34:37], v[18:21], v[234:237], v[192:195]
	v_mfma_f32_16x16x32_bf16 v[18:21], v[18:21], v[238:241], v[226:229]
	v_mfma_f32_16x16x32_bf16 v[62:65], v[30:33], v[234:237], v[138:141]
	v_mfma_f32_16x16x32_bf16 v[30:33], v[30:33], v[238:241], v[142:145]
	s_cbranch_scc1 .LBB0_1205
	s_mov_b64 s[34:35], -1
	s_mov_b64 s[52:53], 0
	s_cmp_lt_i32 s54, 3
	s_mov_b64 s[30:31], 0
	s_cbranch_scc1 .LBB0_1206
	s_cmp_gt_i32 s54, 3
	s_cbranch_scc0 .LBB0_1221
	s_mov_b64 s[50:51], -1
	s_mov_b64 s[2:3], 0
	s_cmp_gt_i32 s54, 4
	s_mov_b64 s[28:29], -1
	s_cbranch_scc0 .LBB0_1191
	s_cmp_eq_u32 s54, 5
	s_mov_b64 s[30:31], -1
	s_cbranch_scc0 .LBB0_1190
	s_mov_b64 s[30:31], 0
